# speedup vs baseline: 1.0270x; 1.0270x over previous
; DEVINL float bf2f(u16 h) { return __uint_as_float(((unsigned)h) << 16); }
;   DEVINL void operator()(Acc& acc, int brow, int bcol) const {
;     EPI_IDS
;     const int c0 = bcol + wc * 64 + fr * 4;
;     _Pragma("unroll") for (int ai = 0; ai < 2; ++ai) _Pragma("unroll") for (int m = 0; m < 4; ++m) _Pragma("unroll") for (int j = 0; j < 4; ++j) {
;       const int row = brow + ai * 128 + wr * 64 + m * 16 + fq * 4 + j;
;       const size_t o = (size_t)row * DM + c0;
;       const bf16x4 sn = *(const bf16x4*)(sgn + o);
;       if (which == 0) {
;         const bf16x4 sr = *(const bf16x4*)(sgr + o);
;         acc[ai][0][m][0][j] *= __fdividef(bf2f((u16)sr[0]), fmaxf(bf2f((u16)sn[0]), 1e-30f)); acc[ai][0][m][1][j] *= __fdividef(bf2f((u16)sr[1]), fmaxf(bf2f((u16)sn[1]), 1e-30f));
;         acc[ai][1][m][0][j] *= __fdividef(bf2f((u16)sr[2]), fmaxf(bf2f((u16)sn[2]), 1e-30f)); acc[ai][1][m][1][j] *= __fdividef(bf2f((u16)sr[3]), fmaxf(bf2f((u16)sn[3]), 1e-30f));
;       } else {
;         *(bf16x4*)(merged + o) = pack4(acc[ai][0][m][0][j] * bf2f((u16)sn[0]), acc[ai][0][m][1][j] * bf2f((u16)sn[1]),
.LBB0_136:
	s_or_b64 exec, exec, s[22:23]
	s_load_dword s63, s[88:89], 0x208
	s_mov_b32 s58, 0x10000
	v_readlane_b32 s59, v255, 38
	v_readlane_b32 s62, v255, 45
	v_mov_b32_e32 v243, v235
	v_mov_b32_e32 v0, v234
	v_lshlrev_b32_e32 v3, 2, v0
	v_and_b32_e32 v2, 0xc0, v0
	v_and_b32_e32 v3, 60, v3
	v_or3_b32 v2, v2, v3, s20
	v_ashrrev_i32_e32 v3, 2, v0
	v_and_b32_e32 v3, 0xffffffc0, v3
	v_lshrrev_b32_e32 v0, 2, v0
	v_add_u32_e32 v3, s8, v3
	v_and_or_b32 v132, v0, 12, v3
	v_lshlrev_b32_e32 v132, 10, v132
	v_add_lshl_u32 v132, v132, v2, 1
	s_and_b64 vcc, exec, s[18:19]
	s_cbranch_vccz .Lmx_w0
	v_add_u32_e32 v162, 0x0, v132
	global_load_dwordx2 v[178:179], v162, s[14:15]
	v_add_u32_e32 v163, 0x800, v132
	global_load_dwordx2 v[180:181], v163, s[14:15]
	v_add_u32_e32 v164, 0x1000, v132
	global_load_dwordx2 v[182:183], v164, s[14:15]
	v_add_u32_e32 v165, 0x1800, v132
	global_load_dwordx2 v[184:185], v165, s[14:15]
	v_add_u32_e32 v166, 0x8000, v132
	global_load_dwordx2 v[186:187], v166, s[14:15]
	v_add_u32_e32 v167, 0x8800, v132
	global_load_dwordx2 v[188:189], v167, s[14:15]
	v_add_u32_e32 v168, 0x9000, v132
	global_load_dwordx2 v[190:191], v168, s[14:15]
	v_add_u32_e32 v169, 0x9800, v132
	global_load_dwordx2 v[192:193], v169, s[14:15]
	v_add_u32_e32 v170, 0x10000, v132
	global_load_dwordx2 v[194:195], v170, s[14:15]
	v_add_u32_e32 v171, 0x10800, v132
	global_load_dwordx2 v[196:197], v171, s[14:15]
	v_add_u32_e32 v172, 0x11000, v132
	global_load_dwordx2 v[198:199], v172, s[14:15]
	v_add_u32_e32 v173, 0x11800, v132
	global_load_dwordx2 v[200:201], v173, s[14:15]
	v_add_u32_e32 v174, 0x18000, v132
	global_load_dwordx2 v[202:203], v174, s[14:15]
	v_add_u32_e32 v175, 0x18800, v132
	global_load_dwordx2 v[204:205], v175, s[14:15]
	v_add_u32_e32 v176, 0x19000, v132
	global_load_dwordx2 v[206:207], v176, s[14:15]
	v_add_u32_e32 v177, 0x19800, v132
	global_load_dwordx2 v[208:209], v177, s[14:15]
	s_waitcnt vmcnt(8)
	v_lshlrev_b32_e32 v238, 16, v178
	v_and_b32_e32 v239, 0xffff0000, v178
	v_lshlrev_b32_e32 v240, 16, v179
	v_and_b32_e32 v241, 0xffff0000, v179
	v_mul_f32_e32 v238, v104, v238
	v_mul_f32_e32 v239, v100, v239
	v_mul_f32_e32 v240, v72, v240
	v_mul_f32_e32 v241, v68, v241
	v_cvt_pk_bf16_f32 v236, v238, v239
	v_cvt_pk_bf16_f32 v237, v240, v241
	global_store_dwordx2 v162, v[236:237], s[10:11]
	v_lshlrev_b32_e32 v0, 16, v180
	v_and_b32_e32 v2, 0xffff0000, v180
	v_lshlrev_b32_e32 v3, 16, v181
	v_and_b32_e32 v133, 0xffff0000, v181
	v_mul_f32_e32 v0, v105, v0
	v_mul_f32_e32 v2, v101, v2
	v_mul_f32_e32 v3, v73, v3
	v_mul_f32_e32 v133, v69, v133
	v_cvt_pk_bf16_f32 v142, v0, v2
	v_cvt_pk_bf16_f32 v143, v3, v133
	global_store_dwordx2 v163, v[142:143], s[10:11]
	v_lshlrev_b32_e32 v238, 16, v182
	v_and_b32_e32 v239, 0xffff0000, v182
	v_lshlrev_b32_e32 v240, 16, v183
	v_and_b32_e32 v241, 0xffff0000, v183
	v_mul_f32_e32 v238, v106, v238
	v_mul_f32_e32 v239, v102, v239
	v_mul_f32_e32 v240, v74, v240
	v_mul_f32_e32 v241, v70, v241
	v_cvt_pk_bf16_f32 v236, v238, v239
	v_cvt_pk_bf16_f32 v237, v240, v241
	global_store_dwordx2 v164, v[236:237], s[10:11]
	v_lshlrev_b32_e32 v0, 16, v184
	v_and_b32_e32 v2, 0xffff0000, v184
	v_lshlrev_b32_e32 v3, 16, v185
	v_and_b32_e32 v133, 0xffff0000, v185
	v_mul_f32_e32 v0, v107, v0
	v_mul_f32_e32 v2, v103, v2
	v_mul_f32_e32 v3, v75, v3
	v_mul_f32_e32 v133, v71, v133
	v_cvt_pk_bf16_f32 v142, v0, v2
	v_cvt_pk_bf16_f32 v143, v3, v133
	global_store_dwordx2 v165, v[142:143], s[10:11]
	v_lshlrev_b32_e32 v238, 16, v186
	v_and_b32_e32 v239, 0xffff0000, v186
	v_lshlrev_b32_e32 v240, 16, v187
	v_and_b32_e32 v241, 0xffff0000, v187
	v_mul_f32_e32 v238, v112, v238
	v_mul_f32_e32 v239, v108, v239
	v_mul_f32_e32 v240, v80, v240
	v_mul_f32_e32 v241, v76, v241
	v_cvt_pk_bf16_f32 v236, v238, v239
	v_cvt_pk_bf16_f32 v237, v240, v241
	global_store_dwordx2 v166, v[236:237], s[10:11]
	v_lshlrev_b32_e32 v0, 16, v188
	v_and_b32_e32 v2, 0xffff0000, v188
	v_lshlrev_b32_e32 v3, 16, v189
	v_and_b32_e32 v133, 0xffff0000, v189
	v_mul_f32_e32 v0, v113, v0
	v_mul_f32_e32 v2, v109, v2
	v_mul_f32_e32 v3, v81, v3
	v_mul_f32_e32 v133, v77, v133
	v_cvt_pk_bf16_f32 v142, v0, v2
	v_cvt_pk_bf16_f32 v143, v3, v133
	global_store_dwordx2 v167, v[142:143], s[10:11]
	v_lshlrev_b32_e32 v238, 16, v190
	v_and_b32_e32 v239, 0xffff0000, v190
	v_lshlrev_b32_e32 v240, 16, v191
	v_and_b32_e32 v241, 0xffff0000, v191
	v_mul_f32_e32 v238, v114, v238
	v_mul_f32_e32 v239, v110, v239
	v_mul_f32_e32 v240, v82, v240
	v_mul_f32_e32 v241, v78, v241
	v_cvt_pk_bf16_f32 v236, v238, v239
	v_cvt_pk_bf16_f32 v237, v240, v241
	global_store_dwordx2 v168, v[236:237], s[10:11]
	v_lshlrev_b32_e32 v0, 16, v192
	v_and_b32_e32 v2, 0xffff0000, v192
	v_lshlrev_b32_e32 v3, 16, v193
	v_and_b32_e32 v133, 0xffff0000, v193
	v_mul_f32_e32 v0, v115, v0
	v_mul_f32_e32 v2, v111, v2
	v_mul_f32_e32 v3, v83, v3
	v_mul_f32_e32 v133, v79, v133
	v_cvt_pk_bf16_f32 v142, v0, v2
	v_cvt_pk_bf16_f32 v143, v3, v133
	global_store_dwordx2 v169, v[142:143], s[10:11]
	v_add_u32_e32 v162, 0x40000, v132
	global_load_dwordx2 v[178:179], v162, s[14:15]
	v_add_u32_e32 v163, 0x40800, v132
	global_load_dwordx2 v[180:181], v163, s[14:15]
	v_add_u32_e32 v164, 0x41000, v132
	global_load_dwordx2 v[182:183], v164, s[14:15]
	v_add_u32_e32 v165, 0x41800, v132
	global_load_dwordx2 v[184:185], v165, s[14:15]
	v_add_u32_e32 v166, 0x48000, v132
	global_load_dwordx2 v[186:187], v166, s[14:15]
	v_add_u32_e32 v167, 0x48800, v132
	global_load_dwordx2 v[188:189], v167, s[14:15]
	v_add_u32_e32 v168, 0x49000, v132
	global_load_dwordx2 v[190:191], v168, s[14:15]
	v_add_u32_e32 v169, 0x49800, v132
	global_load_dwordx2 v[192:193], v169, s[14:15]
	s_waitcnt vmcnt(16)
; DEVINL float bf2f(u16 h) { return __uint_as_float(((unsigned)h) << 16); }
;   DEVINL void operator()(Acc& acc, int brow, int bcol) const {
;     ...
;     _Pragma("unroll") for (int ai = 0; ai < 2; ++ai) _Pragma("unroll") for (int m = 0; m < 4; ++m) _Pragma("unroll") for (int j = 0; j < 4; ++j) {
;       const int row = brow + ai * 128 + wr * 64 + m * 16 + fq * 4 + j;
;       const size_t o = (size_t)row * DM + c0;
;       const bf16x4 sn = *(const bf16x4*)(sgn + o);
;       if (which == 0) {
;         const bf16x4 sr = *(const bf16x4*)(sgr + o);
;         acc[ai][0][m][0][j] *= __fdividef(bf2f((u16)sr[0]), fmaxf(bf2f((u16)sn[0]), 1e-30f)); acc[ai][0][m][1][j] *= __fdividef(bf2f((u16)sr[1]), fmaxf(bf2f((u16)sn[1]), 1e-30f));
;         acc[ai][1][m][0][j] *= __fdividef(bf2f((u16)sr[2]), fmaxf(bf2f((u16)sn[2]), 1e-30f)); acc[ai][1][m][1][j] *= __fdividef(bf2f((u16)sr[3]), fmaxf(bf2f((u16)sn[3]), 1e-30f));
;       } else {
;         *(bf16x4*)(merged + o) = pack4(acc[ai][0][m][0][j] * bf2f((u16)sn[0]), acc[ai][0][m][1][j] * bf2f((u16)sn[1]),
;                                        acc[ai][1][m][0][j] * bf2f((u16)sn[2]), acc[ai][1][m][1][j] * bf2f((u16)sn[3]));
	v_lshlrev_b32_e32 v238, 16, v194
	v_and_b32_e32 v239, 0xffff0000, v194
	v_lshlrev_b32_e32 v240, 16, v195
	v_and_b32_e32 v241, 0xffff0000, v195
	v_mul_f32_e32 v238, v120, v238
	v_mul_f32_e32 v239, v116, v239
	v_mul_f32_e32 v240, v88, v240
	v_mul_f32_e32 v241, v84, v241
	v_cvt_pk_bf16_f32 v236, v238, v239
	v_cvt_pk_bf16_f32 v237, v240, v241
	global_store_dwordx2 v170, v[236:237], s[10:11]
	v_lshlrev_b32_e32 v0, 16, v196
	v_and_b32_e32 v2, 0xffff0000, v196
	v_lshlrev_b32_e32 v3, 16, v197
	v_and_b32_e32 v133, 0xffff0000, v197
	v_mul_f32_e32 v0, v121, v0
	v_mul_f32_e32 v2, v117, v2
	v_mul_f32_e32 v3, v89, v3
	v_mul_f32_e32 v133, v85, v133
	v_cvt_pk_bf16_f32 v142, v0, v2
	v_cvt_pk_bf16_f32 v143, v3, v133
	global_store_dwordx2 v171, v[142:143], s[10:11]
	v_lshlrev_b32_e32 v238, 16, v198
	v_and_b32_e32 v239, 0xffff0000, v198
	v_lshlrev_b32_e32 v240, 16, v199
	v_and_b32_e32 v241, 0xffff0000, v199
	v_mul_f32_e32 v238, v122, v238
	v_mul_f32_e32 v239, v118, v239
	v_mul_f32_e32 v240, v90, v240
	v_mul_f32_e32 v241, v86, v241
	v_cvt_pk_bf16_f32 v236, v238, v239
	v_cvt_pk_bf16_f32 v237, v240, v241
	global_store_dwordx2 v172, v[236:237], s[10:11]
	v_lshlrev_b32_e32 v0, 16, v200
	v_and_b32_e32 v2, 0xffff0000, v200
	v_lshlrev_b32_e32 v3, 16, v201
	v_and_b32_e32 v133, 0xffff0000, v201
	v_mul_f32_e32 v0, v123, v0
	v_mul_f32_e32 v2, v119, v2
	v_mul_f32_e32 v3, v91, v3
	v_mul_f32_e32 v133, v87, v133
	v_cvt_pk_bf16_f32 v142, v0, v2
	v_cvt_pk_bf16_f32 v143, v3, v133
	global_store_dwordx2 v173, v[142:143], s[10:11]
	v_lshlrev_b32_e32 v238, 16, v202
	v_and_b32_e32 v239, 0xffff0000, v202
	v_lshlrev_b32_e32 v240, 16, v203
	v_and_b32_e32 v241, 0xffff0000, v203
	v_mul_f32_e32 v238, v128, v238
	v_mul_f32_e32 v239, v124, v239
	v_mul_f32_e32 v240, v96, v240
	v_mul_f32_e32 v241, v92, v241
	v_cvt_pk_bf16_f32 v236, v238, v239
	v_cvt_pk_bf16_f32 v237, v240, v241
	global_store_dwordx2 v174, v[236:237], s[10:11]
	v_lshlrev_b32_e32 v0, 16, v204
	v_and_b32_e32 v2, 0xffff0000, v204
	v_lshlrev_b32_e32 v3, 16, v205
	v_and_b32_e32 v133, 0xffff0000, v205
	v_mul_f32_e32 v0, v129, v0
	v_mul_f32_e32 v2, v125, v2
	v_mul_f32_e32 v3, v97, v3
	v_mul_f32_e32 v133, v93, v133
	v_cvt_pk_bf16_f32 v142, v0, v2
	v_cvt_pk_bf16_f32 v143, v3, v133
	global_store_dwordx2 v175, v[142:143], s[10:11]
	v_lshlrev_b32_e32 v238, 16, v206
	v_and_b32_e32 v239, 0xffff0000, v206
	v_lshlrev_b32_e32 v240, 16, v207
	v_and_b32_e32 v241, 0xffff0000, v207
	v_mul_f32_e32 v238, v130, v238
	v_mul_f32_e32 v239, v126, v239
	v_mul_f32_e32 v240, v98, v240
	v_mul_f32_e32 v241, v94, v241
	v_cvt_pk_bf16_f32 v236, v238, v239
	v_cvt_pk_bf16_f32 v237, v240, v241
	global_store_dwordx2 v176, v[236:237], s[10:11]
	v_lshlrev_b32_e32 v0, 16, v208
	v_and_b32_e32 v2, 0xffff0000, v208
	v_lshlrev_b32_e32 v3, 16, v209
	v_and_b32_e32 v133, 0xffff0000, v209
	v_mul_f32_e32 v0, v131, v0
	v_mul_f32_e32 v2, v127, v2
	v_mul_f32_e32 v3, v99, v3
	v_mul_f32_e32 v133, v95, v133
	v_cvt_pk_bf16_f32 v142, v0, v2
	v_cvt_pk_bf16_f32 v143, v3, v133
	global_store_dwordx2 v177, v[142:143], s[10:11]
	v_add_u32_e32 v170, 0x50000, v132
	global_load_dwordx2 v[194:195], v170, s[14:15]
	v_add_u32_e32 v171, 0x50800, v132
	global_load_dwordx2 v[196:197], v171, s[14:15]
	v_add_u32_e32 v172, 0x51000, v132
	global_load_dwordx2 v[198:199], v172, s[14:15]
	v_add_u32_e32 v173, 0x51800, v132
	global_load_dwordx2 v[200:201], v173, s[14:15]
	v_add_u32_e32 v174, 0x58000, v132
	global_load_dwordx2 v[202:203], v174, s[14:15]
	v_add_u32_e32 v175, 0x58800, v132
	global_load_dwordx2 v[204:205], v175, s[14:15]
	v_add_u32_e32 v176, 0x59000, v132
	global_load_dwordx2 v[206:207], v176, s[14:15]
	v_add_u32_e32 v177, 0x59800, v132
	global_load_dwordx2 v[208:209], v177, s[14:15]
	s_waitcnt vmcnt(16)
	v_lshlrev_b32_e32 v238, 16, v178
	v_and_b32_e32 v239, 0xffff0000, v178
	v_lshlrev_b32_e32 v240, 16, v179
	v_and_b32_e32 v241, 0xffff0000, v179
	v_mul_f32_e32 v238, v40, v238
	v_mul_f32_e32 v239, v36, v239
	v_mul_f32_e32 v240, v8, v240
	v_mul_f32_e32 v241, v4, v241
	v_cvt_pk_bf16_f32 v236, v238, v239
	v_cvt_pk_bf16_f32 v237, v240, v241
	global_store_dwordx2 v162, v[236:237], s[10:11]
	v_lshlrev_b32_e32 v0, 16, v180
	v_and_b32_e32 v2, 0xffff0000, v180
	v_lshlrev_b32_e32 v3, 16, v181
	v_and_b32_e32 v133, 0xffff0000, v181
	v_mul_f32_e32 v0, v41, v0
	v_mul_f32_e32 v2, v37, v2
	v_mul_f32_e32 v3, v9, v3
	v_mul_f32_e32 v133, v5, v133
	v_cvt_pk_bf16_f32 v142, v0, v2
	v_cvt_pk_bf16_f32 v143, v3, v133
	global_store_dwordx2 v163, v[142:143], s[10:11]
	v_lshlrev_b32_e32 v238, 16, v182
	v_and_b32_e32 v239, 0xffff0000, v182
	v_lshlrev_b32_e32 v240, 16, v183
	v_and_b32_e32 v241, 0xffff0000, v183
	v_mul_f32_e32 v238, v42, v238
	v_mul_f32_e32 v239, v38, v239
	v_mul_f32_e32 v240, v10, v240
	v_mul_f32_e32 v241, v6, v241
	v_cvt_pk_bf16_f32 v236, v238, v239
	v_cvt_pk_bf16_f32 v237, v240, v241
	global_store_dwordx2 v164, v[236:237], s[10:11]
	v_lshlrev_b32_e32 v0, 16, v184
	v_and_b32_e32 v2, 0xffff0000, v184
	v_lshlrev_b32_e32 v3, 16, v185
	v_and_b32_e32 v133, 0xffff0000, v185
	v_mul_f32_e32 v0, v43, v0
	v_mul_f32_e32 v2, v39, v2
	v_mul_f32_e32 v3, v11, v3
	v_mul_f32_e32 v133, v7, v133
	v_cvt_pk_bf16_f32 v142, v0, v2
	v_cvt_pk_bf16_f32 v143, v3, v133
	global_store_dwordx2 v165, v[142:143], s[10:11]
	v_lshlrev_b32_e32 v238, 16, v186
	v_and_b32_e32 v239, 0xffff0000, v186
	v_lshlrev_b32_e32 v240, 16, v187
	v_and_b32_e32 v241, 0xffff0000, v187
	v_mul_f32_e32 v238, v48, v238
	v_mul_f32_e32 v239, v44, v239
	v_mul_f32_e32 v240, v16, v240
	v_mul_f32_e32 v241, v12, v241
	v_cvt_pk_bf16_f32 v236, v238, v239
	v_cvt_pk_bf16_f32 v237, v240, v241
	global_store_dwordx2 v166, v[236:237], s[10:11]
	v_lshlrev_b32_e32 v0, 16, v188
	v_and_b32_e32 v2, 0xffff0000, v188
	v_lshlrev_b32_e32 v3, 16, v189
	v_and_b32_e32 v133, 0xffff0000, v189
	v_mul_f32_e32 v0, v49, v0
	v_mul_f32_e32 v2, v45, v2
	v_mul_f32_e32 v3, v17, v3
	v_mul_f32_e32 v133, v13, v133
	v_cvt_pk_bf16_f32 v142, v0, v2
	v_cvt_pk_bf16_f32 v143, v3, v133
	global_store_dwordx2 v167, v[142:143], s[10:11]
	v_lshlrev_b32_e32 v238, 16, v190
	v_and_b32_e32 v239, 0xffff0000, v190
	v_lshlrev_b32_e32 v240, 16, v191
	v_and_b32_e32 v241, 0xffff0000, v191
	v_mul_f32_e32 v238, v50, v238
	v_mul_f32_e32 v239, v46, v239
	v_mul_f32_e32 v240, v18, v240
	v_mul_f32_e32 v241, v14, v241
	v_cvt_pk_bf16_f32 v236, v238, v239
	v_cvt_pk_bf16_f32 v237, v240, v241
	global_store_dwordx2 v168, v[236:237], s[10:11]
	v_lshlrev_b32_e32 v0, 16, v192
	v_and_b32_e32 v2, 0xffff0000, v192
	v_lshlrev_b32_e32 v3, 16, v193
	v_and_b32_e32 v133, 0xffff0000, v193
	v_mul_f32_e32 v0, v51, v0
	v_mul_f32_e32 v2, v47, v2
	v_mul_f32_e32 v3, v19, v3
	v_mul_f32_e32 v133, v15, v133
	v_cvt_pk_bf16_f32 v142, v0, v2
	v_cvt_pk_bf16_f32 v143, v3, v133
	global_store_dwordx2 v169, v[142:143], s[10:11]
	s_waitcnt vmcnt(8)
; DEVINL float bf2f(u16 h) { return __uint_as_float(((unsigned)h) << 16); }
;   DEVINL void operator()(Acc& acc, int brow, int bcol) const {
;     ...
;     _Pragma("unroll") for (int ai = 0; ai < 2; ++ai) _Pragma("unroll") for (int m = 0; m < 4; ++m) _Pragma("unroll") for (int j = 0; j < 4; ++j) {
;       const int row = brow + ai * 128 + wr * 64 + m * 16 + fq * 4 + j;
;       const size_t o = (size_t)row * DM + c0;
;       const bf16x4 sn = *(const bf16x4*)(sgn + o);
;       if (which == 0) {
;         const bf16x4 sr = *(const bf16x4*)(sgr + o);
;         acc[ai][0][m][0][j] *= __fdividef(bf2f((u16)sr[0]), fmaxf(bf2f((u16)sn[0]), 1e-30f)); acc[ai][0][m][1][j] *= __fdividef(bf2f((u16)sr[1]), fmaxf(bf2f((u16)sn[1]), 1e-30f));
;         acc[ai][1][m][0][j] *= __fdividef(bf2f((u16)sr[2]), fmaxf(bf2f((u16)sn[2]), 1e-30f)); acc[ai][1][m][1][j] *= __fdividef(bf2f((u16)sr[3]), fmaxf(bf2f((u16)sn[3]), 1e-30f));
;       } else {
;         *(bf16x4*)(merged + o) = pack4(acc[ai][0][m][0][j] * bf2f((u16)sn[0]), acc[ai][0][m][1][j] * bf2f((u16)sn[1]),
;                                        acc[ai][1][m][0][j] * bf2f((u16)sn[2]), acc[ai][1][m][1][j] * bf2f((u16)sn[3]));
	v_lshlrev_b32_e32 v238, 16, v194
	v_and_b32_e32 v239, 0xffff0000, v194
	v_lshlrev_b32_e32 v240, 16, v195
	v_and_b32_e32 v241, 0xffff0000, v195
	v_mul_f32_e32 v238, v56, v238
	v_mul_f32_e32 v239, v52, v239
	v_mul_f32_e32 v240, v24, v240
	v_mul_f32_e32 v241, v20, v241
	v_cvt_pk_bf16_f32 v236, v238, v239
	v_cvt_pk_bf16_f32 v237, v240, v241
	global_store_dwordx2 v170, v[236:237], s[10:11]
	v_lshlrev_b32_e32 v0, 16, v196
	v_and_b32_e32 v2, 0xffff0000, v196
	v_lshlrev_b32_e32 v3, 16, v197
	v_and_b32_e32 v133, 0xffff0000, v197
	v_mul_f32_e32 v0, v57, v0
	v_mul_f32_e32 v2, v53, v2
	v_mul_f32_e32 v3, v25, v3
	v_mul_f32_e32 v133, v21, v133
	v_cvt_pk_bf16_f32 v142, v0, v2
	v_cvt_pk_bf16_f32 v143, v3, v133
	global_store_dwordx2 v171, v[142:143], s[10:11]
	v_lshlrev_b32_e32 v238, 16, v198
	v_and_b32_e32 v239, 0xffff0000, v198
	v_lshlrev_b32_e32 v240, 16, v199
	v_and_b32_e32 v241, 0xffff0000, v199
	v_mul_f32_e32 v238, v58, v238
	v_mul_f32_e32 v239, v54, v239
	v_mul_f32_e32 v240, v26, v240
	v_mul_f32_e32 v241, v22, v241
	v_cvt_pk_bf16_f32 v236, v238, v239
	v_cvt_pk_bf16_f32 v237, v240, v241
	global_store_dwordx2 v172, v[236:237], s[10:11]
	v_lshlrev_b32_e32 v0, 16, v200
	v_and_b32_e32 v2, 0xffff0000, v200
	v_lshlrev_b32_e32 v3, 16, v201
	v_and_b32_e32 v133, 0xffff0000, v201
	v_mul_f32_e32 v0, v59, v0
	v_mul_f32_e32 v2, v55, v2
	v_mul_f32_e32 v3, v27, v3
	v_mul_f32_e32 v133, v23, v133
	v_cvt_pk_bf16_f32 v142, v0, v2
	v_cvt_pk_bf16_f32 v143, v3, v133
	global_store_dwordx2 v173, v[142:143], s[10:11]
	v_lshlrev_b32_e32 v238, 16, v202
	v_and_b32_e32 v239, 0xffff0000, v202
	v_lshlrev_b32_e32 v240, 16, v203
	v_and_b32_e32 v241, 0xffff0000, v203
	v_mul_f32_e32 v238, v64, v238
	v_mul_f32_e32 v239, v60, v239
	v_mul_f32_e32 v240, v32, v240
	v_mul_f32_e32 v241, v28, v241
	v_cvt_pk_bf16_f32 v236, v238, v239
	v_cvt_pk_bf16_f32 v237, v240, v241
	global_store_dwordx2 v174, v[236:237], s[10:11]
	v_lshlrev_b32_e32 v0, 16, v204
	v_and_b32_e32 v2, 0xffff0000, v204
	v_lshlrev_b32_e32 v3, 16, v205
	v_and_b32_e32 v133, 0xffff0000, v205
	v_mul_f32_e32 v0, v65, v0
	v_mul_f32_e32 v2, v61, v2
	v_mul_f32_e32 v3, v33, v3
	v_mul_f32_e32 v133, v29, v133
	v_cvt_pk_bf16_f32 v142, v0, v2
	v_cvt_pk_bf16_f32 v143, v3, v133
	global_store_dwordx2 v175, v[142:143], s[10:11]
	v_lshlrev_b32_e32 v238, 16, v206
	v_and_b32_e32 v239, 0xffff0000, v206
	v_lshlrev_b32_e32 v240, 16, v207
	v_and_b32_e32 v241, 0xffff0000, v207
	v_mul_f32_e32 v238, v66, v238
	v_mul_f32_e32 v239, v62, v239
	v_mul_f32_e32 v240, v34, v240
	v_mul_f32_e32 v241, v30, v241
	v_cvt_pk_bf16_f32 v236, v238, v239
	v_cvt_pk_bf16_f32 v237, v240, v241
	global_store_dwordx2 v176, v[236:237], s[10:11]
	v_lshlrev_b32_e32 v0, 16, v208
	v_and_b32_e32 v2, 0xffff0000, v208
	v_lshlrev_b32_e32 v3, 16, v209
	v_and_b32_e32 v133, 0xffff0000, v209
	v_mul_f32_e32 v0, v67, v0
	v_mul_f32_e32 v2, v63, v2
	v_mul_f32_e32 v3, v35, v3
	v_mul_f32_e32 v133, v31, v133
	v_cvt_pk_bf16_f32 v142, v0, v2
	v_cvt_pk_bf16_f32 v143, v3, v133
	global_store_dwordx2 v177, v[142:143], s[10:11]
	s_waitcnt lgkmcnt(0)
	s_branch .LBB0_127
.Lmx_w0:
	v_add_u32_e32 v162, 0x0, v132
	global_load_dwordx2 v[178:179], v162, s[14:15]
	global_load_dwordx2 v[210:211], v162, s[12:13]
	v_add_u32_e32 v163, 0x800, v132
	global_load_dwordx2 v[180:181], v163, s[14:15]
	global_load_dwordx2 v[212:213], v163, s[12:13]
	v_add_u32_e32 v164, 0x1000, v132
	global_load_dwordx2 v[182:183], v164, s[14:15]
	global_load_dwordx2 v[214:215], v164, s[12:13]
	v_add_u32_e32 v165, 0x1800, v132
	global_load_dwordx2 v[184:185], v165, s[14:15]
	global_load_dwordx2 v[216:217], v165, s[12:13]
	v_add_u32_e32 v166, 0x8000, v132
	global_load_dwordx2 v[186:187], v166, s[14:15]
	global_load_dwordx2 v[218:219], v166, s[12:13]
	v_add_u32_e32 v167, 0x8800, v132
	global_load_dwordx2 v[188:189], v167, s[14:15]
	global_load_dwordx2 v[220:221], v167, s[12:13]
	v_add_u32_e32 v168, 0x9000, v132
	global_load_dwordx2 v[190:191], v168, s[14:15]
	global_load_dwordx2 v[222:223], v168, s[12:13]
	v_add_u32_e32 v169, 0x9800, v132
	global_load_dwordx2 v[192:193], v169, s[14:15]
	global_load_dwordx2 v[224:225], v169, s[12:13]
	v_add_u32_e32 v170, 0x10000, v132
	global_load_dwordx2 v[194:195], v170, s[14:15]
	global_load_dwordx2 v[226:227], v170, s[12:13]
	v_add_u32_e32 v171, 0x10800, v132
	global_load_dwordx2 v[196:197], v171, s[14:15]
	global_load_dwordx2 v[228:229], v171, s[12:13]
	v_add_u32_e32 v172, 0x11000, v132
	global_load_dwordx2 v[198:199], v172, s[14:15]
	global_load_dwordx2 v[230:231], v172, s[12:13]
	v_add_u32_e32 v173, 0x11800, v132
	global_load_dwordx2 v[200:201], v173, s[14:15]
	global_load_dwordx2 v[232:233], v173, s[12:13]
	v_add_u32_e32 v174, 0x18000, v132
	global_load_dwordx2 v[202:203], v174, s[14:15]
	global_load_dwordx2 v[134:135], v174, s[12:13]
	v_add_u32_e32 v175, 0x18800, v132
	global_load_dwordx2 v[204:205], v175, s[14:15]
	global_load_dwordx2 v[136:137], v175, s[12:13]
	v_add_u32_e32 v176, 0x19000, v132
	global_load_dwordx2 v[206:207], v176, s[14:15]
	global_load_dwordx2 v[138:139], v176, s[12:13]
	v_add_u32_e32 v177, 0x19800, v132
	global_load_dwordx2 v[208:209], v177, s[14:15]
	global_load_dwordx2 v[140:141], v177, s[12:13]
	s_waitcnt vmcnt(16)
; DEVINL float bf2f(u16 h) { return __uint_as_float(((unsigned)h) << 16); }
;   DEVINL void operator()(Acc& acc, int brow, int bcol) const {
;     ...
;     _Pragma("unroll") for (int ai = 0; ai < 2; ++ai) _Pragma("unroll") for (int m = 0; m < 4; ++m) _Pragma("unroll") for (int j = 0; j < 4; ++j) {
;       const int row = brow + ai * 128 + wr * 64 + m * 16 + fq * 4 + j;
;       const size_t o = (size_t)row * DM + c0;
;       const bf16x4 sn = *(const bf16x4*)(sgn + o);
;       if (which == 0) {
;         const bf16x4 sr = *(const bf16x4*)(sgr + o);
;         acc[ai][0][m][0][j] *= __fdividef(bf2f((u16)sr[0]), fmaxf(bf2f((u16)sn[0]), 1e-30f)); acc[ai][0][m][1][j] *= __fdividef(bf2f((u16)sr[1]), fmaxf(bf2f((u16)sn[1]), 1e-30f));
;         acc[ai][1][m][0][j] *= __fdividef(bf2f((u16)sr[2]), fmaxf(bf2f((u16)sn[2]), 1e-30f)); acc[ai][1][m][1][j] *= __fdividef(bf2f((u16)sr[3]), fmaxf(bf2f((u16)sn[3]), 1e-30f));
	v_lshlrev_b32_e32 v238, 16, v178
	v_and_b32_e32 v239, 0xffff0000, v178
	v_lshlrev_b32_e32 v240, 16, v179
	v_and_b32_e32 v241, 0xffff0000, v179
	v_max_f32_e32 v238, 0xda24260, v238
	v_max_f32_e32 v239, 0xda24260, v239
	v_max_f32_e32 v240, 0xda24260, v240
	v_max_f32_e32 v241, 0xda24260, v241
	v_rcp_f32_e32 v238, v238
	v_rcp_f32_e32 v239, v239
	v_rcp_f32_e32 v240, v240
	v_rcp_f32_e32 v241, v241
	v_lshlrev_b32_e32 v0, 16, v210
	v_and_b32_e32 v2, 0xffff0000, v210
	v_lshlrev_b32_e32 v3, 16, v211
	v_and_b32_e32 v133, 0xffff0000, v211
	v_mul_f32_e32 v0, v0, v238
	v_mul_f32_e32 v2, v2, v239
	v_mul_f32_e32 v3, v3, v240
	v_mul_f32_e32 v133, v133, v241
	v_mul_f32_e32 v104, v104, v0
	v_mul_f32_e32 v100, v100, v2
	v_mul_f32_e32 v72, v72, v3
	v_mul_f32_e32 v68, v68, v133
	v_lshlrev_b32_e32 v236, 16, v180
	v_and_b32_e32 v237, 0xffff0000, v180
	v_lshlrev_b32_e32 v142, 16, v181
	v_and_b32_e32 v143, 0xffff0000, v181
	v_max_f32_e32 v236, 0xda24260, v236
	v_max_f32_e32 v237, 0xda24260, v237
	v_max_f32_e32 v142, 0xda24260, v142
	v_max_f32_e32 v143, 0xda24260, v143
	v_rcp_f32_e32 v236, v236
	v_rcp_f32_e32 v237, v237
	v_rcp_f32_e32 v142, v142
	v_rcp_f32_e32 v143, v143
	v_lshlrev_b32_e32 v0, 16, v212
	v_and_b32_e32 v2, 0xffff0000, v212
	v_lshlrev_b32_e32 v3, 16, v213
	v_and_b32_e32 v133, 0xffff0000, v213
	v_mul_f32_e32 v0, v0, v236
	v_mul_f32_e32 v2, v2, v237
	v_mul_f32_e32 v3, v3, v142
	v_mul_f32_e32 v133, v133, v143
	v_mul_f32_e32 v105, v105, v0
	v_mul_f32_e32 v101, v101, v2
	v_mul_f32_e32 v73, v73, v3
	v_mul_f32_e32 v69, v69, v133
	v_lshlrev_b32_e32 v238, 16, v182
	v_and_b32_e32 v239, 0xffff0000, v182
	v_lshlrev_b32_e32 v240, 16, v183
	v_and_b32_e32 v241, 0xffff0000, v183
	v_max_f32_e32 v238, 0xda24260, v238
	v_max_f32_e32 v239, 0xda24260, v239
	v_max_f32_e32 v240, 0xda24260, v240
	v_max_f32_e32 v241, 0xda24260, v241
	v_rcp_f32_e32 v238, v238
	v_rcp_f32_e32 v239, v239
	v_rcp_f32_e32 v240, v240
	v_rcp_f32_e32 v241, v241
	v_lshlrev_b32_e32 v0, 16, v214
	v_and_b32_e32 v2, 0xffff0000, v214
	v_lshlrev_b32_e32 v3, 16, v215
	v_and_b32_e32 v133, 0xffff0000, v215
	v_mul_f32_e32 v0, v0, v238
	v_mul_f32_e32 v2, v2, v239
	v_mul_f32_e32 v3, v3, v240
	v_mul_f32_e32 v133, v133, v241
	v_mul_f32_e32 v106, v106, v0
	v_mul_f32_e32 v102, v102, v2
	v_mul_f32_e32 v74, v74, v3
	v_mul_f32_e32 v70, v70, v133
	v_lshlrev_b32_e32 v236, 16, v184
	v_and_b32_e32 v237, 0xffff0000, v184
	v_lshlrev_b32_e32 v142, 16, v185
	v_and_b32_e32 v143, 0xffff0000, v185
	v_max_f32_e32 v236, 0xda24260, v236
	v_max_f32_e32 v237, 0xda24260, v237
	v_max_f32_e32 v142, 0xda24260, v142
	v_max_f32_e32 v143, 0xda24260, v143
	v_rcp_f32_e32 v236, v236
	v_rcp_f32_e32 v237, v237
	v_rcp_f32_e32 v142, v142
	v_rcp_f32_e32 v143, v143
	v_lshlrev_b32_e32 v0, 16, v216
	v_and_b32_e32 v2, 0xffff0000, v216
	v_lshlrev_b32_e32 v3, 16, v217
	v_and_b32_e32 v133, 0xffff0000, v217
	v_mul_f32_e32 v0, v0, v236
	v_mul_f32_e32 v2, v2, v237
	v_mul_f32_e32 v3, v3, v142
	v_mul_f32_e32 v133, v133, v143
	v_mul_f32_e32 v107, v107, v0
	v_mul_f32_e32 v103, v103, v2
	v_mul_f32_e32 v75, v75, v3
	v_mul_f32_e32 v71, v71, v133
	v_lshlrev_b32_e32 v238, 16, v186
	v_and_b32_e32 v239, 0xffff0000, v186
	v_lshlrev_b32_e32 v240, 16, v187
	v_and_b32_e32 v241, 0xffff0000, v187
	v_max_f32_e32 v238, 0xda24260, v238
	v_max_f32_e32 v239, 0xda24260, v239
	v_max_f32_e32 v240, 0xda24260, v240
	v_max_f32_e32 v241, 0xda24260, v241
	v_rcp_f32_e32 v238, v238
	v_rcp_f32_e32 v239, v239
	v_rcp_f32_e32 v240, v240
	v_rcp_f32_e32 v241, v241
	v_lshlrev_b32_e32 v0, 16, v218
	v_and_b32_e32 v2, 0xffff0000, v218
	v_lshlrev_b32_e32 v3, 16, v219
	v_and_b32_e32 v133, 0xffff0000, v219
	v_mul_f32_e32 v0, v0, v238
	v_mul_f32_e32 v2, v2, v239
	v_mul_f32_e32 v3, v3, v240
	v_mul_f32_e32 v133, v133, v241
	v_mul_f32_e32 v112, v112, v0
	v_mul_f32_e32 v108, v108, v2
	v_mul_f32_e32 v80, v80, v3
	v_mul_f32_e32 v76, v76, v133
	v_lshlrev_b32_e32 v236, 16, v188
	v_and_b32_e32 v237, 0xffff0000, v188
	v_lshlrev_b32_e32 v142, 16, v189
	v_and_b32_e32 v143, 0xffff0000, v189
	v_max_f32_e32 v236, 0xda24260, v236
	v_max_f32_e32 v237, 0xda24260, v237
	v_max_f32_e32 v142, 0xda24260, v142
	v_max_f32_e32 v143, 0xda24260, v143
	v_rcp_f32_e32 v236, v236
	v_rcp_f32_e32 v237, v237
	v_rcp_f32_e32 v142, v142
	v_rcp_f32_e32 v143, v143
	v_lshlrev_b32_e32 v0, 16, v220
	v_and_b32_e32 v2, 0xffff0000, v220
	v_lshlrev_b32_e32 v3, 16, v221
	v_and_b32_e32 v133, 0xffff0000, v221
	v_mul_f32_e32 v0, v0, v236
	v_mul_f32_e32 v2, v2, v237
	v_mul_f32_e32 v3, v3, v142
	v_mul_f32_e32 v133, v133, v143
	v_mul_f32_e32 v113, v113, v0
	v_mul_f32_e32 v109, v109, v2
	v_mul_f32_e32 v81, v81, v3
	v_mul_f32_e32 v77, v77, v133
	v_lshlrev_b32_e32 v238, 16, v190
	v_and_b32_e32 v239, 0xffff0000, v190
	v_lshlrev_b32_e32 v240, 16, v191
	v_and_b32_e32 v241, 0xffff0000, v191
	v_max_f32_e32 v238, 0xda24260, v238
	v_max_f32_e32 v239, 0xda24260, v239
	v_max_f32_e32 v240, 0xda24260, v240
	v_max_f32_e32 v241, 0xda24260, v241
	v_rcp_f32_e32 v238, v238
	v_rcp_f32_e32 v239, v239
	v_rcp_f32_e32 v240, v240
	v_rcp_f32_e32 v241, v241
	v_lshlrev_b32_e32 v0, 16, v222
	v_and_b32_e32 v2, 0xffff0000, v222
	v_lshlrev_b32_e32 v3, 16, v223
	v_and_b32_e32 v133, 0xffff0000, v223
	v_mul_f32_e32 v0, v0, v238
	v_mul_f32_e32 v2, v2, v239
	v_mul_f32_e32 v3, v3, v240
	v_mul_f32_e32 v133, v133, v241
	v_mul_f32_e32 v114, v114, v0
	v_mul_f32_e32 v110, v110, v2
	v_mul_f32_e32 v82, v82, v3
	v_mul_f32_e32 v78, v78, v133
	v_lshlrev_b32_e32 v236, 16, v192
	v_and_b32_e32 v237, 0xffff0000, v192
	v_lshlrev_b32_e32 v142, 16, v193
	v_and_b32_e32 v143, 0xffff0000, v193
	v_max_f32_e32 v236, 0xda24260, v236
	v_max_f32_e32 v237, 0xda24260, v237
	v_max_f32_e32 v142, 0xda24260, v142
; DEVINL float bf2f(u16 h) { return __uint_as_float(((unsigned)h) << 16); }
;   DEVINL void operator()(Acc& acc, int brow, int bcol) const {
;     ...
;     _Pragma("unroll") for (int ai = 0; ai < 2; ++ai) _Pragma("unroll") for (int m = 0; m < 4; ++m) _Pragma("unroll") for (int j = 0; j < 4; ++j) {
;       const int row = brow + ai * 128 + wr * 64 + m * 16 + fq * 4 + j;
;       const size_t o = (size_t)row * DM + c0;
;       const bf16x4 sn = *(const bf16x4*)(sgn + o);
;       if (which == 0) {
;         const bf16x4 sr = *(const bf16x4*)(sgr + o);
;         acc[ai][0][m][0][j] *= __fdividef(bf2f((u16)sr[0]), fmaxf(bf2f((u16)sn[0]), 1e-30f)); acc[ai][0][m][1][j] *= __fdividef(bf2f((u16)sr[1]), fmaxf(bf2f((u16)sn[1]), 1e-30f));
;         acc[ai][1][m][0][j] *= __fdividef(bf2f((u16)sr[2]), fmaxf(bf2f((u16)sn[2]), 1e-30f)); acc[ai][1][m][1][j] *= __fdividef(bf2f((u16)sr[3]), fmaxf(bf2f((u16)sn[3]), 1e-30f));
	v_max_f32_e32 v143, 0xda24260, v143
	v_rcp_f32_e32 v236, v236
	v_rcp_f32_e32 v237, v237
	v_rcp_f32_e32 v142, v142
	v_rcp_f32_e32 v143, v143
	v_lshlrev_b32_e32 v0, 16, v224
	v_and_b32_e32 v2, 0xffff0000, v224
	v_lshlrev_b32_e32 v3, 16, v225
	v_and_b32_e32 v133, 0xffff0000, v225
	v_mul_f32_e32 v0, v0, v236
	v_mul_f32_e32 v2, v2, v237
	v_mul_f32_e32 v3, v3, v142
	v_mul_f32_e32 v133, v133, v143
	v_mul_f32_e32 v115, v115, v0
	v_mul_f32_e32 v111, v111, v2
	v_mul_f32_e32 v83, v83, v3
	v_mul_f32_e32 v79, v79, v133
	v_add_u32_e32 v162, 0x40000, v132
	global_load_dwordx2 v[178:179], v162, s[14:15]
	global_load_dwordx2 v[210:211], v162, s[12:13]
	v_add_u32_e32 v163, 0x40800, v132
	global_load_dwordx2 v[180:181], v163, s[14:15]
	global_load_dwordx2 v[212:213], v163, s[12:13]
	v_add_u32_e32 v164, 0x41000, v132
	global_load_dwordx2 v[182:183], v164, s[14:15]
	global_load_dwordx2 v[214:215], v164, s[12:13]
	v_add_u32_e32 v165, 0x41800, v132
	global_load_dwordx2 v[184:185], v165, s[14:15]
	global_load_dwordx2 v[216:217], v165, s[12:13]
	v_add_u32_e32 v166, 0x48000, v132
	global_load_dwordx2 v[186:187], v166, s[14:15]
	global_load_dwordx2 v[218:219], v166, s[12:13]
	v_add_u32_e32 v167, 0x48800, v132
	global_load_dwordx2 v[188:189], v167, s[14:15]
	global_load_dwordx2 v[220:221], v167, s[12:13]
	v_add_u32_e32 v168, 0x49000, v132
	global_load_dwordx2 v[190:191], v168, s[14:15]
	global_load_dwordx2 v[222:223], v168, s[12:13]
	v_add_u32_e32 v169, 0x49800, v132
	global_load_dwordx2 v[192:193], v169, s[14:15]
	global_load_dwordx2 v[224:225], v169, s[12:13]
	s_waitcnt vmcnt(16)
	v_lshlrev_b32_e32 v238, 16, v194
	v_and_b32_e32 v239, 0xffff0000, v194
	v_lshlrev_b32_e32 v240, 16, v195
	v_and_b32_e32 v241, 0xffff0000, v195
	v_max_f32_e32 v238, 0xda24260, v238
	v_max_f32_e32 v239, 0xda24260, v239
	v_max_f32_e32 v240, 0xda24260, v240
	v_max_f32_e32 v241, 0xda24260, v241
	v_rcp_f32_e32 v238, v238
	v_rcp_f32_e32 v239, v239
	v_rcp_f32_e32 v240, v240
	v_rcp_f32_e32 v241, v241
	v_lshlrev_b32_e32 v0, 16, v226
	v_and_b32_e32 v2, 0xffff0000, v226
	v_lshlrev_b32_e32 v3, 16, v227
	v_and_b32_e32 v133, 0xffff0000, v227
	v_mul_f32_e32 v0, v0, v238
	v_mul_f32_e32 v2, v2, v239
	v_mul_f32_e32 v3, v3, v240
	v_mul_f32_e32 v133, v133, v241
	v_mul_f32_e32 v120, v120, v0
	v_mul_f32_e32 v116, v116, v2
	v_mul_f32_e32 v88, v88, v3
	v_mul_f32_e32 v84, v84, v133
	v_lshlrev_b32_e32 v236, 16, v196
	v_and_b32_e32 v237, 0xffff0000, v196
	v_lshlrev_b32_e32 v142, 16, v197
	v_and_b32_e32 v143, 0xffff0000, v197
	v_max_f32_e32 v236, 0xda24260, v236
	v_max_f32_e32 v237, 0xda24260, v237
	v_max_f32_e32 v142, 0xda24260, v142
	v_max_f32_e32 v143, 0xda24260, v143
	v_rcp_f32_e32 v236, v236
	v_rcp_f32_e32 v237, v237
	v_rcp_f32_e32 v142, v142
	v_rcp_f32_e32 v143, v143
	v_lshlrev_b32_e32 v0, 16, v228
	v_and_b32_e32 v2, 0xffff0000, v228
	v_lshlrev_b32_e32 v3, 16, v229
	v_and_b32_e32 v133, 0xffff0000, v229
	v_mul_f32_e32 v0, v0, v236
	v_mul_f32_e32 v2, v2, v237
	v_mul_f32_e32 v3, v3, v142
	v_mul_f32_e32 v133, v133, v143
	v_mul_f32_e32 v121, v121, v0
	v_mul_f32_e32 v117, v117, v2
	v_mul_f32_e32 v89, v89, v3
	v_mul_f32_e32 v85, v85, v133
	v_lshlrev_b32_e32 v238, 16, v198
	v_and_b32_e32 v239, 0xffff0000, v198
	v_lshlrev_b32_e32 v240, 16, v199
	v_and_b32_e32 v241, 0xffff0000, v199
	v_max_f32_e32 v238, 0xda24260, v238
	v_max_f32_e32 v239, 0xda24260, v239
	v_max_f32_e32 v240, 0xda24260, v240
	v_max_f32_e32 v241, 0xda24260, v241
	v_rcp_f32_e32 v238, v238
	v_rcp_f32_e32 v239, v239
	v_rcp_f32_e32 v240, v240
	v_rcp_f32_e32 v241, v241
	v_lshlrev_b32_e32 v0, 16, v230
	v_and_b32_e32 v2, 0xffff0000, v230
	v_lshlrev_b32_e32 v3, 16, v231
	v_and_b32_e32 v133, 0xffff0000, v231
	v_mul_f32_e32 v0, v0, v238
	v_mul_f32_e32 v2, v2, v239
	v_mul_f32_e32 v3, v3, v240
	v_mul_f32_e32 v133, v133, v241
	v_mul_f32_e32 v122, v122, v0
	v_mul_f32_e32 v118, v118, v2
	v_mul_f32_e32 v90, v90, v3
	v_mul_f32_e32 v86, v86, v133
	v_lshlrev_b32_e32 v236, 16, v200
	v_and_b32_e32 v237, 0xffff0000, v200
	v_lshlrev_b32_e32 v142, 16, v201
	v_and_b32_e32 v143, 0xffff0000, v201
	v_max_f32_e32 v236, 0xda24260, v236
	v_max_f32_e32 v237, 0xda24260, v237
	v_max_f32_e32 v142, 0xda24260, v142
	v_max_f32_e32 v143, 0xda24260, v143
	v_rcp_f32_e32 v236, v236
	v_rcp_f32_e32 v237, v237
	v_rcp_f32_e32 v142, v142
	v_rcp_f32_e32 v143, v143
	v_lshlrev_b32_e32 v0, 16, v232
	v_and_b32_e32 v2, 0xffff0000, v232
	v_lshlrev_b32_e32 v3, 16, v233
	v_and_b32_e32 v133, 0xffff0000, v233
	v_mul_f32_e32 v0, v0, v236
	v_mul_f32_e32 v2, v2, v237
	v_mul_f32_e32 v3, v3, v142
	v_mul_f32_e32 v133, v133, v143
	v_mul_f32_e32 v123, v123, v0
	v_mul_f32_e32 v119, v119, v2
	v_mul_f32_e32 v91, v91, v3
	v_mul_f32_e32 v87, v87, v133
	v_lshlrev_b32_e32 v238, 16, v202
	v_and_b32_e32 v239, 0xffff0000, v202
	v_lshlrev_b32_e32 v240, 16, v203
	v_and_b32_e32 v241, 0xffff0000, v203
	v_max_f32_e32 v238, 0xda24260, v238
	v_max_f32_e32 v239, 0xda24260, v239
	v_max_f32_e32 v240, 0xda24260, v240
	v_max_f32_e32 v241, 0xda24260, v241
	v_rcp_f32_e32 v238, v238
	v_rcp_f32_e32 v239, v239
	v_rcp_f32_e32 v240, v240
	v_rcp_f32_e32 v241, v241
	v_lshlrev_b32_e32 v0, 16, v134
	v_and_b32_e32 v2, 0xffff0000, v134
	v_lshlrev_b32_e32 v3, 16, v135
	v_and_b32_e32 v133, 0xffff0000, v135
	v_mul_f32_e32 v0, v0, v238
	v_mul_f32_e32 v2, v2, v239
	v_mul_f32_e32 v3, v3, v240
	v_mul_f32_e32 v133, v133, v241
	v_mul_f32_e32 v128, v128, v0
	v_mul_f32_e32 v124, v124, v2
	v_mul_f32_e32 v96, v96, v3
	v_mul_f32_e32 v92, v92, v133
	v_lshlrev_b32_e32 v236, 16, v204
	v_and_b32_e32 v237, 0xffff0000, v204
	v_lshlrev_b32_e32 v142, 16, v205
	v_and_b32_e32 v143, 0xffff0000, v205
	v_max_f32_e32 v236, 0xda24260, v236
	v_max_f32_e32 v237, 0xda24260, v237
; DEVINL float bf2f(u16 h) { return __uint_as_float(((unsigned)h) << 16); }
;   DEVINL void operator()(Acc& acc, int brow, int bcol) const {
;     ...
;     _Pragma("unroll") for (int ai = 0; ai < 2; ++ai) _Pragma("unroll") for (int m = 0; m < 4; ++m) _Pragma("unroll") for (int j = 0; j < 4; ++j) {
;       const int row = brow + ai * 128 + wr * 64 + m * 16 + fq * 4 + j;
;       const size_t o = (size_t)row * DM + c0;
;       const bf16x4 sn = *(const bf16x4*)(sgn + o);
;       if (which == 0) {
;         const bf16x4 sr = *(const bf16x4*)(sgr + o);
;         acc[ai][0][m][0][j] *= __fdividef(bf2f((u16)sr[0]), fmaxf(bf2f((u16)sn[0]), 1e-30f)); acc[ai][0][m][1][j] *= __fdividef(bf2f((u16)sr[1]), fmaxf(bf2f((u16)sn[1]), 1e-30f));
;         acc[ai][1][m][0][j] *= __fdividef(bf2f((u16)sr[2]), fmaxf(bf2f((u16)sn[2]), 1e-30f)); acc[ai][1][m][1][j] *= __fdividef(bf2f((u16)sr[3]), fmaxf(bf2f((u16)sn[3]), 1e-30f));
	v_max_f32_e32 v142, 0xda24260, v142
	v_max_f32_e32 v143, 0xda24260, v143
	v_rcp_f32_e32 v236, v236
	v_rcp_f32_e32 v237, v237
	v_rcp_f32_e32 v142, v142
	v_rcp_f32_e32 v143, v143
	v_lshlrev_b32_e32 v0, 16, v136
	v_and_b32_e32 v2, 0xffff0000, v136
	v_lshlrev_b32_e32 v3, 16, v137
	v_and_b32_e32 v133, 0xffff0000, v137
	v_mul_f32_e32 v0, v0, v236
	v_mul_f32_e32 v2, v2, v237
	v_mul_f32_e32 v3, v3, v142
	v_mul_f32_e32 v133, v133, v143
	v_mul_f32_e32 v129, v129, v0
	v_mul_f32_e32 v125, v125, v2
	v_mul_f32_e32 v97, v97, v3
	v_mul_f32_e32 v93, v93, v133
	v_lshlrev_b32_e32 v238, 16, v206
	v_and_b32_e32 v239, 0xffff0000, v206
	v_lshlrev_b32_e32 v240, 16, v207
	v_and_b32_e32 v241, 0xffff0000, v207
	v_max_f32_e32 v238, 0xda24260, v238
	v_max_f32_e32 v239, 0xda24260, v239
	v_max_f32_e32 v240, 0xda24260, v240
	v_max_f32_e32 v241, 0xda24260, v241
	v_rcp_f32_e32 v238, v238
	v_rcp_f32_e32 v239, v239
	v_rcp_f32_e32 v240, v240
	v_rcp_f32_e32 v241, v241
	v_lshlrev_b32_e32 v0, 16, v138
	v_and_b32_e32 v2, 0xffff0000, v138
	v_lshlrev_b32_e32 v3, 16, v139
	v_and_b32_e32 v133, 0xffff0000, v139
	v_mul_f32_e32 v0, v0, v238
	v_mul_f32_e32 v2, v2, v239
	v_mul_f32_e32 v3, v3, v240
	v_mul_f32_e32 v133, v133, v241
	v_mul_f32_e32 v130, v130, v0
	v_mul_f32_e32 v126, v126, v2
	v_mul_f32_e32 v98, v98, v3
	v_mul_f32_e32 v94, v94, v133
	v_lshlrev_b32_e32 v236, 16, v208
	v_and_b32_e32 v237, 0xffff0000, v208
	v_lshlrev_b32_e32 v142, 16, v209
	v_and_b32_e32 v143, 0xffff0000, v209
	v_max_f32_e32 v236, 0xda24260, v236
	v_max_f32_e32 v237, 0xda24260, v237
	v_max_f32_e32 v142, 0xda24260, v142
	v_max_f32_e32 v143, 0xda24260, v143
	v_rcp_f32_e32 v236, v236
	v_rcp_f32_e32 v237, v237
	v_rcp_f32_e32 v142, v142
	v_rcp_f32_e32 v143, v143
	v_lshlrev_b32_e32 v0, 16, v140
	v_and_b32_e32 v2, 0xffff0000, v140
	v_lshlrev_b32_e32 v3, 16, v141
	v_and_b32_e32 v133, 0xffff0000, v141
	v_mul_f32_e32 v0, v0, v236
	v_mul_f32_e32 v2, v2, v237
	v_mul_f32_e32 v3, v3, v142
	v_mul_f32_e32 v133, v133, v143
	v_mul_f32_e32 v131, v131, v0
	v_mul_f32_e32 v127, v127, v2
	v_mul_f32_e32 v99, v99, v3
	v_mul_f32_e32 v95, v95, v133
	v_add_u32_e32 v170, 0x50000, v132
	global_load_dwordx2 v[194:195], v170, s[14:15]
	global_load_dwordx2 v[226:227], v170, s[12:13]
	v_add_u32_e32 v171, 0x50800, v132
	global_load_dwordx2 v[196:197], v171, s[14:15]
	global_load_dwordx2 v[228:229], v171, s[12:13]
	v_add_u32_e32 v172, 0x51000, v132
	global_load_dwordx2 v[198:199], v172, s[14:15]
	global_load_dwordx2 v[230:231], v172, s[12:13]
	v_add_u32_e32 v173, 0x51800, v132
	global_load_dwordx2 v[200:201], v173, s[14:15]
	global_load_dwordx2 v[232:233], v173, s[12:13]
	v_add_u32_e32 v174, 0x58000, v132
	global_load_dwordx2 v[202:203], v174, s[14:15]
	global_load_dwordx2 v[134:135], v174, s[12:13]
	v_add_u32_e32 v175, 0x58800, v132
	global_load_dwordx2 v[204:205], v175, s[14:15]
	global_load_dwordx2 v[136:137], v175, s[12:13]
	v_add_u32_e32 v176, 0x59000, v132
	global_load_dwordx2 v[206:207], v176, s[14:15]
	global_load_dwordx2 v[138:139], v176, s[12:13]
	v_add_u32_e32 v177, 0x59800, v132
	global_load_dwordx2 v[208:209], v177, s[14:15]
	global_load_dwordx2 v[140:141], v177, s[12:13]
	s_waitcnt vmcnt(16)
	v_lshlrev_b32_e32 v238, 16, v178
	v_and_b32_e32 v239, 0xffff0000, v178
	v_lshlrev_b32_e32 v240, 16, v179
	v_and_b32_e32 v241, 0xffff0000, v179
	v_max_f32_e32 v238, 0xda24260, v238
	v_max_f32_e32 v239, 0xda24260, v239
	v_max_f32_e32 v240, 0xda24260, v240
	v_max_f32_e32 v241, 0xda24260, v241
	v_rcp_f32_e32 v238, v238
	v_rcp_f32_e32 v239, v239
	v_rcp_f32_e32 v240, v240
	v_rcp_f32_e32 v241, v241
	v_lshlrev_b32_e32 v0, 16, v210
	v_and_b32_e32 v2, 0xffff0000, v210
	v_lshlrev_b32_e32 v3, 16, v211
	v_and_b32_e32 v133, 0xffff0000, v211
	v_mul_f32_e32 v0, v0, v238
	v_mul_f32_e32 v2, v2, v239
	v_mul_f32_e32 v3, v3, v240
	v_mul_f32_e32 v133, v133, v241
	v_mul_f32_e32 v40, v40, v0
	v_mul_f32_e32 v36, v36, v2
	v_mul_f32_e32 v8, v8, v3
	v_mul_f32_e32 v4, v4, v133
	v_lshlrev_b32_e32 v236, 16, v180
	v_and_b32_e32 v237, 0xffff0000, v180
	v_lshlrev_b32_e32 v142, 16, v181
	v_and_b32_e32 v143, 0xffff0000, v181
	v_max_f32_e32 v236, 0xda24260, v236
	v_max_f32_e32 v237, 0xda24260, v237
	v_max_f32_e32 v142, 0xda24260, v142
	v_max_f32_e32 v143, 0xda24260, v143
	v_rcp_f32_e32 v236, v236
	v_rcp_f32_e32 v237, v237
	v_rcp_f32_e32 v142, v142
	v_rcp_f32_e32 v143, v143
	v_lshlrev_b32_e32 v0, 16, v212
	v_and_b32_e32 v2, 0xffff0000, v212
	v_lshlrev_b32_e32 v3, 16, v213
	v_and_b32_e32 v133, 0xffff0000, v213
	v_mul_f32_e32 v0, v0, v236
	v_mul_f32_e32 v2, v2, v237
	v_mul_f32_e32 v3, v3, v142
	v_mul_f32_e32 v133, v133, v143
	v_mul_f32_e32 v41, v41, v0
	v_mul_f32_e32 v37, v37, v2
	v_mul_f32_e32 v9, v9, v3
	v_mul_f32_e32 v5, v5, v133
	v_lshlrev_b32_e32 v238, 16, v182
	v_and_b32_e32 v239, 0xffff0000, v182
	v_lshlrev_b32_e32 v240, 16, v183
	v_and_b32_e32 v241, 0xffff0000, v183
	v_max_f32_e32 v238, 0xda24260, v238
	v_max_f32_e32 v239, 0xda24260, v239
	v_max_f32_e32 v240, 0xda24260, v240
	v_max_f32_e32 v241, 0xda24260, v241
	v_rcp_f32_e32 v238, v238
	v_rcp_f32_e32 v239, v239
	v_rcp_f32_e32 v240, v240
	v_rcp_f32_e32 v241, v241
	v_lshlrev_b32_e32 v0, 16, v214
	v_and_b32_e32 v2, 0xffff0000, v214
	v_lshlrev_b32_e32 v3, 16, v215
	v_and_b32_e32 v133, 0xffff0000, v215
	v_mul_f32_e32 v0, v0, v238
	v_mul_f32_e32 v2, v2, v239
	v_mul_f32_e32 v3, v3, v240
	v_mul_f32_e32 v133, v133, v241
	v_mul_f32_e32 v42, v42, v0
	v_mul_f32_e32 v38, v38, v2
	v_mul_f32_e32 v10, v10, v3
	v_mul_f32_e32 v6, v6, v133
	v_lshlrev_b32_e32 v236, 16, v184
	v_and_b32_e32 v237, 0xffff0000, v184
	v_lshlrev_b32_e32 v142, 16, v185
	v_and_b32_e32 v143, 0xffff0000, v185
	v_max_f32_e32 v236, 0xda24260, v236
	v_max_f32_e32 v237, 0xda24260, v237
; DEVINL float bf2f(u16 h) { return __uint_as_float(((unsigned)h) << 16); }
;   DEVINL void operator()(Acc& acc, int brow, int bcol) const {
;     ...
;     _Pragma("unroll") for (int ai = 0; ai < 2; ++ai) _Pragma("unroll") for (int m = 0; m < 4; ++m) _Pragma("unroll") for (int j = 0; j < 4; ++j) {
;       const int row = brow + ai * 128 + wr * 64 + m * 16 + fq * 4 + j;
;       const size_t o = (size_t)row * DM + c0;
;       const bf16x4 sn = *(const bf16x4*)(sgn + o);
;       if (which == 0) {
;         const bf16x4 sr = *(const bf16x4*)(sgr + o);
;         acc[ai][0][m][0][j] *= __fdividef(bf2f((u16)sr[0]), fmaxf(bf2f((u16)sn[0]), 1e-30f)); acc[ai][0][m][1][j] *= __fdividef(bf2f((u16)sr[1]), fmaxf(bf2f((u16)sn[1]), 1e-30f));
;         acc[ai][1][m][0][j] *= __fdividef(bf2f((u16)sr[2]), fmaxf(bf2f((u16)sn[2]), 1e-30f)); acc[ai][1][m][1][j] *= __fdividef(bf2f((u16)sr[3]), fmaxf(bf2f((u16)sn[3]), 1e-30f));
	v_max_f32_e32 v142, 0xda24260, v142
	v_max_f32_e32 v143, 0xda24260, v143
	v_rcp_f32_e32 v236, v236
	v_rcp_f32_e32 v237, v237
	v_rcp_f32_e32 v142, v142
	v_rcp_f32_e32 v143, v143
	v_lshlrev_b32_e32 v0, 16, v216
	v_and_b32_e32 v2, 0xffff0000, v216
	v_lshlrev_b32_e32 v3, 16, v217
	v_and_b32_e32 v133, 0xffff0000, v217
	v_mul_f32_e32 v0, v0, v236
	v_mul_f32_e32 v2, v2, v237
	v_mul_f32_e32 v3, v3, v142
	v_mul_f32_e32 v133, v133, v143
	v_mul_f32_e32 v43, v43, v0
	v_mul_f32_e32 v39, v39, v2
	v_mul_f32_e32 v11, v11, v3
	v_mul_f32_e32 v7, v7, v133
	v_lshlrev_b32_e32 v238, 16, v186
	v_and_b32_e32 v239, 0xffff0000, v186
	v_lshlrev_b32_e32 v240, 16, v187
	v_and_b32_e32 v241, 0xffff0000, v187
	v_max_f32_e32 v238, 0xda24260, v238
	v_max_f32_e32 v239, 0xda24260, v239
	v_max_f32_e32 v240, 0xda24260, v240
	v_max_f32_e32 v241, 0xda24260, v241
	v_rcp_f32_e32 v238, v238
	v_rcp_f32_e32 v239, v239
	v_rcp_f32_e32 v240, v240
	v_rcp_f32_e32 v241, v241
	v_lshlrev_b32_e32 v0, 16, v218
	v_and_b32_e32 v2, 0xffff0000, v218
	v_lshlrev_b32_e32 v3, 16, v219
	v_and_b32_e32 v133, 0xffff0000, v219
	v_mul_f32_e32 v0, v0, v238
	v_mul_f32_e32 v2, v2, v239
	v_mul_f32_e32 v3, v3, v240
	v_mul_f32_e32 v133, v133, v241
	v_mul_f32_e32 v48, v48, v0
	v_mul_f32_e32 v44, v44, v2
	v_mul_f32_e32 v16, v16, v3
	v_mul_f32_e32 v12, v12, v133
	v_lshlrev_b32_e32 v236, 16, v188
	v_and_b32_e32 v237, 0xffff0000, v188
	v_lshlrev_b32_e32 v142, 16, v189
	v_and_b32_e32 v143, 0xffff0000, v189
	v_max_f32_e32 v236, 0xda24260, v236
	v_max_f32_e32 v237, 0xda24260, v237
	v_max_f32_e32 v142, 0xda24260, v142
	v_max_f32_e32 v143, 0xda24260, v143
	v_rcp_f32_e32 v236, v236
	v_rcp_f32_e32 v237, v237
	v_rcp_f32_e32 v142, v142
	v_rcp_f32_e32 v143, v143
	v_lshlrev_b32_e32 v0, 16, v220
	v_and_b32_e32 v2, 0xffff0000, v220
	v_lshlrev_b32_e32 v3, 16, v221
	v_and_b32_e32 v133, 0xffff0000, v221
	v_mul_f32_e32 v0, v0, v236
	v_mul_f32_e32 v2, v2, v237
	v_mul_f32_e32 v3, v3, v142
	v_mul_f32_e32 v133, v133, v143
	v_mul_f32_e32 v49, v49, v0
	v_mul_f32_e32 v45, v45, v2
	v_mul_f32_e32 v17, v17, v3
	v_mul_f32_e32 v13, v13, v133
	v_lshlrev_b32_e32 v238, 16, v190
	v_and_b32_e32 v239, 0xffff0000, v190
	v_lshlrev_b32_e32 v240, 16, v191
	v_and_b32_e32 v241, 0xffff0000, v191
	v_max_f32_e32 v238, 0xda24260, v238
	v_max_f32_e32 v239, 0xda24260, v239
	v_max_f32_e32 v240, 0xda24260, v240
	v_max_f32_e32 v241, 0xda24260, v241
	v_rcp_f32_e32 v238, v238
	v_rcp_f32_e32 v239, v239
	v_rcp_f32_e32 v240, v240
	v_rcp_f32_e32 v241, v241
	v_lshlrev_b32_e32 v0, 16, v222
	v_and_b32_e32 v2, 0xffff0000, v222
	v_lshlrev_b32_e32 v3, 16, v223
	v_and_b32_e32 v133, 0xffff0000, v223
	v_mul_f32_e32 v0, v0, v238
	v_mul_f32_e32 v2, v2, v239
	v_mul_f32_e32 v3, v3, v240
	v_mul_f32_e32 v133, v133, v241
	v_mul_f32_e32 v50, v50, v0
	v_mul_f32_e32 v46, v46, v2
	v_mul_f32_e32 v18, v18, v3
	v_mul_f32_e32 v14, v14, v133
	v_lshlrev_b32_e32 v236, 16, v192
	v_and_b32_e32 v237, 0xffff0000, v192
	v_lshlrev_b32_e32 v142, 16, v193
	v_and_b32_e32 v143, 0xffff0000, v193
	v_max_f32_e32 v236, 0xda24260, v236
	v_max_f32_e32 v237, 0xda24260, v237
	v_max_f32_e32 v142, 0xda24260, v142
	v_max_f32_e32 v143, 0xda24260, v143
	v_rcp_f32_e32 v236, v236
	v_rcp_f32_e32 v237, v237
	v_rcp_f32_e32 v142, v142
	v_rcp_f32_e32 v143, v143
	v_lshlrev_b32_e32 v0, 16, v224
	v_and_b32_e32 v2, 0xffff0000, v224
	v_lshlrev_b32_e32 v3, 16, v225
	v_and_b32_e32 v133, 0xffff0000, v225
	v_mul_f32_e32 v0, v0, v236
	v_mul_f32_e32 v2, v2, v237
	v_mul_f32_e32 v3, v3, v142
	v_mul_f32_e32 v133, v133, v143
	v_mul_f32_e32 v51, v51, v0
	v_mul_f32_e32 v47, v47, v2
	v_mul_f32_e32 v19, v19, v3
	v_mul_f32_e32 v15, v15, v133
	s_waitcnt vmcnt(0)
; DEVINL float bf2f(u16 h) { return __uint_as_float(((unsigned)h) << 16); }
;   DEVINL void operator()(Acc& acc, int brow, int bcol) const {
;     ...
;     _Pragma("unroll") for (int ai = 0; ai < 2; ++ai) _Pragma("unroll") for (int m = 0; m < 4; ++m) _Pragma("unroll") for (int j = 0; j < 4; ++j) {
;       const int row = brow + ai * 128 + wr * 64 + m * 16 + fq * 4 + j;
;       const size_t o = (size_t)row * DM + c0;
;       const bf16x4 sn = *(const bf16x4*)(sgn + o);
;       if (which == 0) {
;         const bf16x4 sr = *(const bf16x4*)(sgr + o);
;         acc[ai][0][m][0][j] *= __fdividef(bf2f((u16)sr[0]), fmaxf(bf2f((u16)sn[0]), 1e-30f)); acc[ai][0][m][1][j] *= __fdividef(bf2f((u16)sr[1]), fmaxf(bf2f((u16)sn[1]), 1e-30f));
;         acc[ai][1][m][0][j] *= __fdividef(bf2f((u16)sr[2]), fmaxf(bf2f((u16)sn[2]), 1e-30f)); acc[ai][1][m][1][j] *= __fdividef(bf2f((u16)sr[3]), fmaxf(bf2f((u16)sn[3]), 1e-30f));
	v_lshlrev_b32_e32 v238, 16, v194
	v_and_b32_e32 v239, 0xffff0000, v194
	v_lshlrev_b32_e32 v240, 16, v195
	v_and_b32_e32 v241, 0xffff0000, v195
	v_max_f32_e32 v238, 0xda24260, v238
	v_max_f32_e32 v239, 0xda24260, v239
	v_max_f32_e32 v240, 0xda24260, v240
	v_max_f32_e32 v241, 0xda24260, v241
	v_rcp_f32_e32 v238, v238
	v_rcp_f32_e32 v239, v239
	v_rcp_f32_e32 v240, v240
	v_rcp_f32_e32 v241, v241
	v_lshlrev_b32_e32 v0, 16, v226
	v_and_b32_e32 v2, 0xffff0000, v226
	v_lshlrev_b32_e32 v3, 16, v227
	v_and_b32_e32 v133, 0xffff0000, v227
	v_mul_f32_e32 v0, v0, v238
	v_mul_f32_e32 v2, v2, v239
	v_mul_f32_e32 v3, v3, v240
	v_mul_f32_e32 v133, v133, v241
	v_mul_f32_e32 v56, v56, v0
	v_mul_f32_e32 v52, v52, v2
	v_mul_f32_e32 v24, v24, v3
	v_mul_f32_e32 v20, v20, v133
	v_lshlrev_b32_e32 v236, 16, v196
	v_and_b32_e32 v237, 0xffff0000, v196
	v_lshlrev_b32_e32 v142, 16, v197
	v_and_b32_e32 v143, 0xffff0000, v197
	v_max_f32_e32 v236, 0xda24260, v236
	v_max_f32_e32 v237, 0xda24260, v237
	v_max_f32_e32 v142, 0xda24260, v142
	v_max_f32_e32 v143, 0xda24260, v143
	v_rcp_f32_e32 v236, v236
	v_rcp_f32_e32 v237, v237
	v_rcp_f32_e32 v142, v142
	v_rcp_f32_e32 v143, v143
	v_lshlrev_b32_e32 v0, 16, v228
	v_and_b32_e32 v2, 0xffff0000, v228
	v_lshlrev_b32_e32 v3, 16, v229
	v_and_b32_e32 v133, 0xffff0000, v229
	v_mul_f32_e32 v0, v0, v236
	v_mul_f32_e32 v2, v2, v237
	v_mul_f32_e32 v3, v3, v142
	v_mul_f32_e32 v133, v133, v143
	v_mul_f32_e32 v57, v57, v0
	v_mul_f32_e32 v53, v53, v2
	v_mul_f32_e32 v25, v25, v3
	v_mul_f32_e32 v21, v21, v133
	v_lshlrev_b32_e32 v238, 16, v198
	v_and_b32_e32 v239, 0xffff0000, v198
	v_lshlrev_b32_e32 v240, 16, v199
	v_and_b32_e32 v241, 0xffff0000, v199
	v_max_f32_e32 v238, 0xda24260, v238
	v_max_f32_e32 v239, 0xda24260, v239
	v_max_f32_e32 v240, 0xda24260, v240
	v_max_f32_e32 v241, 0xda24260, v241
	v_rcp_f32_e32 v238, v238
	v_rcp_f32_e32 v239, v239
	v_rcp_f32_e32 v240, v240
	v_rcp_f32_e32 v241, v241
	v_lshlrev_b32_e32 v0, 16, v230
	v_and_b32_e32 v2, 0xffff0000, v230
	v_lshlrev_b32_e32 v3, 16, v231
	v_and_b32_e32 v133, 0xffff0000, v231
	v_mul_f32_e32 v0, v0, v238
	v_mul_f32_e32 v2, v2, v239
	v_mul_f32_e32 v3, v3, v240
	v_mul_f32_e32 v133, v133, v241
	v_mul_f32_e32 v58, v58, v0
	v_mul_f32_e32 v54, v54, v2
	v_mul_f32_e32 v26, v26, v3
	v_mul_f32_e32 v22, v22, v133
	v_lshlrev_b32_e32 v236, 16, v200
	v_and_b32_e32 v237, 0xffff0000, v200
	v_lshlrev_b32_e32 v142, 16, v201
	v_and_b32_e32 v143, 0xffff0000, v201
	v_max_f32_e32 v236, 0xda24260, v236
	v_max_f32_e32 v237, 0xda24260, v237
	v_max_f32_e32 v142, 0xda24260, v142
	v_max_f32_e32 v143, 0xda24260, v143
	v_rcp_f32_e32 v236, v236
	v_rcp_f32_e32 v237, v237
	v_rcp_f32_e32 v142, v142
	v_rcp_f32_e32 v143, v143
	v_lshlrev_b32_e32 v0, 16, v232
	v_and_b32_e32 v2, 0xffff0000, v232
	v_lshlrev_b32_e32 v3, 16, v233
	v_and_b32_e32 v133, 0xffff0000, v233
	v_mul_f32_e32 v0, v0, v236
	v_mul_f32_e32 v2, v2, v237
	v_mul_f32_e32 v3, v3, v142
	v_mul_f32_e32 v133, v133, v143
	v_mul_f32_e32 v59, v59, v0
	v_mul_f32_e32 v55, v55, v2
	v_mul_f32_e32 v27, v27, v3
	v_mul_f32_e32 v23, v23, v133
	v_lshlrev_b32_e32 v238, 16, v202
	v_and_b32_e32 v239, 0xffff0000, v202
	v_lshlrev_b32_e32 v240, 16, v203
	v_and_b32_e32 v241, 0xffff0000, v203
	v_max_f32_e32 v238, 0xda24260, v238
	v_max_f32_e32 v239, 0xda24260, v239
	v_max_f32_e32 v240, 0xda24260, v240
	v_max_f32_e32 v241, 0xda24260, v241
	v_rcp_f32_e32 v238, v238
	v_rcp_f32_e32 v239, v239
	v_rcp_f32_e32 v240, v240
	v_rcp_f32_e32 v241, v241
	v_lshlrev_b32_e32 v0, 16, v134
	v_and_b32_e32 v2, 0xffff0000, v134
	v_lshlrev_b32_e32 v3, 16, v135
	v_and_b32_e32 v133, 0xffff0000, v135
	v_mul_f32_e32 v0, v0, v238
	v_mul_f32_e32 v2, v2, v239
	v_mul_f32_e32 v3, v3, v240
	v_mul_f32_e32 v133, v133, v241
	v_mul_f32_e32 v64, v64, v0
	v_mul_f32_e32 v60, v60, v2
	v_mul_f32_e32 v32, v32, v3
	v_mul_f32_e32 v28, v28, v133
	v_lshlrev_b32_e32 v236, 16, v204
	v_and_b32_e32 v237, 0xffff0000, v204
	v_lshlrev_b32_e32 v142, 16, v205
	v_and_b32_e32 v143, 0xffff0000, v205
	v_max_f32_e32 v236, 0xda24260, v236
	v_max_f32_e32 v237, 0xda24260, v237
	v_max_f32_e32 v142, 0xda24260, v142
	v_max_f32_e32 v143, 0xda24260, v143
	v_rcp_f32_e32 v236, v236
	v_rcp_f32_e32 v237, v237
	v_rcp_f32_e32 v142, v142
	v_rcp_f32_e32 v143, v143
	v_lshlrev_b32_e32 v0, 16, v136
	v_and_b32_e32 v2, 0xffff0000, v136
	v_lshlrev_b32_e32 v3, 16, v137
	v_and_b32_e32 v133, 0xffff0000, v137
	v_mul_f32_e32 v0, v0, v236
	v_mul_f32_e32 v2, v2, v237
	v_mul_f32_e32 v3, v3, v142
	v_mul_f32_e32 v133, v133, v143
	v_mul_f32_e32 v65, v65, v0
	v_mul_f32_e32 v61, v61, v2
	v_mul_f32_e32 v33, v33, v3
	v_mul_f32_e32 v29, v29, v133
	v_lshlrev_b32_e32 v238, 16, v206
	v_and_b32_e32 v239, 0xffff0000, v206
	v_lshlrev_b32_e32 v240, 16, v207
	v_and_b32_e32 v241, 0xffff0000, v207
	v_max_f32_e32 v238, 0xda24260, v238
	v_max_f32_e32 v239, 0xda24260, v239
	v_max_f32_e32 v240, 0xda24260, v240
	v_max_f32_e32 v241, 0xda24260, v241
	v_rcp_f32_e32 v238, v238
	v_rcp_f32_e32 v239, v239
	v_rcp_f32_e32 v240, v240
	v_rcp_f32_e32 v241, v241
	v_lshlrev_b32_e32 v0, 16, v138
	v_and_b32_e32 v2, 0xffff0000, v138
	v_lshlrev_b32_e32 v3, 16, v139
	v_and_b32_e32 v133, 0xffff0000, v139
	v_mul_f32_e32 v0, v0, v238
	v_mul_f32_e32 v2, v2, v239
	v_mul_f32_e32 v3, v3, v240
	v_mul_f32_e32 v133, v133, v241
	v_mul_f32_e32 v66, v66, v0
	v_mul_f32_e32 v62, v62, v2
	v_mul_f32_e32 v34, v34, v3
	v_mul_f32_e32 v30, v30, v133
	v_lshlrev_b32_e32 v236, 16, v208
	v_and_b32_e32 v237, 0xffff0000, v208
	v_lshlrev_b32_e32 v142, 16, v209
	v_and_b32_e32 v143, 0xffff0000, v209
	v_max_f32_e32 v236, 0xda24260, v236
	v_max_f32_e32 v237, 0xda24260, v237
	v_max_f32_e32 v142, 0xda24260, v142
	v_max_f32_e32 v143, 0xda24260, v143
	v_rcp_f32_e32 v236, v236
	v_rcp_f32_e32 v237, v237
	v_rcp_f32_e32 v142, v142
	v_rcp_f32_e32 v143, v143
	v_lshlrev_b32_e32 v0, 16, v140
	v_and_b32_e32 v2, 0xffff0000, v140
	v_lshlrev_b32_e32 v3, 16, v141
	v_and_b32_e32 v133, 0xffff0000, v141
	v_mul_f32_e32 v0, v0, v236
	v_mul_f32_e32 v2, v2, v237
	v_mul_f32_e32 v3, v3, v142
	v_mul_f32_e32 v133, v133, v143
	v_mul_f32_e32 v67, v67, v0
	v_mul_f32_e32 v63, v63, v2
	v_mul_f32_e32 v35, v35, v3
	v_mul_f32_e32 v31, v31, v133
	s_waitcnt lgkmcnt(0)
	s_branch .LBB0_127

; DEVINL float sigmoidf_(float x) { return __fdividef(1.f, 1.f + __expf(-x)); }
; DEVINL float siluf_(float x) { return __fdividef(x, 1.f + __expf(-x)); }
;   DEVINL void operator()(Acc& acc, int brow, int bcol) const {
;     ...
;       u16* dst; int ld, cbase, fn;
;       if (tt < 12)      { dst = P.sg;  ld = 1024; cbase = (tt - 8) * 256;  fn = 1; }
;       else if (tt < 14) { dst = P.qn;  ld = 512;  cbase = (tt - 12) * 256; fn = 3; }
;       else if (tt < 16) { dst = P.kn;  ld = 512;  cbase = (tt - 14) * 256; fn = 0; }
;       else if (tt < 22) { dst = P.sgr; ld = 1024; cbase = (tt - 18) * 256; fn = 2; }
;       else              { dst = P.sgn; ld = 1024; cbase = (tt - 22) * 256; fn = 2; }
;       const int c0 = cbase + wc * 64 + fr * 4;
;       _Pragma("unroll") for (int ai = 0; ai < 2; ++ai) _Pragma("unroll") for (int m = 0; m < 4; ++m) _Pragma("unroll") for (int j = 0; j < 4; ++j) {
;         const int row = brow + ai * 128 + wr * 64 + m * 16 + fq * 4 + j;
;         float v[4] = {acc[ai][0][m][0][j], acc[ai][0][m][1][j], acc[ai][1][m][0][j], acc[ai][1][m][1][j]};
;         _Pragma("unroll") for (int k = 0; k < 4; ++k) v[k] = fn == 1 ? siluf_(v[k]) : (fn == 2 ? sigmoidf_(v[k]) : (fn == 3 ? v[k] * 0.125f : v[k]));
;         *(bf16x4*)(dst + (size_t)row * ld + c0) = pack4(v[0], v[1], v[2], v[3]);
.LBB0_462:
	s_and_b64 vcc, exec, s[10:11]
	s_cbranch_vccnz .Lgw_sig
	s_and_b64 vcc, exec, s[8:9]
	s_cbranch_vccz .Lgw_silu
	s_and_b64 vcc, exec, s[20:21]
	s_cbranch_vccnz .Lgw_scl
	s_add_u32 s24, s88, s24
	s_addc_u32 s25, s89, s25
	v_mul_f32_e32 v0, 0x3e000000, v118
	v_cndmask_b32_e64 v148, v118, v0, s[20:21]
	v_mul_f32_e32 v0, 0x3e000000, v114
	v_cndmask_b32_e64 v152, v114, v0, s[20:21]
	s_load_dwordx2 s[24:25], s[24:25], 0x0
	v_mul_f32_e32 v0, 0x3e000000, v126
	v_cndmask_b32_e64 v153, v126, v0, s[20:21]
	v_mul_f32_e32 v0, 0x3e000000, v122
	v_cndmask_b32_e64 v154, v122, v0, s[20:21]
	s_add_i32 s13, s13, s22
	v_lshlrev_b32_e32 v0, 6, v149
	v_lshlrev_b32_e32 v142, 2, v146
	v_or3_b32 v142, v0, v142, s13
	v_lshl_add_u32 v0, v144, 6, s12
	v_lshl_or_b32 v0, v145, 2, v0
	v_ashrrev_i32_e32 v143, 31, v142
	s_waitcnt lgkmcnt(0)
	v_lshl_add_u64 v[142:143], v[142:143], 1, s[24:25]
	v_cvt_pk_bf16_f32 v153, v153, v154
	v_mad_i64_i32 v[154:155], s[22:23], s14, v0, 0
	v_cvt_pk_bf16_f32 v152, v148, v152
	v_lshl_add_u64 v[154:155], v[154:155], 1, v[142:143]
	global_store_dwordx2 v[154:155], v[152:153], off
	v_mul_f32_e32 v148, 0x3e000000, v119
	v_cndmask_b32_e64 v148, v119, v148, s[20:21]
	v_mul_f32_e32 v152, 0x3e000000, v115
	v_cndmask_b32_e64 v152, v115, v152, s[20:21]
	v_mul_f32_e32 v153, 0x3e000000, v127
	v_cndmask_b32_e64 v153, v127, v153, s[20:21]
	v_mul_f32_e32 v154, 0x3e000000, v123
	v_cndmask_b32_e64 v154, v123, v154, s[20:21]
	v_or_b32_e32 v155, 1, v0
	v_cvt_pk_bf16_f32 v153, v153, v154
	v_mad_i64_i32 v[154:155], s[22:23], s14, v155, 0
	v_cvt_pk_bf16_f32 v152, v148, v152
	v_lshl_add_u64 v[154:155], v[154:155], 1, v[142:143]
	global_store_dwordx2 v[154:155], v[152:153], off
	v_mul_f32_e32 v148, 0x3e000000, v120
	v_cndmask_b32_e64 v148, v120, v148, s[20:21]
	v_mul_f32_e32 v152, 0x3e000000, v116
	v_cndmask_b32_e64 v152, v116, v152, s[20:21]
	v_mul_f32_e32 v153, 0x3e000000, v128
	v_cndmask_b32_e64 v153, v128, v153, s[20:21]
	v_mul_f32_e32 v154, 0x3e000000, v124
	v_cndmask_b32_e64 v154, v124, v154, s[20:21]
	v_or_b32_e32 v155, 2, v0
	v_cvt_pk_bf16_f32 v153, v153, v154
	v_mad_i64_i32 v[154:155], s[22:23], s14, v155, 0
	v_cvt_pk_bf16_f32 v152, v148, v152
	v_lshl_add_u64 v[154:155], v[154:155], 1, v[142:143]
	global_store_dwordx2 v[154:155], v[152:153], off
	v_mul_f32_e32 v148, 0x3e000000, v121
	v_cndmask_b32_e64 v148, v121, v148, s[20:21]
	v_mul_f32_e32 v152, 0x3e000000, v117
	v_cndmask_b32_e64 v152, v117, v152, s[20:21]
	v_mul_f32_e32 v153, 0x3e000000, v129
	v_cndmask_b32_e64 v153, v129, v153, s[20:21]
	v_mul_f32_e32 v154, 0x3e000000, v125
	v_cndmask_b32_e64 v154, v125, v154, s[20:21]
	v_or_b32_e32 v155, 3, v0
	v_cvt_pk_bf16_f32 v153, v153, v154
	v_mad_i64_i32 v[154:155], s[22:23], s14, v155, 0
	v_cvt_pk_bf16_f32 v152, v148, v152
	v_lshl_add_u64 v[154:155], v[154:155], 1, v[142:143]
	global_store_dwordx2 v[154:155], v[152:153], off
	v_mul_f32_e32 v148, 0x3e000000, v102
	v_cndmask_b32_e64 v148, v102, v148, s[20:21]
	v_mul_f32_e32 v152, 0x3e000000, v98
	v_cndmask_b32_e64 v152, v98, v152, s[20:21]
	v_mul_f32_e32 v153, 0x3e000000, v110
	v_cndmask_b32_e64 v153, v110, v153, s[20:21]
	v_mul_f32_e32 v154, 0x3e000000, v106
	v_cndmask_b32_e64 v154, v106, v154, s[20:21]
	v_or_b32_e32 v155, 16, v0
	v_cvt_pk_bf16_f32 v153, v153, v154
	v_mad_i64_i32 v[154:155], s[22:23], s14, v155, 0
	v_cvt_pk_bf16_f32 v152, v148, v152
	v_lshl_add_u64 v[154:155], v[154:155], 1, v[142:143]
	global_store_dwordx2 v[154:155], v[152:153], off
	v_mul_f32_e32 v148, 0x3e000000, v103
	v_cndmask_b32_e64 v148, v103, v148, s[20:21]
	v_mul_f32_e32 v152, 0x3e000000, v99
	v_cndmask_b32_e64 v152, v99, v152, s[20:21]
	v_mul_f32_e32 v153, 0x3e000000, v111
	v_cndmask_b32_e64 v153, v111, v153, s[20:21]
	v_mul_f32_e32 v154, 0x3e000000, v107
	v_cndmask_b32_e64 v154, v107, v154, s[20:21]
	v_or_b32_e32 v155, 17, v0
	v_cvt_pk_bf16_f32 v153, v153, v154
	v_mad_i64_i32 v[154:155], s[22:23], s14, v155, 0
	v_cvt_pk_bf16_f32 v152, v148, v152
	v_lshl_add_u64 v[154:155], v[154:155], 1, v[142:143]
	global_store_dwordx2 v[154:155], v[152:153], off
	v_mul_f32_e32 v148, 0x3e000000, v104
	v_cndmask_b32_e64 v148, v104, v148, s[20:21]
	v_mul_f32_e32 v152, 0x3e000000, v100
	v_cndmask_b32_e64 v152, v100, v152, s[20:21]
	v_mul_f32_e32 v153, 0x3e000000, v112
	v_cndmask_b32_e64 v153, v112, v153, s[20:21]
	v_mul_f32_e32 v154, 0x3e000000, v108
	v_cndmask_b32_e64 v154, v108, v154, s[20:21]
	v_or_b32_e32 v155, 18, v0
	v_cvt_pk_bf16_f32 v153, v153, v154
	v_mad_i64_i32 v[154:155], s[22:23], s14, v155, 0
	v_cvt_pk_bf16_f32 v152, v148, v152
	v_lshl_add_u64 v[154:155], v[154:155], 1, v[142:143]
	global_store_dwordx2 v[154:155], v[152:153], off
	v_mul_f32_e32 v148, 0x3e000000, v105
	v_cndmask_b32_e64 v148, v105, v148, s[20:21]
	v_mul_f32_e32 v152, 0x3e000000, v101
	v_cndmask_b32_e64 v152, v101, v152, s[20:21]
	v_mul_f32_e32 v153, 0x3e000000, v113
	v_cndmask_b32_e64 v153, v113, v153, s[20:21]
	v_mul_f32_e32 v154, 0x3e000000, v109
	v_cndmask_b32_e64 v154, v109, v154, s[20:21]
	v_or_b32_e32 v155, 19, v0
	v_cvt_pk_bf16_f32 v153, v153, v154
	v_mad_i64_i32 v[154:155], s[22:23], s14, v155, 0
	v_cvt_pk_bf16_f32 v152, v148, v152
	v_lshl_add_u64 v[154:155], v[154:155], 1, v[142:143]
	global_store_dwordx2 v[154:155], v[152:153], off
	v_mul_f32_e32 v148, 0x3e000000, v86
	v_cndmask_b32_e64 v148, v86, v148, s[20:21]
	v_mul_f32_e32 v152, 0x3e000000, v82
	v_cndmask_b32_e64 v152, v82, v152, s[20:21]
	v_mul_f32_e32 v153, 0x3e000000, v94
	v_cndmask_b32_e64 v153, v94, v153, s[20:21]
	v_mul_f32_e32 v154, 0x3e000000, v90
	v_cndmask_b32_e64 v154, v90, v154, s[20:21]
	v_or_b32_e32 v155, 32, v0
	v_cvt_pk_bf16_f32 v153, v153, v154
	v_mad_i64_i32 v[154:155], s[22:23], s14, v155, 0
; DEVINL float sigmoidf_(float x) { return __fdividef(1.f, 1.f + __expf(-x)); }
; DEVINL float siluf_(float x) { return __fdividef(x, 1.f + __expf(-x)); }
;   DEVINL void operator()(Acc& acc, int brow, int bcol) const {
;     ...
;       _Pragma("unroll") for (int ai = 0; ai < 2; ++ai) _Pragma("unroll") for (int m = 0; m < 4; ++m) _Pragma("unroll") for (int j = 0; j < 4; ++j) {
;         const int row = brow + ai * 128 + wr * 64 + m * 16 + fq * 4 + j;
;         float v[4] = {acc[ai][0][m][0][j], acc[ai][0][m][1][j], acc[ai][1][m][0][j], acc[ai][1][m][1][j]};
;         _Pragma("unroll") for (int k = 0; k < 4; ++k) v[k] = fn == 1 ? siluf_(v[k]) : (fn == 2 ? sigmoidf_(v[k]) : (fn == 3 ? v[k] * 0.125f : v[k]));
;         *(bf16x4*)(dst + (size_t)row * ld + c0) = pack4(v[0], v[1], v[2], v[3]);
	v_cvt_pk_bf16_f32 v152, v148, v152
	v_lshl_add_u64 v[154:155], v[154:155], 1, v[142:143]
	global_store_dwordx2 v[154:155], v[152:153], off
	v_mul_f32_e32 v148, 0x3e000000, v87
	v_cndmask_b32_e64 v148, v87, v148, s[20:21]
	v_mul_f32_e32 v152, 0x3e000000, v83
	v_cndmask_b32_e64 v152, v83, v152, s[20:21]
	v_mul_f32_e32 v153, 0x3e000000, v95
	v_cndmask_b32_e64 v153, v95, v153, s[20:21]
	v_mul_f32_e32 v154, 0x3e000000, v91
	v_cndmask_b32_e64 v154, v91, v154, s[20:21]
	v_or_b32_e32 v155, 33, v0
	v_cvt_pk_bf16_f32 v153, v153, v154
	v_mad_i64_i32 v[154:155], s[22:23], s14, v155, 0
	v_cvt_pk_bf16_f32 v152, v148, v152
	v_lshl_add_u64 v[154:155], v[154:155], 1, v[142:143]
	global_store_dwordx2 v[154:155], v[152:153], off
	v_mul_f32_e32 v148, 0x3e000000, v88
	v_cndmask_b32_e64 v148, v88, v148, s[20:21]
	v_mul_f32_e32 v152, 0x3e000000, v84
	v_cndmask_b32_e64 v152, v84, v152, s[20:21]
	v_mul_f32_e32 v153, 0x3e000000, v96
	v_cndmask_b32_e64 v153, v96, v153, s[20:21]
	v_mul_f32_e32 v154, 0x3e000000, v92
	v_cndmask_b32_e64 v154, v92, v154, s[20:21]
	v_or_b32_e32 v155, 34, v0
	v_cvt_pk_bf16_f32 v153, v153, v154
	v_mad_i64_i32 v[154:155], s[22:23], s14, v155, 0
	v_cvt_pk_bf16_f32 v152, v148, v152
	v_lshl_add_u64 v[154:155], v[154:155], 1, v[142:143]
	global_store_dwordx2 v[154:155], v[152:153], off
	v_mul_f32_e32 v148, 0x3e000000, v89
	v_cndmask_b32_e64 v148, v89, v148, s[20:21]
	v_mul_f32_e32 v152, 0x3e000000, v85
	v_cndmask_b32_e64 v152, v85, v152, s[20:21]
	v_mul_f32_e32 v153, 0x3e000000, v97
	v_cndmask_b32_e64 v153, v97, v153, s[20:21]
	v_mul_f32_e32 v154, 0x3e000000, v93
	v_cndmask_b32_e64 v154, v93, v154, s[20:21]
	v_or_b32_e32 v155, 35, v0
	v_cvt_pk_bf16_f32 v153, v153, v154
	v_mad_i64_i32 v[154:155], s[22:23], s14, v155, 0
	v_cvt_pk_bf16_f32 v152, v148, v152
	v_lshl_add_u64 v[154:155], v[154:155], 1, v[142:143]
	global_store_dwordx2 v[154:155], v[152:153], off
	v_mul_f32_e32 v148, 0x3e000000, v70
	v_cndmask_b32_e64 v148, v70, v148, s[20:21]
	v_mul_f32_e32 v152, 0x3e000000, v66
	v_cndmask_b32_e64 v152, v66, v152, s[20:21]
	v_mul_f32_e32 v153, 0x3e000000, v78
	v_cndmask_b32_e64 v153, v78, v153, s[20:21]
	v_mul_f32_e32 v154, 0x3e000000, v74
	v_cndmask_b32_e64 v154, v74, v154, s[20:21]
	v_or_b32_e32 v155, 48, v0
	v_cvt_pk_bf16_f32 v153, v153, v154
	v_mad_i64_i32 v[154:155], s[22:23], s14, v155, 0
	v_cvt_pk_bf16_f32 v152, v148, v152
	v_lshl_add_u64 v[154:155], v[154:155], 1, v[142:143]
	global_store_dwordx2 v[154:155], v[152:153], off
	v_mul_f32_e32 v148, 0x3e000000, v71
	v_cndmask_b32_e64 v148, v71, v148, s[20:21]
	v_mul_f32_e32 v152, 0x3e000000, v67
	v_cndmask_b32_e64 v152, v67, v152, s[20:21]
	v_mul_f32_e32 v153, 0x3e000000, v79
	v_cndmask_b32_e64 v153, v79, v153, s[20:21]
	v_mul_f32_e32 v154, 0x3e000000, v75
	v_cndmask_b32_e64 v154, v75, v154, s[20:21]
	v_or_b32_e32 v155, 49, v0
	v_cvt_pk_bf16_f32 v153, v153, v154
	v_mad_i64_i32 v[154:155], s[22:23], s14, v155, 0
	v_cvt_pk_bf16_f32 v152, v148, v152
	v_lshl_add_u64 v[154:155], v[154:155], 1, v[142:143]
	global_store_dwordx2 v[154:155], v[152:153], off
	v_mul_f32_e32 v148, 0x3e000000, v72
	v_cndmask_b32_e64 v148, v72, v148, s[20:21]
	v_mul_f32_e32 v152, 0x3e000000, v68
	v_cndmask_b32_e64 v152, v68, v152, s[20:21]
	v_mul_f32_e32 v153, 0x3e000000, v80
	v_cndmask_b32_e64 v153, v80, v153, s[20:21]
	v_mul_f32_e32 v154, 0x3e000000, v76
	v_cndmask_b32_e64 v154, v76, v154, s[20:21]
	v_or_b32_e32 v155, 50, v0
	v_cvt_pk_bf16_f32 v153, v153, v154
	v_mad_i64_i32 v[154:155], s[22:23], s14, v155, 0
	v_cvt_pk_bf16_f32 v152, v148, v152
	v_lshl_add_u64 v[154:155], v[154:155], 1, v[142:143]
	global_store_dwordx2 v[154:155], v[152:153], off
	v_mul_f32_e32 v148, 0x3e000000, v73
	v_cndmask_b32_e64 v148, v73, v148, s[20:21]
	v_mul_f32_e32 v152, 0x3e000000, v69
	v_cndmask_b32_e64 v152, v69, v152, s[20:21]
	v_mul_f32_e32 v153, 0x3e000000, v81
	v_cndmask_b32_e64 v153, v81, v153, s[20:21]
	v_mul_f32_e32 v154, 0x3e000000, v77
	v_cndmask_b32_e64 v154, v77, v154, s[20:21]
	v_or_b32_e32 v155, 51, v0
	v_cvt_pk_bf16_f32 v153, v153, v154
	v_mad_i64_i32 v[154:155], s[22:23], s14, v155, 0
	v_cvt_pk_bf16_f32 v152, v148, v152
	v_lshl_add_u64 v[154:155], v[154:155], 1, v[142:143]
	global_store_dwordx2 v[154:155], v[152:153], off
	v_mul_f32_e32 v148, 0x3e000000, v54
	v_cndmask_b32_e64 v148, v54, v148, s[20:21]
	v_mul_f32_e32 v152, 0x3e000000, v50
	v_cndmask_b32_e64 v152, v50, v152, s[20:21]
	v_mul_f32_e32 v153, 0x3e000000, v62
	v_cndmask_b32_e64 v153, v62, v153, s[20:21]
	v_mul_f32_e32 v154, 0x3e000000, v58
	v_cndmask_b32_e64 v154, v58, v154, s[20:21]
	v_add_u32_e32 v155, 0x80, v0
	v_cvt_pk_bf16_f32 v153, v153, v154
	v_mad_i64_i32 v[154:155], s[22:23], s14, v155, 0
	v_cvt_pk_bf16_f32 v152, v148, v152
	v_lshl_add_u64 v[154:155], v[154:155], 1, v[142:143]
	global_store_dwordx2 v[154:155], v[152:153], off
	v_mul_f32_e32 v148, 0x3e000000, v55
	v_cndmask_b32_e64 v148, v55, v148, s[20:21]
	v_mul_f32_e32 v152, 0x3e000000, v51
	v_cndmask_b32_e64 v152, v51, v152, s[20:21]
	v_mul_f32_e32 v153, 0x3e000000, v63
	v_cndmask_b32_e64 v153, v63, v153, s[20:21]
	v_mul_f32_e32 v154, 0x3e000000, v59
	v_cndmask_b32_e64 v154, v59, v154, s[20:21]
	v_add_u32_e32 v155, 0x81, v0
	v_cvt_pk_bf16_f32 v153, v153, v154
	v_mad_i64_i32 v[154:155], s[22:23], s14, v155, 0
	v_cvt_pk_bf16_f32 v152, v148, v152
	v_lshl_add_u64 v[154:155], v[154:155], 1, v[142:143]
	global_store_dwordx2 v[154:155], v[152:153], off
	v_mul_f32_e32 v148, 0x3e000000, v56
	v_cndmask_b32_e64 v148, v56, v148, s[20:21]
	v_mul_f32_e32 v152, 0x3e000000, v52
	v_cndmask_b32_e64 v152, v52, v152, s[20:21]
	v_mul_f32_e32 v153, 0x3e000000, v64
	v_cndmask_b32_e64 v153, v64, v153, s[20:21]
	v_mul_f32_e32 v154, 0x3e000000, v60
; DEVINL float sigmoidf_(float x) { return __fdividef(1.f, 1.f + __expf(-x)); }
; DEVINL float siluf_(float x) { return __fdividef(x, 1.f + __expf(-x)); }
;   DEVINL void operator()(Acc& acc, int brow, int bcol) const {
;     ...
;       _Pragma("unroll") for (int ai = 0; ai < 2; ++ai) _Pragma("unroll") for (int m = 0; m < 4; ++m) _Pragma("unroll") for (int j = 0; j < 4; ++j) {
;         const int row = brow + ai * 128 + wr * 64 + m * 16 + fq * 4 + j;
;         float v[4] = {acc[ai][0][m][0][j], acc[ai][0][m][1][j], acc[ai][1][m][0][j], acc[ai][1][m][1][j]};
;         _Pragma("unroll") for (int k = 0; k < 4; ++k) v[k] = fn == 1 ? siluf_(v[k]) : (fn == 2 ? sigmoidf_(v[k]) : (fn == 3 ? v[k] * 0.125f : v[k]));
;         *(bf16x4*)(dst + (size_t)row * ld + c0) = pack4(v[0], v[1], v[2], v[3]);
	v_cndmask_b32_e64 v154, v60, v154, s[20:21]
	v_add_u32_e32 v155, 0x82, v0
	v_cvt_pk_bf16_f32 v153, v153, v154
	v_mad_i64_i32 v[154:155], s[22:23], s14, v155, 0
	v_cvt_pk_bf16_f32 v152, v148, v152
	v_lshl_add_u64 v[154:155], v[154:155], 1, v[142:143]
	global_store_dwordx2 v[154:155], v[152:153], off
	v_mul_f32_e32 v148, 0x3e000000, v57
	v_cndmask_b32_e64 v148, v57, v148, s[20:21]
	v_mul_f32_e32 v152, 0x3e000000, v53
	v_cndmask_b32_e64 v152, v53, v152, s[20:21]
	v_mul_f32_e32 v153, 0x3e000000, v65
	v_cndmask_b32_e64 v153, v65, v153, s[20:21]
	v_mul_f32_e32 v154, 0x3e000000, v61
	v_cndmask_b32_e64 v154, v61, v154, s[20:21]
	v_add_u32_e32 v155, 0x83, v0
	v_cvt_pk_bf16_f32 v153, v153, v154
	v_mad_i64_i32 v[154:155], s[22:23], s14, v155, 0
	v_cvt_pk_bf16_f32 v152, v148, v152
	v_lshl_add_u64 v[154:155], v[154:155], 1, v[142:143]
	global_store_dwordx2 v[154:155], v[152:153], off
	v_mul_f32_e32 v148, 0x3e000000, v38
	v_cndmask_b32_e64 v148, v38, v148, s[20:21]
	v_mul_f32_e32 v152, 0x3e000000, v34
	v_cndmask_b32_e64 v152, v34, v152, s[20:21]
	v_mul_f32_e32 v153, 0x3e000000, v46
	v_cndmask_b32_e64 v153, v46, v153, s[20:21]
	v_mul_f32_e32 v154, 0x3e000000, v42
	v_cndmask_b32_e64 v154, v42, v154, s[20:21]
	v_add_u32_e32 v155, 0x90, v0
	v_cvt_pk_bf16_f32 v153, v153, v154
	v_mad_i64_i32 v[154:155], s[22:23], s14, v155, 0
	v_cvt_pk_bf16_f32 v152, v148, v152
	v_lshl_add_u64 v[154:155], v[154:155], 1, v[142:143]
	global_store_dwordx2 v[154:155], v[152:153], off
	v_mul_f32_e32 v148, 0x3e000000, v39
	v_cndmask_b32_e64 v148, v39, v148, s[20:21]
	v_mul_f32_e32 v152, 0x3e000000, v35
	v_cndmask_b32_e64 v152, v35, v152, s[20:21]
	v_mul_f32_e32 v153, 0x3e000000, v47
	v_cndmask_b32_e64 v153, v47, v153, s[20:21]
	v_mul_f32_e32 v154, 0x3e000000, v43
	v_cndmask_b32_e64 v154, v43, v154, s[20:21]
	v_add_u32_e32 v155, 0x91, v0
	v_cvt_pk_bf16_f32 v153, v153, v154
	v_mad_i64_i32 v[154:155], s[22:23], s14, v155, 0
	v_cvt_pk_bf16_f32 v152, v148, v152
	v_lshl_add_u64 v[154:155], v[154:155], 1, v[142:143]
	global_store_dwordx2 v[154:155], v[152:153], off
	v_mul_f32_e32 v148, 0x3e000000, v40
	v_cndmask_b32_e64 v148, v40, v148, s[20:21]
	v_mul_f32_e32 v152, 0x3e000000, v36
	v_cndmask_b32_e64 v152, v36, v152, s[20:21]
	v_mul_f32_e32 v153, 0x3e000000, v48
	v_cndmask_b32_e64 v153, v48, v153, s[20:21]
	v_mul_f32_e32 v154, 0x3e000000, v44
	v_cndmask_b32_e64 v154, v44, v154, s[20:21]
	v_add_u32_e32 v155, 0x92, v0
	v_cvt_pk_bf16_f32 v153, v153, v154
	v_mad_i64_i32 v[154:155], s[22:23], s14, v155, 0
	v_cvt_pk_bf16_f32 v152, v148, v152
	v_lshl_add_u64 v[154:155], v[154:155], 1, v[142:143]
	global_store_dwordx2 v[154:155], v[152:153], off
	v_mul_f32_e32 v148, 0x3e000000, v41
	v_cndmask_b32_e64 v148, v41, v148, s[20:21]
	v_mul_f32_e32 v152, 0x3e000000, v37
	v_cndmask_b32_e64 v152, v37, v152, s[20:21]
	v_mul_f32_e32 v153, 0x3e000000, v49
	v_cndmask_b32_e64 v153, v49, v153, s[20:21]
	v_mul_f32_e32 v154, 0x3e000000, v45
	v_cndmask_b32_e64 v154, v45, v154, s[20:21]
	v_add_u32_e32 v155, 0x93, v0
	v_cvt_pk_bf16_f32 v153, v153, v154
	v_mad_i64_i32 v[154:155], s[22:23], s14, v155, 0
	v_cvt_pk_bf16_f32 v152, v148, v152
	v_lshl_add_u64 v[154:155], v[154:155], 1, v[142:143]
	global_store_dwordx2 v[154:155], v[152:153], off
	v_mul_f32_e32 v148, 0x3e000000, v22
	v_cndmask_b32_e64 v148, v22, v148, s[20:21]
	v_mul_f32_e32 v152, 0x3e000000, v18
	v_cndmask_b32_e64 v152, v18, v152, s[20:21]
	v_mul_f32_e32 v153, 0x3e000000, v30
	v_cndmask_b32_e64 v153, v30, v153, s[20:21]
	v_mul_f32_e32 v154, 0x3e000000, v26
	v_cndmask_b32_e64 v154, v26, v154, s[20:21]
	v_add_u32_e32 v155, 0xa0, v0
	v_cvt_pk_bf16_f32 v153, v153, v154
	v_mad_i64_i32 v[154:155], s[22:23], s14, v155, 0
	v_cvt_pk_bf16_f32 v152, v148, v152
	v_lshl_add_u64 v[154:155], v[154:155], 1, v[142:143]
	global_store_dwordx2 v[154:155], v[152:153], off
	v_mul_f32_e32 v148, 0x3e000000, v23
	v_cndmask_b32_e64 v148, v23, v148, s[20:21]
	v_mul_f32_e32 v152, 0x3e000000, v19
	v_cndmask_b32_e64 v152, v19, v152, s[20:21]
	v_mul_f32_e32 v153, 0x3e000000, v31
	v_cndmask_b32_e64 v153, v31, v153, s[20:21]
	v_mul_f32_e32 v154, 0x3e000000, v27
	v_cndmask_b32_e64 v154, v27, v154, s[20:21]
	v_add_u32_e32 v155, 0xa1, v0
	v_cvt_pk_bf16_f32 v153, v153, v154
	v_mad_i64_i32 v[154:155], s[22:23], s14, v155, 0
	v_cvt_pk_bf16_f32 v152, v148, v152
	v_lshl_add_u64 v[154:155], v[154:155], 1, v[142:143]
	global_store_dwordx2 v[154:155], v[152:153], off
	v_mul_f32_e32 v148, 0x3e000000, v24
	v_cndmask_b32_e64 v148, v24, v148, s[20:21]
	v_mul_f32_e32 v152, 0x3e000000, v20
	v_cndmask_b32_e64 v152, v20, v152, s[20:21]
	v_mul_f32_e32 v153, 0x3e000000, v32
	v_cndmask_b32_e64 v153, v32, v153, s[20:21]
	v_mul_f32_e32 v154, 0x3e000000, v28
	v_cndmask_b32_e64 v154, v28, v154, s[20:21]
	v_add_u32_e32 v155, 0xa2, v0
	v_cvt_pk_bf16_f32 v153, v153, v154
	v_mad_i64_i32 v[154:155], s[22:23], s14, v155, 0
	v_cvt_pk_bf16_f32 v152, v148, v152
	v_lshl_add_u64 v[154:155], v[154:155], 1, v[142:143]
	global_store_dwordx2 v[154:155], v[152:153], off
	v_mul_f32_e32 v148, 0x3e000000, v25
	v_cndmask_b32_e64 v148, v25, v148, s[20:21]
	v_mul_f32_e32 v152, 0x3e000000, v21
	v_cndmask_b32_e64 v152, v21, v152, s[20:21]
	v_mul_f32_e32 v153, 0x3e000000, v33
	v_cndmask_b32_e64 v153, v33, v153, s[20:21]
	v_mul_f32_e32 v154, 0x3e000000, v29
	v_cndmask_b32_e64 v154, v29, v154, s[20:21]
	v_add_u32_e32 v155, 0xa3, v0
	v_cvt_pk_bf16_f32 v153, v153, v154
	v_mad_i64_i32 v[154:155], s[22:23], s14, v155, 0
	v_cvt_pk_bf16_f32 v152, v148, v152
	v_lshl_add_u64 v[154:155], v[154:155], 1, v[142:143]
	global_store_dwordx2 v[154:155], v[152:153], off
	v_mul_f32_e32 v148, 0x3e000000, v6
	v_cndmask_b32_e64 v148, v6, v148, s[20:21]
; DEVINL float sigmoidf_(float x) { return __fdividef(1.f, 1.f + __expf(-x)); }
; DEVINL float siluf_(float x) { return __fdividef(x, 1.f + __expf(-x)); }
;   DEVINL void operator()(Acc& acc, int brow, int bcol) const {
;     ...
;       _Pragma("unroll") for (int ai = 0; ai < 2; ++ai) _Pragma("unroll") for (int m = 0; m < 4; ++m) _Pragma("unroll") for (int j = 0; j < 4; ++j) {
;         const int row = brow + ai * 128 + wr * 64 + m * 16 + fq * 4 + j;
;         float v[4] = {acc[ai][0][m][0][j], acc[ai][0][m][1][j], acc[ai][1][m][0][j], acc[ai][1][m][1][j]};
;         _Pragma("unroll") for (int k = 0; k < 4; ++k) v[k] = fn == 1 ? siluf_(v[k]) : (fn == 2 ? sigmoidf_(v[k]) : (fn == 3 ? v[k] * 0.125f : v[k]));
;         *(bf16x4*)(dst + (size_t)row * ld + c0) = pack4(v[0], v[1], v[2], v[3]);
	v_mul_f32_e32 v152, 0x3e000000, v2
	v_cndmask_b32_e64 v152, v2, v152, s[20:21]
	v_mul_f32_e32 v153, 0x3e000000, v14
	v_cndmask_b32_e64 v153, v14, v153, s[20:21]
	v_mul_f32_e32 v154, 0x3e000000, v10
	v_cndmask_b32_e64 v154, v10, v154, s[20:21]
	v_add_u32_e32 v155, 0xb0, v0
	v_cvt_pk_bf16_f32 v153, v153, v154
	v_mad_i64_i32 v[154:155], s[22:23], s14, v155, 0
	v_cvt_pk_bf16_f32 v152, v148, v152
	v_lshl_add_u64 v[154:155], v[154:155], 1, v[142:143]
	global_store_dwordx2 v[154:155], v[152:153], off
	v_mul_f32_e32 v148, 0x3e000000, v7
	v_cndmask_b32_e64 v148, v7, v148, s[20:21]
	v_mul_f32_e32 v152, 0x3e000000, v3
	v_cndmask_b32_e64 v152, v3, v152, s[20:21]
	v_mul_f32_e32 v153, 0x3e000000, v15
	v_cndmask_b32_e64 v153, v15, v153, s[20:21]
	v_mul_f32_e32 v154, 0x3e000000, v11
	v_cndmask_b32_e64 v154, v11, v154, s[20:21]
	v_add_u32_e32 v155, 0xb1, v0
	v_cvt_pk_bf16_f32 v153, v153, v154
	v_mad_i64_i32 v[154:155], s[22:23], s14, v155, 0
	v_cvt_pk_bf16_f32 v152, v148, v152
	v_lshl_add_u64 v[154:155], v[154:155], 1, v[142:143]
	global_store_dwordx2 v[154:155], v[152:153], off
	v_mul_f32_e32 v148, 0x3e000000, v8
	v_cndmask_b32_e64 v148, v8, v148, s[20:21]
	v_mul_f32_e32 v152, 0x3e000000, v4
	v_cndmask_b32_e64 v152, v4, v152, s[20:21]
	v_mul_f32_e32 v153, 0x3e000000, v16
	v_cndmask_b32_e64 v153, v16, v153, s[20:21]
	v_mul_f32_e32 v154, 0x3e000000, v12
	v_cndmask_b32_e64 v154, v12, v154, s[20:21]
	v_add_u32_e32 v155, 0xb2, v0
	v_cvt_pk_bf16_f32 v153, v153, v154
	v_mad_i64_i32 v[154:155], s[22:23], s14, v155, 0
	v_cvt_pk_bf16_f32 v152, v148, v152
	v_lshl_add_u64 v[154:155], v[154:155], 1, v[142:143]
	global_store_dwordx2 v[154:155], v[152:153], off
	v_mul_f32_e32 v148, 0x3e000000, v9
	v_cndmask_b32_e64 v148, v9, v148, s[20:21]
	v_mul_f32_e32 v152, 0x3e000000, v5
	v_cndmask_b32_e64 v152, v5, v152, s[20:21]
	v_mul_f32_e32 v153, 0x3e000000, v17
	v_cndmask_b32_e64 v153, v17, v153, s[20:21]
	v_mul_f32_e32 v154, 0x3e000000, v13
	v_cndmask_b32_e64 v154, v13, v154, s[20:21]
	v_add_u32_e32 v0, 0xb3, v0
	v_cvt_pk_bf16_f32 v153, v153, v154
	v_mad_i64_i32 v[154:155], s[8:9], s14, v0, 0
	v_cvt_pk_bf16_f32 v152, v148, v152
	v_lshl_add_u64 v[142:143], v[154:155], 1, v[142:143]
	global_store_dwordx2 v[142:143], v[152:153], off
	s_branch .LBB0_445
.Lgw_scl:
	s_add_u32 s24, s88, s24
	s_addc_u32 s25, s89, s25
	v_mul_f32_e32 v0, 0x3e000000, v118
	v_cndmask_b32_e64 v148, v118, v0, s[20:21]
	v_mul_f32_e32 v0, 0x3e000000, v114
	v_cndmask_b32_e64 v152, v114, v0, s[20:21]
	s_load_dwordx2 s[24:25], s[24:25], 0x0
	v_mul_f32_e32 v0, 0x3e000000, v126
	v_cndmask_b32_e64 v153, v126, v0, s[20:21]
	v_mul_f32_e32 v0, 0x3e000000, v122
	v_cndmask_b32_e64 v154, v122, v0, s[20:21]
	s_add_i32 s13, s13, s22
	v_lshlrev_b32_e32 v0, 6, v149
	v_lshlrev_b32_e32 v142, 2, v146
	v_or3_b32 v142, v0, v142, s13
	v_lshl_add_u32 v0, v144, 6, s12
	v_lshl_or_b32 v0, v145, 2, v0
	v_ashrrev_i32_e32 v143, 31, v142
	s_waitcnt lgkmcnt(0)
	v_lshl_add_u64 v[142:143], v[142:143], 1, s[24:25]
	v_cvt_pk_bf16_f32 v153, v153, v154
	v_mad_i64_i32 v[154:155], s[22:23], s14, v0, 0
	v_cvt_pk_bf16_f32 v152, v148, v152
	v_lshl_add_u64 v[154:155], v[154:155], 1, v[142:143]
	global_store_dwordx2 v[154:155], v[152:153], off
	v_mul_f32_e32 v148, 0x3e000000, v119
	v_cndmask_b32_e64 v148, v119, v148, s[20:21]
	v_mul_f32_e32 v152, 0x3e000000, v115
	v_cndmask_b32_e64 v152, v115, v152, s[20:21]
	v_mul_f32_e32 v153, 0x3e000000, v127
	v_cndmask_b32_e64 v153, v127, v153, s[20:21]
	v_mul_f32_e32 v154, 0x3e000000, v123
	v_cndmask_b32_e64 v154, v123, v154, s[20:21]
	v_or_b32_e32 v155, 1, v0
	v_cvt_pk_bf16_f32 v153, v153, v154
	v_mad_i64_i32 v[154:155], s[22:23], s14, v155, 0
	v_cvt_pk_bf16_f32 v152, v148, v152
	v_lshl_add_u64 v[154:155], v[154:155], 1, v[142:143]
	global_store_dwordx2 v[154:155], v[152:153], off
	v_mul_f32_e32 v148, 0x3e000000, v120
	v_cndmask_b32_e64 v148, v120, v148, s[20:21]
	v_mul_f32_e32 v152, 0x3e000000, v116
	v_cndmask_b32_e64 v152, v116, v152, s[20:21]
	v_mul_f32_e32 v153, 0x3e000000, v128
	v_cndmask_b32_e64 v153, v128, v153, s[20:21]
	v_mul_f32_e32 v154, 0x3e000000, v124
	v_cndmask_b32_e64 v154, v124, v154, s[20:21]
	v_or_b32_e32 v155, 2, v0
	v_cvt_pk_bf16_f32 v153, v153, v154
	v_mad_i64_i32 v[154:155], s[22:23], s14, v155, 0
	v_cvt_pk_bf16_f32 v152, v148, v152
	v_lshl_add_u64 v[154:155], v[154:155], 1, v[142:143]
	global_store_dwordx2 v[154:155], v[152:153], off
	v_mul_f32_e32 v148, 0x3e000000, v121
	v_cndmask_b32_e64 v148, v121, v148, s[20:21]
	v_mul_f32_e32 v152, 0x3e000000, v117
	v_cndmask_b32_e64 v152, v117, v152, s[20:21]
	v_mul_f32_e32 v153, 0x3e000000, v129
	v_cndmask_b32_e64 v153, v129, v153, s[20:21]
	v_mul_f32_e32 v154, 0x3e000000, v125
	v_cndmask_b32_e64 v154, v125, v154, s[20:21]
	v_or_b32_e32 v155, 3, v0
	v_cvt_pk_bf16_f32 v153, v153, v154
	v_mad_i64_i32 v[154:155], s[22:23], s14, v155, 0
	v_cvt_pk_bf16_f32 v152, v148, v152
	v_lshl_add_u64 v[154:155], v[154:155], 1, v[142:143]
	global_store_dwordx2 v[154:155], v[152:153], off
	v_mul_f32_e32 v148, 0x3e000000, v102
	v_cndmask_b32_e64 v148, v102, v148, s[20:21]
	v_mul_f32_e32 v152, 0x3e000000, v98
	v_cndmask_b32_e64 v152, v98, v152, s[20:21]
	v_mul_f32_e32 v153, 0x3e000000, v110
	v_cndmask_b32_e64 v153, v110, v153, s[20:21]
	v_mul_f32_e32 v154, 0x3e000000, v106
	v_cndmask_b32_e64 v154, v106, v154, s[20:21]
	v_or_b32_e32 v155, 16, v0
	v_cvt_pk_bf16_f32 v153, v153, v154
	v_mad_i64_i32 v[154:155], s[22:23], s14, v155, 0
	v_cvt_pk_bf16_f32 v152, v148, v152
	v_lshl_add_u64 v[154:155], v[154:155], 1, v[142:143]
	global_store_dwordx2 v[154:155], v[152:153], off
	v_mul_f32_e32 v148, 0x3e000000, v103
	v_cndmask_b32_e64 v148, v103, v148, s[20:21]
; DEVINL float sigmoidf_(float x) { return __fdividef(1.f, 1.f + __expf(-x)); }
; DEVINL float siluf_(float x) { return __fdividef(x, 1.f + __expf(-x)); }
;   DEVINL void operator()(Acc& acc, int brow, int bcol) const {
;     ...
;       _Pragma("unroll") for (int ai = 0; ai < 2; ++ai) _Pragma("unroll") for (int m = 0; m < 4; ++m) _Pragma("unroll") for (int j = 0; j < 4; ++j) {
;         const int row = brow + ai * 128 + wr * 64 + m * 16 + fq * 4 + j;
;         float v[4] = {acc[ai][0][m][0][j], acc[ai][0][m][1][j], acc[ai][1][m][0][j], acc[ai][1][m][1][j]};
;         _Pragma("unroll") for (int k = 0; k < 4; ++k) v[k] = fn == 1 ? siluf_(v[k]) : (fn == 2 ? sigmoidf_(v[k]) : (fn == 3 ? v[k] * 0.125f : v[k]));
;         *(bf16x4*)(dst + (size_t)row * ld + c0) = pack4(v[0], v[1], v[2], v[3]);
	v_mul_f32_e32 v152, 0x3e000000, v99
	v_cndmask_b32_e64 v152, v99, v152, s[20:21]
	v_mul_f32_e32 v153, 0x3e000000, v111
	v_cndmask_b32_e64 v153, v111, v153, s[20:21]
	v_mul_f32_e32 v154, 0x3e000000, v107
	v_cndmask_b32_e64 v154, v107, v154, s[20:21]
	v_or_b32_e32 v155, 17, v0
	v_cvt_pk_bf16_f32 v153, v153, v154
	v_mad_i64_i32 v[154:155], s[22:23], s14, v155, 0
	v_cvt_pk_bf16_f32 v152, v148, v152
	v_lshl_add_u64 v[154:155], v[154:155], 1, v[142:143]
	global_store_dwordx2 v[154:155], v[152:153], off
	v_mul_f32_e32 v148, 0x3e000000, v104
	v_cndmask_b32_e64 v148, v104, v148, s[20:21]
	v_mul_f32_e32 v152, 0x3e000000, v100
	v_cndmask_b32_e64 v152, v100, v152, s[20:21]
	v_mul_f32_e32 v153, 0x3e000000, v112
	v_cndmask_b32_e64 v153, v112, v153, s[20:21]
	v_mul_f32_e32 v154, 0x3e000000, v108
	v_cndmask_b32_e64 v154, v108, v154, s[20:21]
	v_or_b32_e32 v155, 18, v0
	v_cvt_pk_bf16_f32 v153, v153, v154
	v_mad_i64_i32 v[154:155], s[22:23], s14, v155, 0
	v_cvt_pk_bf16_f32 v152, v148, v152
	v_lshl_add_u64 v[154:155], v[154:155], 1, v[142:143]
	global_store_dwordx2 v[154:155], v[152:153], off
	v_mul_f32_e32 v148, 0x3e000000, v105
	v_cndmask_b32_e64 v148, v105, v148, s[20:21]
	v_mul_f32_e32 v152, 0x3e000000, v101
	v_cndmask_b32_e64 v152, v101, v152, s[20:21]
	v_mul_f32_e32 v153, 0x3e000000, v113
	v_cndmask_b32_e64 v153, v113, v153, s[20:21]
	v_mul_f32_e32 v154, 0x3e000000, v109
	v_cndmask_b32_e64 v154, v109, v154, s[20:21]
	v_or_b32_e32 v155, 19, v0
	v_cvt_pk_bf16_f32 v153, v153, v154
	v_mad_i64_i32 v[154:155], s[22:23], s14, v155, 0
	v_cvt_pk_bf16_f32 v152, v148, v152
	v_lshl_add_u64 v[154:155], v[154:155], 1, v[142:143]
	global_store_dwordx2 v[154:155], v[152:153], off
	v_mul_f32_e32 v148, 0x3e000000, v86
	v_cndmask_b32_e64 v148, v86, v148, s[20:21]
	v_mul_f32_e32 v152, 0x3e000000, v82
	v_cndmask_b32_e64 v152, v82, v152, s[20:21]
	v_mul_f32_e32 v153, 0x3e000000, v94
	v_cndmask_b32_e64 v153, v94, v153, s[20:21]
	v_mul_f32_e32 v154, 0x3e000000, v90
	v_cndmask_b32_e64 v154, v90, v154, s[20:21]
	v_or_b32_e32 v155, 32, v0
	v_cvt_pk_bf16_f32 v153, v153, v154
	v_mad_i64_i32 v[154:155], s[22:23], s14, v155, 0
	v_cvt_pk_bf16_f32 v152, v148, v152
	v_lshl_add_u64 v[154:155], v[154:155], 1, v[142:143]
	global_store_dwordx2 v[154:155], v[152:153], off
	v_mul_f32_e32 v148, 0x3e000000, v87
	v_cndmask_b32_e64 v148, v87, v148, s[20:21]
	v_mul_f32_e32 v152, 0x3e000000, v83
	v_cndmask_b32_e64 v152, v83, v152, s[20:21]
	v_mul_f32_e32 v153, 0x3e000000, v95
	v_cndmask_b32_e64 v153, v95, v153, s[20:21]
	v_mul_f32_e32 v154, 0x3e000000, v91
	v_cndmask_b32_e64 v154, v91, v154, s[20:21]
	v_or_b32_e32 v155, 33, v0
	v_cvt_pk_bf16_f32 v153, v153, v154
	v_mad_i64_i32 v[154:155], s[22:23], s14, v155, 0
	v_cvt_pk_bf16_f32 v152, v148, v152
	v_lshl_add_u64 v[154:155], v[154:155], 1, v[142:143]
	global_store_dwordx2 v[154:155], v[152:153], off
	v_mul_f32_e32 v148, 0x3e000000, v88
	v_cndmask_b32_e64 v148, v88, v148, s[20:21]
	v_mul_f32_e32 v152, 0x3e000000, v84
	v_cndmask_b32_e64 v152, v84, v152, s[20:21]
	v_mul_f32_e32 v153, 0x3e000000, v96
	v_cndmask_b32_e64 v153, v96, v153, s[20:21]
	v_mul_f32_e32 v154, 0x3e000000, v92
	v_cndmask_b32_e64 v154, v92, v154, s[20:21]
	v_or_b32_e32 v155, 34, v0
	v_cvt_pk_bf16_f32 v153, v153, v154
	v_mad_i64_i32 v[154:155], s[22:23], s14, v155, 0
	v_cvt_pk_bf16_f32 v152, v148, v152
	v_lshl_add_u64 v[154:155], v[154:155], 1, v[142:143]
	global_store_dwordx2 v[154:155], v[152:153], off
	v_mul_f32_e32 v148, 0x3e000000, v89
	v_cndmask_b32_e64 v148, v89, v148, s[20:21]
	v_mul_f32_e32 v152, 0x3e000000, v85
	v_cndmask_b32_e64 v152, v85, v152, s[20:21]
	v_mul_f32_e32 v153, 0x3e000000, v97
	v_cndmask_b32_e64 v153, v97, v153, s[20:21]
	v_mul_f32_e32 v154, 0x3e000000, v93
	v_cndmask_b32_e64 v154, v93, v154, s[20:21]
	v_or_b32_e32 v155, 35, v0
	v_cvt_pk_bf16_f32 v153, v153, v154
	v_mad_i64_i32 v[154:155], s[22:23], s14, v155, 0
	v_cvt_pk_bf16_f32 v152, v148, v152
	v_lshl_add_u64 v[154:155], v[154:155], 1, v[142:143]
	global_store_dwordx2 v[154:155], v[152:153], off
	v_mul_f32_e32 v148, 0x3e000000, v70
	v_cndmask_b32_e64 v148, v70, v148, s[20:21]
	v_mul_f32_e32 v152, 0x3e000000, v66
	v_cndmask_b32_e64 v152, v66, v152, s[20:21]
	v_mul_f32_e32 v153, 0x3e000000, v78
	v_cndmask_b32_e64 v153, v78, v153, s[20:21]
	v_mul_f32_e32 v154, 0x3e000000, v74
	v_cndmask_b32_e64 v154, v74, v154, s[20:21]
	v_or_b32_e32 v155, 48, v0
	v_cvt_pk_bf16_f32 v153, v153, v154
	v_mad_i64_i32 v[154:155], s[22:23], s14, v155, 0
	v_cvt_pk_bf16_f32 v152, v148, v152
	v_lshl_add_u64 v[154:155], v[154:155], 1, v[142:143]
	global_store_dwordx2 v[154:155], v[152:153], off
	v_mul_f32_e32 v148, 0x3e000000, v71
	v_cndmask_b32_e64 v148, v71, v148, s[20:21]
	v_mul_f32_e32 v152, 0x3e000000, v67
	v_cndmask_b32_e64 v152, v67, v152, s[20:21]
	v_mul_f32_e32 v153, 0x3e000000, v79
	v_cndmask_b32_e64 v153, v79, v153, s[20:21]
	v_mul_f32_e32 v154, 0x3e000000, v75
	v_cndmask_b32_e64 v154, v75, v154, s[20:21]
	v_or_b32_e32 v155, 49, v0
	v_cvt_pk_bf16_f32 v153, v153, v154
	v_mad_i64_i32 v[154:155], s[22:23], s14, v155, 0
	v_cvt_pk_bf16_f32 v152, v148, v152
	v_lshl_add_u64 v[154:155], v[154:155], 1, v[142:143]
	global_store_dwordx2 v[154:155], v[152:153], off
	v_mul_f32_e32 v148, 0x3e000000, v72
	v_cndmask_b32_e64 v148, v72, v148, s[20:21]
	v_mul_f32_e32 v152, 0x3e000000, v68
	v_cndmask_b32_e64 v152, v68, v152, s[20:21]
	v_mul_f32_e32 v153, 0x3e000000, v80
	v_cndmask_b32_e64 v153, v80, v153, s[20:21]
	v_mul_f32_e32 v154, 0x3e000000, v76
	v_cndmask_b32_e64 v154, v76, v154, s[20:21]
	v_or_b32_e32 v155, 50, v0
	v_cvt_pk_bf16_f32 v153, v153, v154
	v_mad_i64_i32 v[154:155], s[22:23], s14, v155, 0
	v_cvt_pk_bf16_f32 v152, v148, v152
; DEVINL float sigmoidf_(float x) { return __fdividef(1.f, 1.f + __expf(-x)); }
; DEVINL float siluf_(float x) { return __fdividef(x, 1.f + __expf(-x)); }
;   DEVINL void operator()(Acc& acc, int brow, int bcol) const {
;     ...
;       _Pragma("unroll") for (int ai = 0; ai < 2; ++ai) _Pragma("unroll") for (int m = 0; m < 4; ++m) _Pragma("unroll") for (int j = 0; j < 4; ++j) {
;         const int row = brow + ai * 128 + wr * 64 + m * 16 + fq * 4 + j;
;         float v[4] = {acc[ai][0][m][0][j], acc[ai][0][m][1][j], acc[ai][1][m][0][j], acc[ai][1][m][1][j]};
;         _Pragma("unroll") for (int k = 0; k < 4; ++k) v[k] = fn == 1 ? siluf_(v[k]) : (fn == 2 ? sigmoidf_(v[k]) : (fn == 3 ? v[k] * 0.125f : v[k]));
;         *(bf16x4*)(dst + (size_t)row * ld + c0) = pack4(v[0], v[1], v[2], v[3]);
	v_lshl_add_u64 v[154:155], v[154:155], 1, v[142:143]
	global_store_dwordx2 v[154:155], v[152:153], off
	v_mul_f32_e32 v148, 0x3e000000, v73
	v_cndmask_b32_e64 v148, v73, v148, s[20:21]
	v_mul_f32_e32 v152, 0x3e000000, v69
	v_cndmask_b32_e64 v152, v69, v152, s[20:21]
	v_mul_f32_e32 v153, 0x3e000000, v81
	v_cndmask_b32_e64 v153, v81, v153, s[20:21]
	v_mul_f32_e32 v154, 0x3e000000, v77
	v_cndmask_b32_e64 v154, v77, v154, s[20:21]
	v_or_b32_e32 v155, 51, v0
	v_cvt_pk_bf16_f32 v153, v153, v154
	v_mad_i64_i32 v[154:155], s[22:23], s14, v155, 0
	v_cvt_pk_bf16_f32 v152, v148, v152
	v_lshl_add_u64 v[154:155], v[154:155], 1, v[142:143]
	global_store_dwordx2 v[154:155], v[152:153], off
	v_mul_f32_e32 v148, 0x3e000000, v54
	v_cndmask_b32_e64 v148, v54, v148, s[20:21]
	v_mul_f32_e32 v152, 0x3e000000, v50
	v_cndmask_b32_e64 v152, v50, v152, s[20:21]
	v_mul_f32_e32 v153, 0x3e000000, v62
	v_cndmask_b32_e64 v153, v62, v153, s[20:21]
	v_mul_f32_e32 v154, 0x3e000000, v58
	v_cndmask_b32_e64 v154, v58, v154, s[20:21]
	v_add_u32_e32 v155, 0x80, v0
	v_cvt_pk_bf16_f32 v153, v153, v154
	v_mad_i64_i32 v[154:155], s[22:23], s14, v155, 0
	v_cvt_pk_bf16_f32 v152, v148, v152
	v_lshl_add_u64 v[154:155], v[154:155], 1, v[142:143]
	global_store_dwordx2 v[154:155], v[152:153], off
	v_mul_f32_e32 v148, 0x3e000000, v55
	v_cndmask_b32_e64 v148, v55, v148, s[20:21]
	v_mul_f32_e32 v152, 0x3e000000, v51
	v_cndmask_b32_e64 v152, v51, v152, s[20:21]
	v_mul_f32_e32 v153, 0x3e000000, v63
	v_cndmask_b32_e64 v153, v63, v153, s[20:21]
	v_mul_f32_e32 v154, 0x3e000000, v59
	v_cndmask_b32_e64 v154, v59, v154, s[20:21]
	v_add_u32_e32 v155, 0x81, v0
	v_cvt_pk_bf16_f32 v153, v153, v154
	v_mad_i64_i32 v[154:155], s[22:23], s14, v155, 0
	v_cvt_pk_bf16_f32 v152, v148, v152
	v_lshl_add_u64 v[154:155], v[154:155], 1, v[142:143]
	global_store_dwordx2 v[154:155], v[152:153], off
	v_mul_f32_e32 v148, 0x3e000000, v56
	v_cndmask_b32_e64 v148, v56, v148, s[20:21]
	v_mul_f32_e32 v152, 0x3e000000, v52
	v_cndmask_b32_e64 v152, v52, v152, s[20:21]
	v_mul_f32_e32 v153, 0x3e000000, v64
	v_cndmask_b32_e64 v153, v64, v153, s[20:21]
	v_mul_f32_e32 v154, 0x3e000000, v60
	v_cndmask_b32_e64 v154, v60, v154, s[20:21]
	v_add_u32_e32 v155, 0x82, v0
	v_cvt_pk_bf16_f32 v153, v153, v154
	v_mad_i64_i32 v[154:155], s[22:23], s14, v155, 0
	v_cvt_pk_bf16_f32 v152, v148, v152
	v_lshl_add_u64 v[154:155], v[154:155], 1, v[142:143]
	global_store_dwordx2 v[154:155], v[152:153], off
	v_mul_f32_e32 v148, 0x3e000000, v57
	v_cndmask_b32_e64 v148, v57, v148, s[20:21]
	v_mul_f32_e32 v152, 0x3e000000, v53
	v_cndmask_b32_e64 v152, v53, v152, s[20:21]
	v_mul_f32_e32 v153, 0x3e000000, v65
	v_cndmask_b32_e64 v153, v65, v153, s[20:21]
	v_mul_f32_e32 v154, 0x3e000000, v61
	v_cndmask_b32_e64 v154, v61, v154, s[20:21]
	v_add_u32_e32 v155, 0x83, v0
	v_cvt_pk_bf16_f32 v153, v153, v154
	v_mad_i64_i32 v[154:155], s[22:23], s14, v155, 0
	v_cvt_pk_bf16_f32 v152, v148, v152
	v_lshl_add_u64 v[154:155], v[154:155], 1, v[142:143]
	global_store_dwordx2 v[154:155], v[152:153], off
	v_mul_f32_e32 v148, 0x3e000000, v38
	v_cndmask_b32_e64 v148, v38, v148, s[20:21]
	v_mul_f32_e32 v152, 0x3e000000, v34
	v_cndmask_b32_e64 v152, v34, v152, s[20:21]
	v_mul_f32_e32 v153, 0x3e000000, v46
	v_cndmask_b32_e64 v153, v46, v153, s[20:21]
	v_mul_f32_e32 v154, 0x3e000000, v42
	v_cndmask_b32_e64 v154, v42, v154, s[20:21]
	v_add_u32_e32 v155, 0x90, v0
	v_cvt_pk_bf16_f32 v153, v153, v154
	v_mad_i64_i32 v[154:155], s[22:23], s14, v155, 0
	v_cvt_pk_bf16_f32 v152, v148, v152
	v_lshl_add_u64 v[154:155], v[154:155], 1, v[142:143]
	global_store_dwordx2 v[154:155], v[152:153], off
	v_mul_f32_e32 v148, 0x3e000000, v39
	v_cndmask_b32_e64 v148, v39, v148, s[20:21]
	v_mul_f32_e32 v152, 0x3e000000, v35
	v_cndmask_b32_e64 v152, v35, v152, s[20:21]
	v_mul_f32_e32 v153, 0x3e000000, v47
	v_cndmask_b32_e64 v153, v47, v153, s[20:21]
	v_mul_f32_e32 v154, 0x3e000000, v43
	v_cndmask_b32_e64 v154, v43, v154, s[20:21]
	v_add_u32_e32 v155, 0x91, v0
	v_cvt_pk_bf16_f32 v153, v153, v154
	v_mad_i64_i32 v[154:155], s[22:23], s14, v155, 0
	v_cvt_pk_bf16_f32 v152, v148, v152
	v_lshl_add_u64 v[154:155], v[154:155], 1, v[142:143]
	global_store_dwordx2 v[154:155], v[152:153], off
	v_mul_f32_e32 v148, 0x3e000000, v40
	v_cndmask_b32_e64 v148, v40, v148, s[20:21]
	v_mul_f32_e32 v152, 0x3e000000, v36
	v_cndmask_b32_e64 v152, v36, v152, s[20:21]
	v_mul_f32_e32 v153, 0x3e000000, v48
	v_cndmask_b32_e64 v153, v48, v153, s[20:21]
	v_mul_f32_e32 v154, 0x3e000000, v44
	v_cndmask_b32_e64 v154, v44, v154, s[20:21]
	v_add_u32_e32 v155, 0x92, v0
	v_cvt_pk_bf16_f32 v153, v153, v154
	v_mad_i64_i32 v[154:155], s[22:23], s14, v155, 0
	v_cvt_pk_bf16_f32 v152, v148, v152
	v_lshl_add_u64 v[154:155], v[154:155], 1, v[142:143]
	global_store_dwordx2 v[154:155], v[152:153], off
	v_mul_f32_e32 v148, 0x3e000000, v41
	v_cndmask_b32_e64 v148, v41, v148, s[20:21]
	v_mul_f32_e32 v152, 0x3e000000, v37
	v_cndmask_b32_e64 v152, v37, v152, s[20:21]
	v_mul_f32_e32 v153, 0x3e000000, v49
	v_cndmask_b32_e64 v153, v49, v153, s[20:21]
	v_mul_f32_e32 v154, 0x3e000000, v45
	v_cndmask_b32_e64 v154, v45, v154, s[20:21]
	v_add_u32_e32 v155, 0x93, v0
	v_cvt_pk_bf16_f32 v153, v153, v154
	v_mad_i64_i32 v[154:155], s[22:23], s14, v155, 0
	v_cvt_pk_bf16_f32 v152, v148, v152
	v_lshl_add_u64 v[154:155], v[154:155], 1, v[142:143]
	global_store_dwordx2 v[154:155], v[152:153], off
	v_mul_f32_e32 v148, 0x3e000000, v22
	v_cndmask_b32_e64 v148, v22, v148, s[20:21]
	v_mul_f32_e32 v152, 0x3e000000, v18
	v_cndmask_b32_e64 v152, v18, v152, s[20:21]
	v_mul_f32_e32 v153, 0x3e000000, v30
	v_cndmask_b32_e64 v153, v30, v153, s[20:21]
	v_mul_f32_e32 v154, 0x3e000000, v26
; DEVINL float sigmoidf_(float x) { return __fdividef(1.f, 1.f + __expf(-x)); }
; DEVINL float siluf_(float x) { return __fdividef(x, 1.f + __expf(-x)); }
;   DEVINL void operator()(Acc& acc, int brow, int bcol) const {
;     ...
;       _Pragma("unroll") for (int ai = 0; ai < 2; ++ai) _Pragma("unroll") for (int m = 0; m < 4; ++m) _Pragma("unroll") for (int j = 0; j < 4; ++j) {
;         const int row = brow + ai * 128 + wr * 64 + m * 16 + fq * 4 + j;
;         float v[4] = {acc[ai][0][m][0][j], acc[ai][0][m][1][j], acc[ai][1][m][0][j], acc[ai][1][m][1][j]};
;         _Pragma("unroll") for (int k = 0; k < 4; ++k) v[k] = fn == 1 ? siluf_(v[k]) : (fn == 2 ? sigmoidf_(v[k]) : (fn == 3 ? v[k] * 0.125f : v[k]));
;         *(bf16x4*)(dst + (size_t)row * ld + c0) = pack4(v[0], v[1], v[2], v[3]);
	v_cndmask_b32_e64 v154, v26, v154, s[20:21]
	v_add_u32_e32 v155, 0xa0, v0
	v_cvt_pk_bf16_f32 v153, v153, v154
	v_mad_i64_i32 v[154:155], s[22:23], s14, v155, 0
	v_cvt_pk_bf16_f32 v152, v148, v152
	v_lshl_add_u64 v[154:155], v[154:155], 1, v[142:143]
	global_store_dwordx2 v[154:155], v[152:153], off
	v_mul_f32_e32 v148, 0x3e000000, v23
	v_cndmask_b32_e64 v148, v23, v148, s[20:21]
	v_mul_f32_e32 v152, 0x3e000000, v19
	v_cndmask_b32_e64 v152, v19, v152, s[20:21]
	v_mul_f32_e32 v153, 0x3e000000, v31
	v_cndmask_b32_e64 v153, v31, v153, s[20:21]
	v_mul_f32_e32 v154, 0x3e000000, v27
	v_cndmask_b32_e64 v154, v27, v154, s[20:21]
	v_add_u32_e32 v155, 0xa1, v0
	v_cvt_pk_bf16_f32 v153, v153, v154
	v_mad_i64_i32 v[154:155], s[22:23], s14, v155, 0
	v_cvt_pk_bf16_f32 v152, v148, v152
	v_lshl_add_u64 v[154:155], v[154:155], 1, v[142:143]
	global_store_dwordx2 v[154:155], v[152:153], off
	v_mul_f32_e32 v148, 0x3e000000, v24
	v_cndmask_b32_e64 v148, v24, v148, s[20:21]
	v_mul_f32_e32 v152, 0x3e000000, v20
	v_cndmask_b32_e64 v152, v20, v152, s[20:21]
	v_mul_f32_e32 v153, 0x3e000000, v32
	v_cndmask_b32_e64 v153, v32, v153, s[20:21]
	v_mul_f32_e32 v154, 0x3e000000, v28
	v_cndmask_b32_e64 v154, v28, v154, s[20:21]
	v_add_u32_e32 v155, 0xa2, v0
	v_cvt_pk_bf16_f32 v153, v153, v154
	v_mad_i64_i32 v[154:155], s[22:23], s14, v155, 0
	v_cvt_pk_bf16_f32 v152, v148, v152
	v_lshl_add_u64 v[154:155], v[154:155], 1, v[142:143]
	global_store_dwordx2 v[154:155], v[152:153], off
	v_mul_f32_e32 v148, 0x3e000000, v25
	v_cndmask_b32_e64 v148, v25, v148, s[20:21]
	v_mul_f32_e32 v152, 0x3e000000, v21
	v_cndmask_b32_e64 v152, v21, v152, s[20:21]
	v_mul_f32_e32 v153, 0x3e000000, v33
	v_cndmask_b32_e64 v153, v33, v153, s[20:21]
	v_mul_f32_e32 v154, 0x3e000000, v29
	v_cndmask_b32_e64 v154, v29, v154, s[20:21]
	v_add_u32_e32 v155, 0xa3, v0
	v_cvt_pk_bf16_f32 v153, v153, v154
	v_mad_i64_i32 v[154:155], s[22:23], s14, v155, 0
	v_cvt_pk_bf16_f32 v152, v148, v152
	v_lshl_add_u64 v[154:155], v[154:155], 1, v[142:143]
	global_store_dwordx2 v[154:155], v[152:153], off
	v_mul_f32_e32 v148, 0x3e000000, v6
	v_cndmask_b32_e64 v148, v6, v148, s[20:21]
	v_mul_f32_e32 v152, 0x3e000000, v2
	v_cndmask_b32_e64 v152, v2, v152, s[20:21]
	v_mul_f32_e32 v153, 0x3e000000, v14
	v_cndmask_b32_e64 v153, v14, v153, s[20:21]
	v_mul_f32_e32 v154, 0x3e000000, v10
	v_cndmask_b32_e64 v154, v10, v154, s[20:21]
	v_add_u32_e32 v155, 0xb0, v0
	v_cvt_pk_bf16_f32 v153, v153, v154
	v_mad_i64_i32 v[154:155], s[22:23], s14, v155, 0
	v_cvt_pk_bf16_f32 v152, v148, v152
	v_lshl_add_u64 v[154:155], v[154:155], 1, v[142:143]
	global_store_dwordx2 v[154:155], v[152:153], off
	v_mul_f32_e32 v148, 0x3e000000, v7
	v_cndmask_b32_e64 v148, v7, v148, s[20:21]
	v_mul_f32_e32 v152, 0x3e000000, v3
	v_cndmask_b32_e64 v152, v3, v152, s[20:21]
	v_mul_f32_e32 v153, 0x3e000000, v15
	v_cndmask_b32_e64 v153, v15, v153, s[20:21]
	v_mul_f32_e32 v154, 0x3e000000, v11
	v_cndmask_b32_e64 v154, v11, v154, s[20:21]
	v_add_u32_e32 v155, 0xb1, v0
	v_cvt_pk_bf16_f32 v153, v153, v154
	v_mad_i64_i32 v[154:155], s[22:23], s14, v155, 0
	v_cvt_pk_bf16_f32 v152, v148, v152
	v_lshl_add_u64 v[154:155], v[154:155], 1, v[142:143]
	global_store_dwordx2 v[154:155], v[152:153], off
	v_mul_f32_e32 v148, 0x3e000000, v8
	v_cndmask_b32_e64 v148, v8, v148, s[20:21]
	v_mul_f32_e32 v152, 0x3e000000, v4
	v_cndmask_b32_e64 v152, v4, v152, s[20:21]
	v_mul_f32_e32 v153, 0x3e000000, v16
	v_cndmask_b32_e64 v153, v16, v153, s[20:21]
	v_mul_f32_e32 v154, 0x3e000000, v12
	v_cndmask_b32_e64 v154, v12, v154, s[20:21]
	v_add_u32_e32 v155, 0xb2, v0
	v_cvt_pk_bf16_f32 v153, v153, v154
	v_mad_i64_i32 v[154:155], s[22:23], s14, v155, 0
	v_cvt_pk_bf16_f32 v152, v148, v152
	v_lshl_add_u64 v[154:155], v[154:155], 1, v[142:143]
	global_store_dwordx2 v[154:155], v[152:153], off
	v_mul_f32_e32 v148, 0x3e000000, v9
	v_cndmask_b32_e64 v148, v9, v148, s[20:21]
	v_mul_f32_e32 v152, 0x3e000000, v5
	v_cndmask_b32_e64 v152, v5, v152, s[20:21]
	v_mul_f32_e32 v153, 0x3e000000, v17
	v_cndmask_b32_e64 v153, v17, v153, s[20:21]
	v_mul_f32_e32 v154, 0x3e000000, v13
	v_cndmask_b32_e64 v154, v13, v154, s[20:21]
	v_add_u32_e32 v0, 0xb3, v0
	v_cvt_pk_bf16_f32 v153, v153, v154
	v_mad_i64_i32 v[154:155], s[8:9], s14, v0, 0
	v_cvt_pk_bf16_f32 v152, v148, v152
	v_lshl_add_u64 v[142:143], v[154:155], 1, v[142:143]
	global_store_dwordx2 v[142:143], v[152:153], off
	s_branch .LBB0_445
; DEVINL float sigmoidf_(float x) { return __fdividef(1.f, 1.f + __expf(-x)); }
; DEVINL float siluf_(float x) { return __fdividef(x, 1.f + __expf(-x)); }
;   DEVINL void operator()(Acc& acc, int brow, int bcol) const {
;     ...
;       _Pragma("unroll") for (int ai = 0; ai < 2; ++ai) _Pragma("unroll") for (int m = 0; m < 4; ++m) _Pragma("unroll") for (int j = 0; j < 4; ++j) {
;         const int row = brow + ai * 128 + wr * 64 + m * 16 + fq * 4 + j;
;         float v[4] = {acc[ai][0][m][0][j], acc[ai][0][m][1][j], acc[ai][1][m][0][j], acc[ai][1][m][1][j]};
;         _Pragma("unroll") for (int k = 0; k < 4; ++k) v[k] = fn == 1 ? siluf_(v[k]) : (fn == 2 ? sigmoidf_(v[k]) : (fn == 3 ? v[k] * 0.125f : v[k]));
;         *(bf16x4*)(dst + (size_t)row * ld + c0) = pack4(v[0], v[1], v[2], v[3]);
.Lgw_silu:
	s_add_u32 s24, s88, s24
	s_addc_u32 s25, s89, s25
	v_mul_f32_e32 v0, 0xbfb8aa3b, v118
	v_exp_f32_e32 v0, v0
	s_nop 0
	v_add_f32_e32 v0, 1.0, v0
	v_rcp_f32_e32 v143, v0
	s_nop 0
	v_mul_f32_e32 v148, v118, v143
	s_load_dwordx2 s[24:25], s[24:25], 0x0
	v_mul_f32_e32 v0, 0xbfb8aa3b, v114
	v_exp_f32_e32 v0, v0
	s_nop 0
	v_add_f32_e32 v0, 1.0, v0
	v_rcp_f32_e32 v143, v0
	s_nop 0
	v_mul_f32_e32 v152, v114, v143
	v_mul_f32_e32 v0, 0xbfb8aa3b, v126
	v_exp_f32_e32 v0, v0
	s_nop 0
	v_add_f32_e32 v0, 1.0, v0
	v_rcp_f32_e32 v143, v0
	s_nop 0
	v_mul_f32_e32 v153, v126, v143
	v_mul_f32_e32 v0, 0xbfb8aa3b, v122
	v_exp_f32_e32 v0, v0
	s_nop 0
	v_add_f32_e32 v0, 1.0, v0
	v_rcp_f32_e32 v143, v0
	s_nop 0
	v_mul_f32_e32 v154, v122, v143
	s_add_i32 s13, s13, s22
	v_lshlrev_b32_e32 v0, 6, v149
	v_lshlrev_b32_e32 v142, 2, v146
	v_or3_b32 v142, v0, v142, s13
	v_lshl_add_u32 v0, v144, 6, s12
	v_lshl_or_b32 v0, v145, 2, v0
	v_ashrrev_i32_e32 v143, 31, v142
	s_waitcnt lgkmcnt(0)
	v_lshl_add_u64 v[142:143], v[142:143], 1, s[24:25]
	v_cvt_pk_bf16_f32 v153, v153, v154
	v_mad_i64_i32 v[154:155], s[22:23], s14, v0, 0
	v_cvt_pk_bf16_f32 v152, v148, v152
	v_lshl_add_u64 v[154:155], v[154:155], 1, v[142:143]
	global_store_dwordx2 v[154:155], v[152:153], off
	v_mul_f32_e32 v148, 0xbfb8aa3b, v119
	v_exp_f32_e32 v148, v148
	s_nop 0
	v_add_f32_e32 v148, 1.0, v148
	v_rcp_f32_e32 v153, v148
	s_nop 0
	v_mul_f32_e32 v148, v119, v153
	v_mul_f32_e32 v152, 0xbfb8aa3b, v115
	v_exp_f32_e32 v152, v152
	s_nop 0
	v_add_f32_e32 v152, 1.0, v152
	v_rcp_f32_e32 v154, v152
	s_nop 0
	v_mul_f32_e32 v152, v115, v154
	v_mul_f32_e32 v153, 0xbfb8aa3b, v127
	v_exp_f32_e32 v153, v153
	s_nop 0
	v_add_f32_e32 v153, 1.0, v153
	v_rcp_f32_e32 v155, v153
	s_nop 0
	v_mul_f32_e32 v153, v127, v155
	v_mul_f32_e32 v154, 0xbfb8aa3b, v123
	v_exp_f32_e32 v154, v154
	s_nop 0
	v_add_f32_e32 v154, 1.0, v154
	v_rcp_f32_e32 v156, v154
	s_nop 0
	v_mul_f32_e32 v154, v123, v156
	v_or_b32_e32 v155, 1, v0
	v_cvt_pk_bf16_f32 v153, v153, v154
	v_mad_i64_i32 v[154:155], s[22:23], s14, v155, 0
	v_cvt_pk_bf16_f32 v152, v148, v152
	v_lshl_add_u64 v[154:155], v[154:155], 1, v[142:143]
	global_store_dwordx2 v[154:155], v[152:153], off
	v_mul_f32_e32 v148, 0xbfb8aa3b, v120
	v_exp_f32_e32 v148, v148
	s_nop 0
	v_add_f32_e32 v148, 1.0, v148
	v_rcp_f32_e32 v153, v148
	s_nop 0
	v_mul_f32_e32 v148, v120, v153
	v_mul_f32_e32 v152, 0xbfb8aa3b, v116
	v_exp_f32_e32 v152, v152
	s_nop 0
	v_add_f32_e32 v152, 1.0, v152
	v_rcp_f32_e32 v154, v152
	s_nop 0
	v_mul_f32_e32 v152, v116, v154
	v_mul_f32_e32 v153, 0xbfb8aa3b, v128
	v_exp_f32_e32 v153, v153
	s_nop 0
	v_add_f32_e32 v153, 1.0, v153
	v_rcp_f32_e32 v155, v153
	s_nop 0
	v_mul_f32_e32 v153, v128, v155
	v_mul_f32_e32 v154, 0xbfb8aa3b, v124
	v_exp_f32_e32 v154, v154
	s_nop 0
	v_add_f32_e32 v154, 1.0, v154
	v_rcp_f32_e32 v156, v154
	s_nop 0
	v_mul_f32_e32 v154, v124, v156
	v_or_b32_e32 v155, 2, v0
	v_cvt_pk_bf16_f32 v153, v153, v154
	v_mad_i64_i32 v[154:155], s[22:23], s14, v155, 0
	v_cvt_pk_bf16_f32 v152, v148, v152
	v_lshl_add_u64 v[154:155], v[154:155], 1, v[142:143]
	global_store_dwordx2 v[154:155], v[152:153], off
	v_mul_f32_e32 v148, 0xbfb8aa3b, v121
	v_exp_f32_e32 v148, v148
	s_nop 0
	v_add_f32_e32 v148, 1.0, v148
	v_rcp_f32_e32 v153, v148
	s_nop 0
	v_mul_f32_e32 v148, v121, v153
	v_mul_f32_e32 v152, 0xbfb8aa3b, v117
	v_exp_f32_e32 v152, v152
	s_nop 0
	v_add_f32_e32 v152, 1.0, v152
	v_rcp_f32_e32 v154, v152
	s_nop 0
	v_mul_f32_e32 v152, v117, v154
	v_mul_f32_e32 v153, 0xbfb8aa3b, v129
	v_exp_f32_e32 v153, v153
	s_nop 0
	v_add_f32_e32 v153, 1.0, v153
	v_rcp_f32_e32 v155, v153
	s_nop 0
	v_mul_f32_e32 v153, v129, v155
	v_mul_f32_e32 v154, 0xbfb8aa3b, v125
	v_exp_f32_e32 v154, v154
	s_nop 0
	v_add_f32_e32 v154, 1.0, v154
	v_rcp_f32_e32 v156, v154
	s_nop 0
	v_mul_f32_e32 v154, v125, v156
	v_or_b32_e32 v155, 3, v0
	v_cvt_pk_bf16_f32 v153, v153, v154
	v_mad_i64_i32 v[154:155], s[22:23], s14, v155, 0
	v_cvt_pk_bf16_f32 v152, v148, v152
	v_lshl_add_u64 v[154:155], v[154:155], 1, v[142:143]
	global_store_dwordx2 v[154:155], v[152:153], off
	v_mul_f32_e32 v148, 0xbfb8aa3b, v102
	v_exp_f32_e32 v148, v148
	s_nop 0
	v_add_f32_e32 v148, 1.0, v148
	v_rcp_f32_e32 v153, v148
	s_nop 0
	v_mul_f32_e32 v148, v102, v153
	v_mul_f32_e32 v152, 0xbfb8aa3b, v98
	v_exp_f32_e32 v152, v152
	s_nop 0
	v_add_f32_e32 v152, 1.0, v152
	v_rcp_f32_e32 v154, v152
	s_nop 0
	v_mul_f32_e32 v152, v98, v154
	v_mul_f32_e32 v153, 0xbfb8aa3b, v110
	v_exp_f32_e32 v153, v153
	s_nop 0
	v_add_f32_e32 v153, 1.0, v153
	v_rcp_f32_e32 v155, v153
	s_nop 0
	v_mul_f32_e32 v153, v110, v155
	v_mul_f32_e32 v154, 0xbfb8aa3b, v106
	v_exp_f32_e32 v154, v154
	s_nop 0
	v_add_f32_e32 v154, 1.0, v154
	v_rcp_f32_e32 v156, v154
	s_nop 0
	v_mul_f32_e32 v154, v106, v156
	v_or_b32_e32 v155, 16, v0
	v_cvt_pk_bf16_f32 v153, v153, v154
	v_mad_i64_i32 v[154:155], s[22:23], s14, v155, 0
	v_cvt_pk_bf16_f32 v152, v148, v152
	v_lshl_add_u64 v[154:155], v[154:155], 1, v[142:143]
	global_store_dwordx2 v[154:155], v[152:153], off
	v_mul_f32_e32 v148, 0xbfb8aa3b, v103
	v_exp_f32_e32 v148, v148
	s_nop 0
	v_add_f32_e32 v148, 1.0, v148
	v_rcp_f32_e32 v153, v148
	s_nop 0
	v_mul_f32_e32 v148, v103, v153
	v_mul_f32_e32 v152, 0xbfb8aa3b, v99
	v_exp_f32_e32 v152, v152
	s_nop 0
	v_add_f32_e32 v152, 1.0, v152
	v_rcp_f32_e32 v154, v152
	s_nop 0
	v_mul_f32_e32 v152, v99, v154
	v_mul_f32_e32 v153, 0xbfb8aa3b, v111
	v_exp_f32_e32 v153, v153
	s_nop 0
	v_add_f32_e32 v153, 1.0, v153
	v_rcp_f32_e32 v155, v153
	s_nop 0
	v_mul_f32_e32 v153, v111, v155
	v_mul_f32_e32 v154, 0xbfb8aa3b, v107
	v_exp_f32_e32 v154, v154
	s_nop 0
	v_add_f32_e32 v154, 1.0, v154
	v_rcp_f32_e32 v156, v154
; DEVINL float sigmoidf_(float x) { return __fdividef(1.f, 1.f + __expf(-x)); }
; DEVINL float siluf_(float x) { return __fdividef(x, 1.f + __expf(-x)); }
;   DEVINL void operator()(Acc& acc, int brow, int bcol) const {
;     ...
;       _Pragma("unroll") for (int ai = 0; ai < 2; ++ai) _Pragma("unroll") for (int m = 0; m < 4; ++m) _Pragma("unroll") for (int j = 0; j < 4; ++j) {
;         const int row = brow + ai * 128 + wr * 64 + m * 16 + fq * 4 + j;
;         float v[4] = {acc[ai][0][m][0][j], acc[ai][0][m][1][j], acc[ai][1][m][0][j], acc[ai][1][m][1][j]};
;         _Pragma("unroll") for (int k = 0; k < 4; ++k) v[k] = fn == 1 ? siluf_(v[k]) : (fn == 2 ? sigmoidf_(v[k]) : (fn == 3 ? v[k] * 0.125f : v[k]));
;         *(bf16x4*)(dst + (size_t)row * ld + c0) = pack4(v[0], v[1], v[2], v[3]);
	s_nop 0
	v_mul_f32_e32 v154, v107, v156
	v_or_b32_e32 v155, 17, v0
	v_cvt_pk_bf16_f32 v153, v153, v154
	v_mad_i64_i32 v[154:155], s[22:23], s14, v155, 0
	v_cvt_pk_bf16_f32 v152, v148, v152
	v_lshl_add_u64 v[154:155], v[154:155], 1, v[142:143]
	global_store_dwordx2 v[154:155], v[152:153], off
	v_mul_f32_e32 v148, 0xbfb8aa3b, v104
	v_exp_f32_e32 v148, v148
	s_nop 0
	v_add_f32_e32 v148, 1.0, v148
	v_rcp_f32_e32 v153, v148
	s_nop 0
	v_mul_f32_e32 v148, v104, v153
	v_mul_f32_e32 v152, 0xbfb8aa3b, v100
	v_exp_f32_e32 v152, v152
	s_nop 0
	v_add_f32_e32 v152, 1.0, v152
	v_rcp_f32_e32 v154, v152
	s_nop 0
	v_mul_f32_e32 v152, v100, v154
	v_mul_f32_e32 v153, 0xbfb8aa3b, v112
	v_exp_f32_e32 v153, v153
	s_nop 0
	v_add_f32_e32 v153, 1.0, v153
	v_rcp_f32_e32 v155, v153
	s_nop 0
	v_mul_f32_e32 v153, v112, v155
	v_mul_f32_e32 v154, 0xbfb8aa3b, v108
	v_exp_f32_e32 v154, v154
	s_nop 0
	v_add_f32_e32 v154, 1.0, v154
	v_rcp_f32_e32 v156, v154
	s_nop 0
	v_mul_f32_e32 v154, v108, v156
	v_or_b32_e32 v155, 18, v0
	v_cvt_pk_bf16_f32 v153, v153, v154
	v_mad_i64_i32 v[154:155], s[22:23], s14, v155, 0
	v_cvt_pk_bf16_f32 v152, v148, v152
	v_lshl_add_u64 v[154:155], v[154:155], 1, v[142:143]
	global_store_dwordx2 v[154:155], v[152:153], off
	v_mul_f32_e32 v148, 0xbfb8aa3b, v105
	v_exp_f32_e32 v148, v148
	s_nop 0
	v_add_f32_e32 v148, 1.0, v148
	v_rcp_f32_e32 v153, v148
	s_nop 0
	v_mul_f32_e32 v148, v105, v153
	v_mul_f32_e32 v152, 0xbfb8aa3b, v101
	v_exp_f32_e32 v152, v152
	s_nop 0
	v_add_f32_e32 v152, 1.0, v152
	v_rcp_f32_e32 v154, v152
	s_nop 0
	v_mul_f32_e32 v152, v101, v154
	v_mul_f32_e32 v153, 0xbfb8aa3b, v113
	v_exp_f32_e32 v153, v153
	s_nop 0
	v_add_f32_e32 v153, 1.0, v153
	v_rcp_f32_e32 v155, v153
	s_nop 0
	v_mul_f32_e32 v153, v113, v155
	v_mul_f32_e32 v154, 0xbfb8aa3b, v109
	v_exp_f32_e32 v154, v154
	s_nop 0
	v_add_f32_e32 v154, 1.0, v154
	v_rcp_f32_e32 v156, v154
	s_nop 0
	v_mul_f32_e32 v154, v109, v156
	v_or_b32_e32 v155, 19, v0
	v_cvt_pk_bf16_f32 v153, v153, v154
	v_mad_i64_i32 v[154:155], s[22:23], s14, v155, 0
	v_cvt_pk_bf16_f32 v152, v148, v152
	v_lshl_add_u64 v[154:155], v[154:155], 1, v[142:143]
	global_store_dwordx2 v[154:155], v[152:153], off
	v_mul_f32_e32 v148, 0xbfb8aa3b, v86
	v_exp_f32_e32 v148, v148
	s_nop 0
	v_add_f32_e32 v148, 1.0, v148
	v_rcp_f32_e32 v153, v148
	s_nop 0
	v_mul_f32_e32 v148, v86, v153
	v_mul_f32_e32 v152, 0xbfb8aa3b, v82
	v_exp_f32_e32 v152, v152
	s_nop 0
	v_add_f32_e32 v152, 1.0, v152
	v_rcp_f32_e32 v154, v152
	s_nop 0
	v_mul_f32_e32 v152, v82, v154
	v_mul_f32_e32 v153, 0xbfb8aa3b, v94
	v_exp_f32_e32 v153, v153
	s_nop 0
	v_add_f32_e32 v153, 1.0, v153
	v_rcp_f32_e32 v155, v153
	s_nop 0
	v_mul_f32_e32 v153, v94, v155
	v_mul_f32_e32 v154, 0xbfb8aa3b, v90
	v_exp_f32_e32 v154, v154
	s_nop 0
	v_add_f32_e32 v154, 1.0, v154
	v_rcp_f32_e32 v156, v154
	s_nop 0
	v_mul_f32_e32 v154, v90, v156
	v_or_b32_e32 v155, 32, v0
	v_cvt_pk_bf16_f32 v153, v153, v154
	v_mad_i64_i32 v[154:155], s[22:23], s14, v155, 0
	v_cvt_pk_bf16_f32 v152, v148, v152
	v_lshl_add_u64 v[154:155], v[154:155], 1, v[142:143]
	global_store_dwordx2 v[154:155], v[152:153], off
	v_mul_f32_e32 v148, 0xbfb8aa3b, v87
	v_exp_f32_e32 v148, v148
	s_nop 0
	v_add_f32_e32 v148, 1.0, v148
	v_rcp_f32_e32 v153, v148
	s_nop 0
	v_mul_f32_e32 v148, v87, v153
	v_mul_f32_e32 v152, 0xbfb8aa3b, v83
	v_exp_f32_e32 v152, v152
	s_nop 0
	v_add_f32_e32 v152, 1.0, v152
	v_rcp_f32_e32 v154, v152
	s_nop 0
	v_mul_f32_e32 v152, v83, v154
	v_mul_f32_e32 v153, 0xbfb8aa3b, v95
	v_exp_f32_e32 v153, v153
	s_nop 0
	v_add_f32_e32 v153, 1.0, v153
	v_rcp_f32_e32 v155, v153
	s_nop 0
	v_mul_f32_e32 v153, v95, v155
	v_mul_f32_e32 v154, 0xbfb8aa3b, v91
	v_exp_f32_e32 v154, v154
	s_nop 0
	v_add_f32_e32 v154, 1.0, v154
	v_rcp_f32_e32 v156, v154
	s_nop 0
	v_mul_f32_e32 v154, v91, v156
	v_or_b32_e32 v155, 33, v0
	v_cvt_pk_bf16_f32 v153, v153, v154
	v_mad_i64_i32 v[154:155], s[22:23], s14, v155, 0
	v_cvt_pk_bf16_f32 v152, v148, v152
	v_lshl_add_u64 v[154:155], v[154:155], 1, v[142:143]
	global_store_dwordx2 v[154:155], v[152:153], off
	v_mul_f32_e32 v148, 0xbfb8aa3b, v88
	v_exp_f32_e32 v148, v148
	s_nop 0
	v_add_f32_e32 v148, 1.0, v148
	v_rcp_f32_e32 v153, v148
	s_nop 0
	v_mul_f32_e32 v148, v88, v153
	v_mul_f32_e32 v152, 0xbfb8aa3b, v84
	v_exp_f32_e32 v152, v152
	s_nop 0
	v_add_f32_e32 v152, 1.0, v152
	v_rcp_f32_e32 v154, v152
	s_nop 0
	v_mul_f32_e32 v152, v84, v154
	v_mul_f32_e32 v153, 0xbfb8aa3b, v96
	v_exp_f32_e32 v153, v153
	s_nop 0
	v_add_f32_e32 v153, 1.0, v153
	v_rcp_f32_e32 v155, v153
	s_nop 0
	v_mul_f32_e32 v153, v96, v155
	v_mul_f32_e32 v154, 0xbfb8aa3b, v92
	v_exp_f32_e32 v154, v154
	s_nop 0
	v_add_f32_e32 v154, 1.0, v154
	v_rcp_f32_e32 v156, v154
	s_nop 0
	v_mul_f32_e32 v154, v92, v156
	v_or_b32_e32 v155, 34, v0
	v_cvt_pk_bf16_f32 v153, v153, v154
	v_mad_i64_i32 v[154:155], s[22:23], s14, v155, 0
	v_cvt_pk_bf16_f32 v152, v148, v152
	v_lshl_add_u64 v[154:155], v[154:155], 1, v[142:143]
	global_store_dwordx2 v[154:155], v[152:153], off
	v_mul_f32_e32 v148, 0xbfb8aa3b, v89
	v_exp_f32_e32 v148, v148
	s_nop 0
	v_add_f32_e32 v148, 1.0, v148
	v_rcp_f32_e32 v153, v148
	s_nop 0
	v_mul_f32_e32 v148, v89, v153
	v_mul_f32_e32 v152, 0xbfb8aa3b, v85
	v_exp_f32_e32 v152, v152
	s_nop 0
	v_add_f32_e32 v152, 1.0, v152
	v_rcp_f32_e32 v154, v152
	s_nop 0
	v_mul_f32_e32 v152, v85, v154
	v_mul_f32_e32 v153, 0xbfb8aa3b, v97
	v_exp_f32_e32 v153, v153
	s_nop 0
	v_add_f32_e32 v153, 1.0, v153
	v_rcp_f32_e32 v155, v153
	s_nop 0
	v_mul_f32_e32 v153, v97, v155
	v_mul_f32_e32 v154, 0xbfb8aa3b, v93
	v_exp_f32_e32 v154, v154
	s_nop 0
	v_add_f32_e32 v154, 1.0, v154
	v_rcp_f32_e32 v156, v154
	s_nop 0
	v_mul_f32_e32 v154, v93, v156
; DEVINL float sigmoidf_(float x) { return __fdividef(1.f, 1.f + __expf(-x)); }
; DEVINL float siluf_(float x) { return __fdividef(x, 1.f + __expf(-x)); }
;   DEVINL void operator()(Acc& acc, int brow, int bcol) const {
;     ...
;       _Pragma("unroll") for (int ai = 0; ai < 2; ++ai) _Pragma("unroll") for (int m = 0; m < 4; ++m) _Pragma("unroll") for (int j = 0; j < 4; ++j) {
;         const int row = brow + ai * 128 + wr * 64 + m * 16 + fq * 4 + j;
;         float v[4] = {acc[ai][0][m][0][j], acc[ai][0][m][1][j], acc[ai][1][m][0][j], acc[ai][1][m][1][j]};
;         _Pragma("unroll") for (int k = 0; k < 4; ++k) v[k] = fn == 1 ? siluf_(v[k]) : (fn == 2 ? sigmoidf_(v[k]) : (fn == 3 ? v[k] * 0.125f : v[k]));
;         *(bf16x4*)(dst + (size_t)row * ld + c0) = pack4(v[0], v[1], v[2], v[3]);
	v_or_b32_e32 v155, 35, v0
	v_cvt_pk_bf16_f32 v153, v153, v154
	v_mad_i64_i32 v[154:155], s[22:23], s14, v155, 0
	v_cvt_pk_bf16_f32 v152, v148, v152
	v_lshl_add_u64 v[154:155], v[154:155], 1, v[142:143]
	global_store_dwordx2 v[154:155], v[152:153], off
	v_mul_f32_e32 v148, 0xbfb8aa3b, v70
	v_exp_f32_e32 v148, v148
	s_nop 0
	v_add_f32_e32 v148, 1.0, v148
	v_rcp_f32_e32 v153, v148
	s_nop 0
	v_mul_f32_e32 v148, v70, v153
	v_mul_f32_e32 v152, 0xbfb8aa3b, v66
	v_exp_f32_e32 v152, v152
	s_nop 0
	v_add_f32_e32 v152, 1.0, v152
	v_rcp_f32_e32 v154, v152
	s_nop 0
	v_mul_f32_e32 v152, v66, v154
	v_mul_f32_e32 v153, 0xbfb8aa3b, v78
	v_exp_f32_e32 v153, v153
	s_nop 0
	v_add_f32_e32 v153, 1.0, v153
	v_rcp_f32_e32 v155, v153
	s_nop 0
	v_mul_f32_e32 v153, v78, v155
	v_mul_f32_e32 v154, 0xbfb8aa3b, v74
	v_exp_f32_e32 v154, v154
	s_nop 0
	v_add_f32_e32 v154, 1.0, v154
	v_rcp_f32_e32 v156, v154
	s_nop 0
	v_mul_f32_e32 v154, v74, v156
	v_or_b32_e32 v155, 48, v0
	v_cvt_pk_bf16_f32 v153, v153, v154
	v_mad_i64_i32 v[154:155], s[22:23], s14, v155, 0
	v_cvt_pk_bf16_f32 v152, v148, v152
	v_lshl_add_u64 v[154:155], v[154:155], 1, v[142:143]
	global_store_dwordx2 v[154:155], v[152:153], off
	v_mul_f32_e32 v148, 0xbfb8aa3b, v71
	v_exp_f32_e32 v148, v148
	s_nop 0
	v_add_f32_e32 v148, 1.0, v148
	v_rcp_f32_e32 v153, v148
	s_nop 0
	v_mul_f32_e32 v148, v71, v153
	v_mul_f32_e32 v152, 0xbfb8aa3b, v67
	v_exp_f32_e32 v152, v152
	s_nop 0
	v_add_f32_e32 v152, 1.0, v152
	v_rcp_f32_e32 v154, v152
	s_nop 0
	v_mul_f32_e32 v152, v67, v154
	v_mul_f32_e32 v153, 0xbfb8aa3b, v79
	v_exp_f32_e32 v153, v153
	s_nop 0
	v_add_f32_e32 v153, 1.0, v153
	v_rcp_f32_e32 v155, v153
	s_nop 0
	v_mul_f32_e32 v153, v79, v155
	v_mul_f32_e32 v154, 0xbfb8aa3b, v75
	v_exp_f32_e32 v154, v154
	s_nop 0
	v_add_f32_e32 v154, 1.0, v154
	v_rcp_f32_e32 v156, v154
	s_nop 0
	v_mul_f32_e32 v154, v75, v156
	v_or_b32_e32 v155, 49, v0
	v_cvt_pk_bf16_f32 v153, v153, v154
	v_mad_i64_i32 v[154:155], s[22:23], s14, v155, 0
	v_cvt_pk_bf16_f32 v152, v148, v152
	v_lshl_add_u64 v[154:155], v[154:155], 1, v[142:143]
	global_store_dwordx2 v[154:155], v[152:153], off
	v_mul_f32_e32 v148, 0xbfb8aa3b, v72
	v_exp_f32_e32 v148, v148
	s_nop 0
	v_add_f32_e32 v148, 1.0, v148
	v_rcp_f32_e32 v153, v148
	s_nop 0
	v_mul_f32_e32 v148, v72, v153
	v_mul_f32_e32 v152, 0xbfb8aa3b, v68
	v_exp_f32_e32 v152, v152
	s_nop 0
	v_add_f32_e32 v152, 1.0, v152
	v_rcp_f32_e32 v154, v152
	s_nop 0
	v_mul_f32_e32 v152, v68, v154
	v_mul_f32_e32 v153, 0xbfb8aa3b, v80
	v_exp_f32_e32 v153, v153
	s_nop 0
	v_add_f32_e32 v153, 1.0, v153
	v_rcp_f32_e32 v155, v153
	s_nop 0
	v_mul_f32_e32 v153, v80, v155
	v_mul_f32_e32 v154, 0xbfb8aa3b, v76
	v_exp_f32_e32 v154, v154
	s_nop 0
	v_add_f32_e32 v154, 1.0, v154
	v_rcp_f32_e32 v156, v154
	s_nop 0
	v_mul_f32_e32 v154, v76, v156
	v_or_b32_e32 v155, 50, v0
	v_cvt_pk_bf16_f32 v153, v153, v154
	v_mad_i64_i32 v[154:155], s[22:23], s14, v155, 0
	v_cvt_pk_bf16_f32 v152, v148, v152
	v_lshl_add_u64 v[154:155], v[154:155], 1, v[142:143]
	global_store_dwordx2 v[154:155], v[152:153], off
	v_mul_f32_e32 v148, 0xbfb8aa3b, v73
	v_exp_f32_e32 v148, v148
	s_nop 0
	v_add_f32_e32 v148, 1.0, v148
	v_rcp_f32_e32 v153, v148
	s_nop 0
	v_mul_f32_e32 v148, v73, v153
	v_mul_f32_e32 v152, 0xbfb8aa3b, v69
	v_exp_f32_e32 v152, v152
	s_nop 0
	v_add_f32_e32 v152, 1.0, v152
	v_rcp_f32_e32 v154, v152
	s_nop 0
	v_mul_f32_e32 v152, v69, v154
	v_mul_f32_e32 v153, 0xbfb8aa3b, v81
	v_exp_f32_e32 v153, v153
	s_nop 0
	v_add_f32_e32 v153, 1.0, v153
	v_rcp_f32_e32 v155, v153
	s_nop 0
	v_mul_f32_e32 v153, v81, v155
	v_mul_f32_e32 v154, 0xbfb8aa3b, v77
	v_exp_f32_e32 v154, v154
	s_nop 0
	v_add_f32_e32 v154, 1.0, v154
	v_rcp_f32_e32 v156, v154
	s_nop 0
	v_mul_f32_e32 v154, v77, v156
	v_or_b32_e32 v155, 51, v0
	v_cvt_pk_bf16_f32 v153, v153, v154
	v_mad_i64_i32 v[154:155], s[22:23], s14, v155, 0
	v_cvt_pk_bf16_f32 v152, v148, v152
	v_lshl_add_u64 v[154:155], v[154:155], 1, v[142:143]
	global_store_dwordx2 v[154:155], v[152:153], off
	v_mul_f32_e32 v148, 0xbfb8aa3b, v54
	v_exp_f32_e32 v148, v148
	s_nop 0
	v_add_f32_e32 v148, 1.0, v148
	v_rcp_f32_e32 v153, v148
	s_nop 0
	v_mul_f32_e32 v148, v54, v153
	v_mul_f32_e32 v152, 0xbfb8aa3b, v50
	v_exp_f32_e32 v152, v152
	s_nop 0
	v_add_f32_e32 v152, 1.0, v152
	v_rcp_f32_e32 v154, v152
	s_nop 0
	v_mul_f32_e32 v152, v50, v154
	v_mul_f32_e32 v153, 0xbfb8aa3b, v62
	v_exp_f32_e32 v153, v153
	s_nop 0
	v_add_f32_e32 v153, 1.0, v153
	v_rcp_f32_e32 v155, v153
	s_nop 0
	v_mul_f32_e32 v153, v62, v155
	v_mul_f32_e32 v154, 0xbfb8aa3b, v58
	v_exp_f32_e32 v154, v154
	s_nop 0
	v_add_f32_e32 v154, 1.0, v154
	v_rcp_f32_e32 v156, v154
	s_nop 0
	v_mul_f32_e32 v154, v58, v156
	v_add_u32_e32 v155, 0x80, v0
	v_cvt_pk_bf16_f32 v153, v153, v154
	v_mad_i64_i32 v[154:155], s[22:23], s14, v155, 0
	v_cvt_pk_bf16_f32 v152, v148, v152
	v_lshl_add_u64 v[154:155], v[154:155], 1, v[142:143]
	global_store_dwordx2 v[154:155], v[152:153], off
	v_mul_f32_e32 v148, 0xbfb8aa3b, v55
	v_exp_f32_e32 v148, v148
	s_nop 0
	v_add_f32_e32 v148, 1.0, v148
	v_rcp_f32_e32 v153, v148
	s_nop 0
	v_mul_f32_e32 v148, v55, v153
	v_mul_f32_e32 v152, 0xbfb8aa3b, v51
	v_exp_f32_e32 v152, v152
	s_nop 0
	v_add_f32_e32 v152, 1.0, v152
	v_rcp_f32_e32 v154, v152
	s_nop 0
	v_mul_f32_e32 v152, v51, v154
	v_mul_f32_e32 v153, 0xbfb8aa3b, v63
	v_exp_f32_e32 v153, v153
	s_nop 0
	v_add_f32_e32 v153, 1.0, v153
	v_rcp_f32_e32 v155, v153
	s_nop 0
	v_mul_f32_e32 v153, v63, v155
	v_mul_f32_e32 v154, 0xbfb8aa3b, v59
	v_exp_f32_e32 v154, v154
	s_nop 0
	v_add_f32_e32 v154, 1.0, v154
	v_rcp_f32_e32 v156, v154
	s_nop 0
	v_mul_f32_e32 v154, v59, v156
	v_add_u32_e32 v155, 0x81, v0
	v_cvt_pk_bf16_f32 v153, v153, v154
; DEVINL float sigmoidf_(float x) { return __fdividef(1.f, 1.f + __expf(-x)); }
; DEVINL float siluf_(float x) { return __fdividef(x, 1.f + __expf(-x)); }
;   DEVINL void operator()(Acc& acc, int brow, int bcol) const {
;     ...
;     } else {
;       u16* dst; int ld, cbase, fn;
;       if (tt < 12)      { dst = P.sg;  ld = 1024; cbase = (tt - 8) * 256;  fn = 1; }
;       else if (tt < 14) { dst = P.qn;  ld = 512;  cbase = (tt - 12) * 256; fn = 3; }
;       else if (tt < 16) { dst = P.kn;  ld = 512;  cbase = (tt - 14) * 256; fn = 0; }
;       else if (tt < 22) { dst = P.sgr; ld = 1024; cbase = (tt - 18) * 256; fn = 2; }
;       else              { dst = P.sgn; ld = 1024; cbase = (tt - 22) * 256; fn = 2; }
;       const int c0 = cbase + wc * 64 + fr * 4;
;       _Pragma("unroll") for (int ai = 0; ai < 2; ++ai) _Pragma("unroll") for (int m = 0; m < 4; ++m) _Pragma("unroll") for (int j = 0; j < 4; ++j) {
;         const int row = brow + ai * 128 + wr * 64 + m * 16 + fq * 4 + j;
;         float v[4] = {acc[ai][0][m][0][j], acc[ai][0][m][1][j], acc[ai][1][m][0][j], acc[ai][1][m][1][j]};
;         _Pragma("unroll") for (int k = 0; k < 4; ++k) v[k] = fn == 1 ? siluf_(v[k]) : (fn == 2 ? sigmoidf_(v[k]) : (fn == 3 ? v[k] * 0.125f : v[k]));
;         *(bf16x4*)(dst + (size_t)row * ld + c0) = pack4(v[0], v[1], v[2], v[3]);
;       }
	v_mad_i64_i32 v[154:155], s[22:23], s14, v155, 0
	v_cvt_pk_bf16_f32 v152, v148, v152
	v_lshl_add_u64 v[154:155], v[154:155], 1, v[142:143]
	global_store_dwordx2 v[154:155], v[152:153], off
	v_mul_f32_e32 v148, 0xbfb8aa3b, v56
	v_exp_f32_e32 v148, v148
	s_nop 0
	v_add_f32_e32 v148, 1.0, v148
	v_rcp_f32_e32 v153, v148
	s_nop 0
	v_mul_f32_e32 v148, v56, v153
	v_mul_f32_e32 v152, 0xbfb8aa3b, v52
	v_exp_f32_e32 v152, v152
	s_nop 0
	v_add_f32_e32 v152, 1.0, v152
	v_rcp_f32_e32 v154, v152
	s_nop 0
	v_mul_f32_e32 v152, v52, v154
	v_mul_f32_e32 v153, 0xbfb8aa3b, v64
	v_exp_f32_e32 v153, v153
	s_nop 0
	v_add_f32_e32 v153, 1.0, v153
	v_rcp_f32_e32 v155, v153
	s_nop 0
	v_mul_f32_e32 v153, v64, v155
	v_mul_f32_e32 v154, 0xbfb8aa3b, v60
	v_exp_f32_e32 v154, v154
	s_nop 0
	v_add_f32_e32 v154, 1.0, v154
	v_rcp_f32_e32 v156, v154
	s_nop 0
	v_mul_f32_e32 v154, v60, v156
	v_add_u32_e32 v155, 0x82, v0
	v_cvt_pk_bf16_f32 v153, v153, v154
	v_mad_i64_i32 v[154:155], s[22:23], s14, v155, 0
	v_cvt_pk_bf16_f32 v152, v148, v152
	v_lshl_add_u64 v[154:155], v[154:155], 1, v[142:143]
	global_store_dwordx2 v[154:155], v[152:153], off
	v_mul_f32_e32 v148, 0xbfb8aa3b, v57
	v_exp_f32_e32 v148, v148
	s_nop 0
	v_add_f32_e32 v148, 1.0, v148
	v_rcp_f32_e32 v153, v148
	s_nop 0
	v_mul_f32_e32 v148, v57, v153
	v_mul_f32_e32 v152, 0xbfb8aa3b, v53
	v_exp_f32_e32 v152, v152
	s_nop 0
	v_add_f32_e32 v152, 1.0, v152
	v_rcp_f32_e32 v154, v152
	s_nop 0
	v_mul_f32_e32 v152, v53, v154
	v_mul_f32_e32 v153, 0xbfb8aa3b, v65
	v_exp_f32_e32 v153, v153
	s_nop 0
	v_add_f32_e32 v153, 1.0, v153
	v_rcp_f32_e32 v155, v153
	s_nop 0
	v_mul_f32_e32 v153, v65, v155
	v_mul_f32_e32 v154, 0xbfb8aa3b, v61
	v_exp_f32_e32 v154, v154
	s_nop 0
	v_add_f32_e32 v154, 1.0, v154
	v_rcp_f32_e32 v156, v154
	s_nop 0
	v_mul_f32_e32 v154, v61, v156
	v_add_u32_e32 v155, 0x83, v0
	v_cvt_pk_bf16_f32 v153, v153, v154
	v_mad_i64_i32 v[154:155], s[22:23], s14, v155, 0
	v_cvt_pk_bf16_f32 v152, v148, v152
	v_lshl_add_u64 v[154:155], v[154:155], 1, v[142:143]
	global_store_dwordx2 v[154:155], v[152:153], off
	v_mul_f32_e32 v148, 0xbfb8aa3b, v38
	v_exp_f32_e32 v148, v148
	s_nop 0
	v_add_f32_e32 v148, 1.0, v148
	v_rcp_f32_e32 v153, v148
	s_nop 0
	v_mul_f32_e32 v148, v38, v153
	v_mul_f32_e32 v152, 0xbfb8aa3b, v34
	v_exp_f32_e32 v152, v152
	s_nop 0
	v_add_f32_e32 v152, 1.0, v152
	v_rcp_f32_e32 v154, v152
	s_nop 0
	v_mul_f32_e32 v152, v34, v154
	v_mul_f32_e32 v153, 0xbfb8aa3b, v46
	v_exp_f32_e32 v153, v153
	s_nop 0
	v_add_f32_e32 v153, 1.0, v153
	v_rcp_f32_e32 v155, v153
	s_nop 0
	v_mul_f32_e32 v153, v46, v155
	v_mul_f32_e32 v154, 0xbfb8aa3b, v42
	v_exp_f32_e32 v154, v154
	s_nop 0
	v_add_f32_e32 v154, 1.0, v154
	v_rcp_f32_e32 v156, v154
	s_nop 0
	v_mul_f32_e32 v154, v42, v156
	v_add_u32_e32 v155, 0x90, v0
	v_cvt_pk_bf16_f32 v153, v153, v154
	v_mad_i64_i32 v[154:155], s[22:23], s14, v155, 0
	v_cvt_pk_bf16_f32 v152, v148, v152
	v_lshl_add_u64 v[154:155], v[154:155], 1, v[142:143]
	global_store_dwordx2 v[154:155], v[152:153], off
	v_mul_f32_e32 v148, 0xbfb8aa3b, v39
	v_exp_f32_e32 v148, v148
	s_nop 0
	v_add_f32_e32 v148, 1.0, v148
	v_rcp_f32_e32 v153, v148
	s_nop 0
	v_mul_f32_e32 v148, v39, v153
	v_mul_f32_e32 v152, 0xbfb8aa3b, v35
	v_exp_f32_e32 v152, v152
	s_nop 0
	v_add_f32_e32 v152, 1.0, v152
	v_rcp_f32_e32 v154, v152
	s_nop 0
	v_mul_f32_e32 v152, v35, v154
	v_mul_f32_e32 v153, 0xbfb8aa3b, v47
	v_exp_f32_e32 v153, v153
	s_nop 0
	v_add_f32_e32 v153, 1.0, v153
	v_rcp_f32_e32 v155, v153
	s_nop 0
	v_mul_f32_e32 v153, v47, v155
	v_mul_f32_e32 v154, 0xbfb8aa3b, v43
	v_exp_f32_e32 v154, v154
	s_nop 0
	v_add_f32_e32 v154, 1.0, v154
	v_rcp_f32_e32 v156, v154
	s_nop 0
	v_mul_f32_e32 v154, v43, v156
	v_add_u32_e32 v155, 0x91, v0
	v_cvt_pk_bf16_f32 v153, v153, v154
	v_mad_i64_i32 v[154:155], s[22:23], s14, v155, 0
	v_cvt_pk_bf16_f32 v152, v148, v152
	v_lshl_add_u64 v[154:155], v[154:155], 1, v[142:143]
	global_store_dwordx2 v[154:155], v[152:153], off
	v_mul_f32_e32 v148, 0xbfb8aa3b, v40
	v_exp_f32_e32 v148, v148
	s_nop 0
	v_add_f32_e32 v148, 1.0, v148
	v_rcp_f32_e32 v153, v148
	s_nop 0
	v_mul_f32_e32 v148, v40, v153
	v_mul_f32_e32 v152, 0xbfb8aa3b, v36
	v_exp_f32_e32 v152, v152
	s_nop 0
	v_add_f32_e32 v152, 1.0, v152
	v_rcp_f32_e32 v154, v152
	s_nop 0
	v_mul_f32_e32 v152, v36, v154
	v_mul_f32_e32 v153, 0xbfb8aa3b, v48
	v_exp_f32_e32 v153, v153
	s_nop 0
	v_add_f32_e32 v153, 1.0, v153
	v_rcp_f32_e32 v155, v153
	s_nop 0
	v_mul_f32_e32 v153, v48, v155
	v_mul_f32_e32 v154, 0xbfb8aa3b, v44
	v_exp_f32_e32 v154, v154
	s_nop 0
	v_add_f32_e32 v154, 1.0, v154
	v_rcp_f32_e32 v156, v154
	s_nop 0
	v_mul_f32_e32 v154, v44, v156
	v_add_u32_e32 v155, 0x92, v0
	v_cvt_pk_bf16_f32 v153, v153, v154
	v_mad_i64_i32 v[154:155], s[22:23], s14, v155, 0
	v_cvt_pk_bf16_f32 v152, v148, v152
	v_lshl_add_u64 v[154:155], v[154:155], 1, v[142:143]
	global_store_dwordx2 v[154:155], v[152:153], off
	v_mul_f32_e32 v148, 0xbfb8aa3b, v41
	v_exp_f32_e32 v148, v148
	s_nop 0
	v_add_f32_e32 v148, 1.0, v148
	v_rcp_f32_e32 v153, v148
	s_nop 0
	v_mul_f32_e32 v148, v41, v153
	v_mul_f32_e32 v152, 0xbfb8aa3b, v37
	v_exp_f32_e32 v152, v152
	s_nop 0
	v_add_f32_e32 v152, 1.0, v152
	v_rcp_f32_e32 v154, v152
	s_nop 0
	v_mul_f32_e32 v152, v37, v154
	v_mul_f32_e32 v153, 0xbfb8aa3b, v49
	v_exp_f32_e32 v153, v153
	s_nop 0
	v_add_f32_e32 v153, 1.0, v153
	v_rcp_f32_e32 v155, v153
	s_nop 0
	v_mul_f32_e32 v153, v49, v155
	v_mul_f32_e32 v154, 0xbfb8aa3b, v45
	v_exp_f32_e32 v154, v154
	s_nop 0
	v_add_f32_e32 v154, 1.0, v154
	v_rcp_f32_e32 v156, v154
	s_nop 0
	v_mul_f32_e32 v154, v45, v156
	v_add_u32_e32 v155, 0x93, v0
	v_cvt_pk_bf16_f32 v153, v153, v154
	v_mad_i64_i32 v[154:155], s[22:23], s14, v155, 0
; DEVINL float sigmoidf_(float x) { return __fdividef(1.f, 1.f + __expf(-x)); }
; DEVINL float siluf_(float x) { return __fdividef(x, 1.f + __expf(-x)); }
;   DEVINL void operator()(Acc& acc, int brow, int bcol) const {
;     ...
;     } else {
;       u16* dst; int ld, cbase, fn;
;       if (tt < 12)      { dst = P.sg;  ld = 1024; cbase = (tt - 8) * 256;  fn = 1; }
;       else if (tt < 14) { dst = P.qn;  ld = 512;  cbase = (tt - 12) * 256; fn = 3; }
;       else if (tt < 16) { dst = P.kn;  ld = 512;  cbase = (tt - 14) * 256; fn = 0; }
;       else if (tt < 22) { dst = P.sgr; ld = 1024; cbase = (tt - 18) * 256; fn = 2; }
;       else              { dst = P.sgn; ld = 1024; cbase = (tt - 22) * 256; fn = 2; }
;       const int c0 = cbase + wc * 64 + fr * 4;
;       _Pragma("unroll") for (int ai = 0; ai < 2; ++ai) _Pragma("unroll") for (int m = 0; m < 4; ++m) _Pragma("unroll") for (int j = 0; j < 4; ++j) {
;         const int row = brow + ai * 128 + wr * 64 + m * 16 + fq * 4 + j;
;         float v[4] = {acc[ai][0][m][0][j], acc[ai][0][m][1][j], acc[ai][1][m][0][j], acc[ai][1][m][1][j]};
;         _Pragma("unroll") for (int k = 0; k < 4; ++k) v[k] = fn == 1 ? siluf_(v[k]) : (fn == 2 ? sigmoidf_(v[k]) : (fn == 3 ? v[k] * 0.125f : v[k]));
;         *(bf16x4*)(dst + (size_t)row * ld + c0) = pack4(v[0], v[1], v[2], v[3]);
;       }
	v_cvt_pk_bf16_f32 v152, v148, v152
	v_lshl_add_u64 v[154:155], v[154:155], 1, v[142:143]
	global_store_dwordx2 v[154:155], v[152:153], off
	v_mul_f32_e32 v148, 0xbfb8aa3b, v22
	v_exp_f32_e32 v148, v148
	s_nop 0
	v_add_f32_e32 v148, 1.0, v148
	v_rcp_f32_e32 v153, v148
	s_nop 0
	v_mul_f32_e32 v148, v22, v153
	v_mul_f32_e32 v152, 0xbfb8aa3b, v18
	v_exp_f32_e32 v152, v152
	s_nop 0
	v_add_f32_e32 v152, 1.0, v152
	v_rcp_f32_e32 v154, v152
	s_nop 0
	v_mul_f32_e32 v152, v18, v154
	v_mul_f32_e32 v153, 0xbfb8aa3b, v30
	v_exp_f32_e32 v153, v153
	s_nop 0
	v_add_f32_e32 v153, 1.0, v153
	v_rcp_f32_e32 v155, v153
	s_nop 0
	v_mul_f32_e32 v153, v30, v155
	v_mul_f32_e32 v154, 0xbfb8aa3b, v26
	v_exp_f32_e32 v154, v154
	s_nop 0
	v_add_f32_e32 v154, 1.0, v154
	v_rcp_f32_e32 v156, v154
	s_nop 0
	v_mul_f32_e32 v154, v26, v156
	v_add_u32_e32 v155, 0xa0, v0
	v_cvt_pk_bf16_f32 v153, v153, v154
	v_mad_i64_i32 v[154:155], s[22:23], s14, v155, 0
	v_cvt_pk_bf16_f32 v152, v148, v152
	v_lshl_add_u64 v[154:155], v[154:155], 1, v[142:143]
	global_store_dwordx2 v[154:155], v[152:153], off
	v_mul_f32_e32 v148, 0xbfb8aa3b, v23
	v_exp_f32_e32 v148, v148
	s_nop 0
	v_add_f32_e32 v148, 1.0, v148
	v_rcp_f32_e32 v153, v148
	s_nop 0
	v_mul_f32_e32 v148, v23, v153
	v_mul_f32_e32 v152, 0xbfb8aa3b, v19
	v_exp_f32_e32 v152, v152
	s_nop 0
	v_add_f32_e32 v152, 1.0, v152
	v_rcp_f32_e32 v154, v152
	s_nop 0
	v_mul_f32_e32 v152, v19, v154
	v_mul_f32_e32 v153, 0xbfb8aa3b, v31
	v_exp_f32_e32 v153, v153
	s_nop 0
	v_add_f32_e32 v153, 1.0, v153
	v_rcp_f32_e32 v155, v153
	s_nop 0
	v_mul_f32_e32 v153, v31, v155
	v_mul_f32_e32 v154, 0xbfb8aa3b, v27
	v_exp_f32_e32 v154, v154
	s_nop 0
	v_add_f32_e32 v154, 1.0, v154
	v_rcp_f32_e32 v156, v154
	s_nop 0
	v_mul_f32_e32 v154, v27, v156
	v_add_u32_e32 v155, 0xa1, v0
	v_cvt_pk_bf16_f32 v153, v153, v154
	v_mad_i64_i32 v[154:155], s[22:23], s14, v155, 0
	v_cvt_pk_bf16_f32 v152, v148, v152
	v_lshl_add_u64 v[154:155], v[154:155], 1, v[142:143]
	global_store_dwordx2 v[154:155], v[152:153], off
	v_mul_f32_e32 v148, 0xbfb8aa3b, v24
	v_exp_f32_e32 v148, v148
	s_nop 0
	v_add_f32_e32 v148, 1.0, v148
	v_rcp_f32_e32 v153, v148
	s_nop 0
	v_mul_f32_e32 v148, v24, v153
	v_mul_f32_e32 v152, 0xbfb8aa3b, v20
	v_exp_f32_e32 v152, v152
	s_nop 0
	v_add_f32_e32 v152, 1.0, v152
	v_rcp_f32_e32 v154, v152
	s_nop 0
	v_mul_f32_e32 v152, v20, v154
	v_mul_f32_e32 v153, 0xbfb8aa3b, v32
	v_exp_f32_e32 v153, v153
	s_nop 0
	v_add_f32_e32 v153, 1.0, v153
	v_rcp_f32_e32 v155, v153
	s_nop 0
	v_mul_f32_e32 v153, v32, v155
	v_mul_f32_e32 v154, 0xbfb8aa3b, v28
	v_exp_f32_e32 v154, v154
	s_nop 0
	v_add_f32_e32 v154, 1.0, v154
	v_rcp_f32_e32 v156, v154
	s_nop 0
	v_mul_f32_e32 v154, v28, v156
	v_add_u32_e32 v155, 0xa2, v0
	v_cvt_pk_bf16_f32 v153, v153, v154
	v_mad_i64_i32 v[154:155], s[22:23], s14, v155, 0
	v_cvt_pk_bf16_f32 v152, v148, v152
	v_lshl_add_u64 v[154:155], v[154:155], 1, v[142:143]
	global_store_dwordx2 v[154:155], v[152:153], off
	v_mul_f32_e32 v148, 0xbfb8aa3b, v25
	v_exp_f32_e32 v148, v148
	s_nop 0
	v_add_f32_e32 v148, 1.0, v148
	v_rcp_f32_e32 v153, v148
	s_nop 0
	v_mul_f32_e32 v148, v25, v153
	v_mul_f32_e32 v152, 0xbfb8aa3b, v21
	v_exp_f32_e32 v152, v152
	s_nop 0
	v_add_f32_e32 v152, 1.0, v152
	v_rcp_f32_e32 v154, v152
	s_nop 0
	v_mul_f32_e32 v152, v21, v154
	v_mul_f32_e32 v153, 0xbfb8aa3b, v33
	v_exp_f32_e32 v153, v153
	s_nop 0
	v_add_f32_e32 v153, 1.0, v153
	v_rcp_f32_e32 v155, v153
	s_nop 0
	v_mul_f32_e32 v153, v33, v155
	v_mul_f32_e32 v154, 0xbfb8aa3b, v29
	v_exp_f32_e32 v154, v154
	s_nop 0
	v_add_f32_e32 v154, 1.0, v154
	v_rcp_f32_e32 v156, v154
	s_nop 0
	v_mul_f32_e32 v154, v29, v156
	v_add_u32_e32 v155, 0xa3, v0
	v_cvt_pk_bf16_f32 v153, v153, v154
	v_mad_i64_i32 v[154:155], s[22:23], s14, v155, 0
	v_cvt_pk_bf16_f32 v152, v148, v152
	v_lshl_add_u64 v[154:155], v[154:155], 1, v[142:143]
	global_store_dwordx2 v[154:155], v[152:153], off
	v_mul_f32_e32 v148, 0xbfb8aa3b, v6
	v_exp_f32_e32 v148, v148
	s_nop 0
	v_add_f32_e32 v148, 1.0, v148
	v_rcp_f32_e32 v153, v148
	s_nop 0
	v_mul_f32_e32 v148, v6, v153
	v_mul_f32_e32 v152, 0xbfb8aa3b, v2
	v_exp_f32_e32 v152, v152
	s_nop 0
	v_add_f32_e32 v152, 1.0, v152
	v_rcp_f32_e32 v154, v152
	s_nop 0
	v_mul_f32_e32 v152, v2, v154
	v_mul_f32_e32 v153, 0xbfb8aa3b, v14
	v_exp_f32_e32 v153, v153
	s_nop 0
	v_add_f32_e32 v153, 1.0, v153
	v_rcp_f32_e32 v155, v153
	s_nop 0
	v_mul_f32_e32 v153, v14, v155
	v_mul_f32_e32 v154, 0xbfb8aa3b, v10
	v_exp_f32_e32 v154, v154
	s_nop 0
	v_add_f32_e32 v154, 1.0, v154
	v_rcp_f32_e32 v156, v154
	s_nop 0
	v_mul_f32_e32 v154, v10, v156
	v_add_u32_e32 v155, 0xb0, v0
	v_cvt_pk_bf16_f32 v153, v153, v154
	v_mad_i64_i32 v[154:155], s[22:23], s14, v155, 0
	v_cvt_pk_bf16_f32 v152, v148, v152
	v_lshl_add_u64 v[154:155], v[154:155], 1, v[142:143]
	global_store_dwordx2 v[154:155], v[152:153], off
	v_mul_f32_e32 v148, 0xbfb8aa3b, v7
	v_exp_f32_e32 v148, v148
	s_nop 0
	v_add_f32_e32 v148, 1.0, v148
	v_rcp_f32_e32 v153, v148
	s_nop 0
	v_mul_f32_e32 v148, v7, v153
	v_mul_f32_e32 v152, 0xbfb8aa3b, v3
	v_exp_f32_e32 v152, v152
	s_nop 0
	v_add_f32_e32 v152, 1.0, v152
	v_rcp_f32_e32 v154, v152
	s_nop 0
	v_mul_f32_e32 v152, v3, v154
	v_mul_f32_e32 v153, 0xbfb8aa3b, v15
	v_exp_f32_e32 v153, v153
	s_nop 0
	v_add_f32_e32 v153, 1.0, v153
	v_rcp_f32_e32 v155, v153
	s_nop 0
	v_mul_f32_e32 v153, v15, v155
	v_mul_f32_e32 v154, 0xbfb8aa3b, v11
	v_exp_f32_e32 v154, v154
	s_nop 0
	v_add_f32_e32 v154, 1.0, v154
	v_rcp_f32_e32 v156, v154
	s_nop 0
	v_mul_f32_e32 v154, v11, v156
	v_add_u32_e32 v155, 0xb1, v0
	v_cvt_pk_bf16_f32 v153, v153, v154
	v_mad_i64_i32 v[154:155], s[22:23], s14, v155, 0
	v_cvt_pk_bf16_f32 v152, v148, v152
; DEVINL float sigmoidf_(float x) { return __fdividef(1.f, 1.f + __expf(-x)); }
; DEVINL float siluf_(float x) { return __fdividef(x, 1.f + __expf(-x)); }
;   DEVINL void operator()(Acc& acc, int brow, int bcol) const {
;     ...
;     } else {
;       u16* dst; int ld, cbase, fn;
;       if (tt < 12)      { dst = P.sg;  ld = 1024; cbase = (tt - 8) * 256;  fn = 1; }
;       else if (tt < 14) { dst = P.qn;  ld = 512;  cbase = (tt - 12) * 256; fn = 3; }
;       else if (tt < 16) { dst = P.kn;  ld = 512;  cbase = (tt - 14) * 256; fn = 0; }
;       else if (tt < 22) { dst = P.sgr; ld = 1024; cbase = (tt - 18) * 256; fn = 2; }
;       else              { dst = P.sgn; ld = 1024; cbase = (tt - 22) * 256; fn = 2; }
;       const int c0 = cbase + wc * 64 + fr * 4;
;       _Pragma("unroll") for (int ai = 0; ai < 2; ++ai) _Pragma("unroll") for (int m = 0; m < 4; ++m) _Pragma("unroll") for (int j = 0; j < 4; ++j) {
;         const int row = brow + ai * 128 + wr * 64 + m * 16 + fq * 4 + j;
;         float v[4] = {acc[ai][0][m][0][j], acc[ai][0][m][1][j], acc[ai][1][m][0][j], acc[ai][1][m][1][j]};
;         _Pragma("unroll") for (int k = 0; k < 4; ++k) v[k] = fn == 1 ? siluf_(v[k]) : (fn == 2 ? sigmoidf_(v[k]) : (fn == 3 ? v[k] * 0.125f : v[k]));
;         *(bf16x4*)(dst + (size_t)row * ld + c0) = pack4(v[0], v[1], v[2], v[3]);
;       }
	v_lshl_add_u64 v[154:155], v[154:155], 1, v[142:143]
	global_store_dwordx2 v[154:155], v[152:153], off
	v_mul_f32_e32 v148, 0xbfb8aa3b, v8
	v_exp_f32_e32 v148, v148
	s_nop 0
	v_add_f32_e32 v148, 1.0, v148
	v_rcp_f32_e32 v153, v148
	s_nop 0
	v_mul_f32_e32 v148, v8, v153
	v_mul_f32_e32 v152, 0xbfb8aa3b, v4
	v_exp_f32_e32 v152, v152
	s_nop 0
	v_add_f32_e32 v152, 1.0, v152
	v_rcp_f32_e32 v154, v152
	s_nop 0
	v_mul_f32_e32 v152, v4, v154
	v_mul_f32_e32 v153, 0xbfb8aa3b, v16
	v_exp_f32_e32 v153, v153
	s_nop 0
	v_add_f32_e32 v153, 1.0, v153
	v_rcp_f32_e32 v155, v153
	s_nop 0
	v_mul_f32_e32 v153, v16, v155
	v_mul_f32_e32 v154, 0xbfb8aa3b, v12
	v_exp_f32_e32 v154, v154
	s_nop 0
	v_add_f32_e32 v154, 1.0, v154
	v_rcp_f32_e32 v156, v154
	s_nop 0
	v_mul_f32_e32 v154, v12, v156
	v_add_u32_e32 v155, 0xb2, v0
	v_cvt_pk_bf16_f32 v153, v153, v154
	v_mad_i64_i32 v[154:155], s[22:23], s14, v155, 0
	v_cvt_pk_bf16_f32 v152, v148, v152
	v_lshl_add_u64 v[154:155], v[154:155], 1, v[142:143]
	global_store_dwordx2 v[154:155], v[152:153], off
	v_mul_f32_e32 v148, 0xbfb8aa3b, v9
	v_exp_f32_e32 v148, v148
	s_nop 0
	v_add_f32_e32 v148, 1.0, v148
	v_rcp_f32_e32 v153, v148
	s_nop 0
	v_mul_f32_e32 v148, v9, v153
	v_mul_f32_e32 v152, 0xbfb8aa3b, v5
	v_exp_f32_e32 v152, v152
	s_nop 0
	v_add_f32_e32 v152, 1.0, v152
	v_rcp_f32_e32 v154, v152
	s_nop 0
	v_mul_f32_e32 v152, v5, v154
	v_mul_f32_e32 v153, 0xbfb8aa3b, v17
	v_exp_f32_e32 v153, v153
	s_nop 0
	v_add_f32_e32 v153, 1.0, v153
	v_rcp_f32_e32 v155, v153
	s_nop 0
	v_mul_f32_e32 v153, v17, v155
	v_mul_f32_e32 v154, 0xbfb8aa3b, v13
	v_exp_f32_e32 v154, v154
	s_nop 0
	v_add_f32_e32 v154, 1.0, v154
	v_rcp_f32_e32 v156, v154
	s_nop 0
	v_mul_f32_e32 v154, v13, v156
	v_add_u32_e32 v0, 0xb3, v0
	v_cvt_pk_bf16_f32 v153, v153, v154
	v_mad_i64_i32 v[154:155], s[8:9], s14, v0, 0
	v_cvt_pk_bf16_f32 v152, v148, v152
	v_lshl_add_u64 v[142:143], v[154:155], 1, v[142:143]
	global_store_dwordx2 v[142:143], v[152:153], off
	s_branch .LBB0_445
.Lgw_sig:
	s_add_u32 s24, s88, s24
	s_addc_u32 s25, s89, s25
	v_mul_f32_e32 v0, 0xbfb8aa3b, v118
	v_exp_f32_e32 v0, v0
	s_nop 0
	v_add_f32_e32 v0, 1.0, v0
	v_rcp_f32_e32 v148, v0
	v_mul_f32_e32 v0, 0xbfb8aa3b, v114
	v_exp_f32_e32 v0, v0
	s_nop 0
	v_add_f32_e32 v0, 1.0, v0
	v_rcp_f32_e32 v152, v0
	s_load_dwordx2 s[24:25], s[24:25], 0x0
	v_mul_f32_e32 v0, 0xbfb8aa3b, v126
	v_exp_f32_e32 v0, v0
	s_nop 0
	v_add_f32_e32 v0, 1.0, v0
	v_rcp_f32_e32 v153, v0
	v_mul_f32_e32 v0, 0xbfb8aa3b, v122
	v_exp_f32_e32 v0, v0
	s_nop 0
	v_add_f32_e32 v0, 1.0, v0
	v_rcp_f32_e32 v154, v0
	s_add_i32 s13, s13, s22
	v_lshlrev_b32_e32 v0, 6, v149
	v_lshlrev_b32_e32 v142, 2, v146
	v_or3_b32 v142, v0, v142, s13
	v_lshl_add_u32 v0, v144, 6, s12
	v_lshl_or_b32 v0, v145, 2, v0
	v_ashrrev_i32_e32 v143, 31, v142
	s_waitcnt lgkmcnt(0)
	v_lshl_add_u64 v[142:143], v[142:143], 1, s[24:25]
	v_cvt_pk_bf16_f32 v153, v153, v154
	v_mad_i64_i32 v[154:155], s[22:23], s14, v0, 0
	v_cvt_pk_bf16_f32 v152, v148, v152
	v_lshl_add_u64 v[154:155], v[154:155], 1, v[142:143]
	global_store_dwordx2 v[154:155], v[152:153], off
	v_mul_f32_e32 v148, 0xbfb8aa3b, v119
	v_exp_f32_e32 v148, v148
	s_nop 0
	v_add_f32_e32 v148, 1.0, v148
	v_rcp_f32_e32 v148, v148
	v_mul_f32_e32 v152, 0xbfb8aa3b, v115
	v_exp_f32_e32 v152, v152
	s_nop 0
	v_add_f32_e32 v152, 1.0, v152
	v_rcp_f32_e32 v152, v152
	v_mul_f32_e32 v153, 0xbfb8aa3b, v127
	v_exp_f32_e32 v153, v153
	s_nop 0
	v_add_f32_e32 v153, 1.0, v153
	v_rcp_f32_e32 v153, v153
	v_mul_f32_e32 v154, 0xbfb8aa3b, v123
	v_exp_f32_e32 v154, v154
	s_nop 0
	v_add_f32_e32 v154, 1.0, v154
	v_rcp_f32_e32 v154, v154
	v_or_b32_e32 v155, 1, v0
	v_cvt_pk_bf16_f32 v153, v153, v154
	v_mad_i64_i32 v[154:155], s[22:23], s14, v155, 0
	v_cvt_pk_bf16_f32 v152, v148, v152
	v_lshl_add_u64 v[154:155], v[154:155], 1, v[142:143]
	global_store_dwordx2 v[154:155], v[152:153], off
	v_mul_f32_e32 v148, 0xbfb8aa3b, v120
	v_exp_f32_e32 v148, v148
	s_nop 0
	v_add_f32_e32 v148, 1.0, v148
	v_rcp_f32_e32 v148, v148
	v_mul_f32_e32 v152, 0xbfb8aa3b, v116
	v_exp_f32_e32 v152, v152
	s_nop 0
	v_add_f32_e32 v152, 1.0, v152
	v_rcp_f32_e32 v152, v152
	v_mul_f32_e32 v153, 0xbfb8aa3b, v128
	v_exp_f32_e32 v153, v153
	s_nop 0
	v_add_f32_e32 v153, 1.0, v153
	v_rcp_f32_e32 v153, v153
	v_mul_f32_e32 v154, 0xbfb8aa3b, v124
	v_exp_f32_e32 v154, v154
	s_nop 0
	v_add_f32_e32 v154, 1.0, v154
	v_rcp_f32_e32 v154, v154
	v_or_b32_e32 v155, 2, v0
	v_cvt_pk_bf16_f32 v153, v153, v154
	v_mad_i64_i32 v[154:155], s[22:23], s14, v155, 0
	v_cvt_pk_bf16_f32 v152, v148, v152
	v_lshl_add_u64 v[154:155], v[154:155], 1, v[142:143]
	global_store_dwordx2 v[154:155], v[152:153], off
	v_mul_f32_e32 v148, 0xbfb8aa3b, v121
	v_exp_f32_e32 v148, v148
	s_nop 0
	v_add_f32_e32 v148, 1.0, v148
	v_rcp_f32_e32 v148, v148
	v_mul_f32_e32 v152, 0xbfb8aa3b, v117
	v_exp_f32_e32 v152, v152
	s_nop 0
	v_add_f32_e32 v152, 1.0, v152
	v_rcp_f32_e32 v152, v152
	v_mul_f32_e32 v153, 0xbfb8aa3b, v129
	v_exp_f32_e32 v153, v153
	s_nop 0
	v_add_f32_e32 v153, 1.0, v153
	v_rcp_f32_e32 v153, v153
	v_mul_f32_e32 v154, 0xbfb8aa3b, v125
	v_exp_f32_e32 v154, v154
	s_nop 0
	v_add_f32_e32 v154, 1.0, v154
	v_rcp_f32_e32 v154, v154
	v_or_b32_e32 v155, 3, v0
	v_cvt_pk_bf16_f32 v153, v153, v154
	v_mad_i64_i32 v[154:155], s[22:23], s14, v155, 0
	v_cvt_pk_bf16_f32 v152, v148, v152
	v_lshl_add_u64 v[154:155], v[154:155], 1, v[142:143]
	global_store_dwordx2 v[154:155], v[152:153], off
	v_mul_f32_e32 v148, 0xbfb8aa3b, v102
	v_exp_f32_e32 v148, v148
	s_nop 0
	v_add_f32_e32 v148, 1.0, v148
	v_rcp_f32_e32 v148, v148
	v_mul_f32_e32 v152, 0xbfb8aa3b, v98
	v_exp_f32_e32 v152, v152
	s_nop 0
	v_add_f32_e32 v152, 1.0, v152
	v_rcp_f32_e32 v152, v152
; DEVINL float sigmoidf_(float x) { return __fdividef(1.f, 1.f + __expf(-x)); }
; DEVINL float siluf_(float x) { return __fdividef(x, 1.f + __expf(-x)); }
;   DEVINL void operator()(Acc& acc, int brow, int bcol) const {
;     ...
;       _Pragma("unroll") for (int ai = 0; ai < 2; ++ai) _Pragma("unroll") for (int m = 0; m < 4; ++m) _Pragma("unroll") for (int j = 0; j < 4; ++j) {
;         const int row = brow + ai * 128 + wr * 64 + m * 16 + fq * 4 + j;
;         float v[4] = {acc[ai][0][m][0][j], acc[ai][0][m][1][j], acc[ai][1][m][0][j], acc[ai][1][m][1][j]};
;         _Pragma("unroll") for (int k = 0; k < 4; ++k) v[k] = fn == 1 ? siluf_(v[k]) : (fn == 2 ? sigmoidf_(v[k]) : (fn == 3 ? v[k] * 0.125f : v[k]));
;         *(bf16x4*)(dst + (size_t)row * ld + c0) = pack4(v[0], v[1], v[2], v[3]);
;       }
	v_mul_f32_e32 v153, 0xbfb8aa3b, v110
	v_exp_f32_e32 v153, v153
	s_nop 0
	v_add_f32_e32 v153, 1.0, v153
	v_rcp_f32_e32 v153, v153
	v_mul_f32_e32 v154, 0xbfb8aa3b, v106
	v_exp_f32_e32 v154, v154
	s_nop 0
	v_add_f32_e32 v154, 1.0, v154
	v_rcp_f32_e32 v154, v154
	v_or_b32_e32 v155, 16, v0
	v_cvt_pk_bf16_f32 v153, v153, v154
	v_mad_i64_i32 v[154:155], s[22:23], s14, v155, 0
	v_cvt_pk_bf16_f32 v152, v148, v152
	v_lshl_add_u64 v[154:155], v[154:155], 1, v[142:143]
	global_store_dwordx2 v[154:155], v[152:153], off
	v_mul_f32_e32 v148, 0xbfb8aa3b, v103
	v_exp_f32_e32 v148, v148
	s_nop 0
	v_add_f32_e32 v148, 1.0, v148
	v_rcp_f32_e32 v148, v148
	v_mul_f32_e32 v152, 0xbfb8aa3b, v99
	v_exp_f32_e32 v152, v152
	s_nop 0
	v_add_f32_e32 v152, 1.0, v152
	v_rcp_f32_e32 v152, v152
	v_mul_f32_e32 v153, 0xbfb8aa3b, v111
	v_exp_f32_e32 v153, v153
	s_nop 0
	v_add_f32_e32 v153, 1.0, v153
	v_rcp_f32_e32 v153, v153
	v_mul_f32_e32 v154, 0xbfb8aa3b, v107
	v_exp_f32_e32 v154, v154
	s_nop 0
	v_add_f32_e32 v154, 1.0, v154
	v_rcp_f32_e32 v154, v154
	v_or_b32_e32 v155, 17, v0
	v_cvt_pk_bf16_f32 v153, v153, v154
	v_mad_i64_i32 v[154:155], s[22:23], s14, v155, 0
	v_cvt_pk_bf16_f32 v152, v148, v152
	v_lshl_add_u64 v[154:155], v[154:155], 1, v[142:143]
	global_store_dwordx2 v[154:155], v[152:153], off
	v_mul_f32_e32 v148, 0xbfb8aa3b, v104
	v_exp_f32_e32 v148, v148
	s_nop 0
	v_add_f32_e32 v148, 1.0, v148
	v_rcp_f32_e32 v148, v148
	v_mul_f32_e32 v152, 0xbfb8aa3b, v100
	v_exp_f32_e32 v152, v152
	s_nop 0
	v_add_f32_e32 v152, 1.0, v152
	v_rcp_f32_e32 v152, v152
	v_mul_f32_e32 v153, 0xbfb8aa3b, v112
	v_exp_f32_e32 v153, v153
	s_nop 0
	v_add_f32_e32 v153, 1.0, v153
	v_rcp_f32_e32 v153, v153
	v_mul_f32_e32 v154, 0xbfb8aa3b, v108
	v_exp_f32_e32 v154, v154
	s_nop 0
	v_add_f32_e32 v154, 1.0, v154
	v_rcp_f32_e32 v154, v154
	v_or_b32_e32 v155, 18, v0
	v_cvt_pk_bf16_f32 v153, v153, v154
	v_mad_i64_i32 v[154:155], s[22:23], s14, v155, 0
	v_cvt_pk_bf16_f32 v152, v148, v152
	v_lshl_add_u64 v[154:155], v[154:155], 1, v[142:143]
	global_store_dwordx2 v[154:155], v[152:153], off
	v_mul_f32_e32 v148, 0xbfb8aa3b, v105
	v_exp_f32_e32 v148, v148
	s_nop 0
	v_add_f32_e32 v148, 1.0, v148
	v_rcp_f32_e32 v148, v148
	v_mul_f32_e32 v152, 0xbfb8aa3b, v101
	v_exp_f32_e32 v152, v152
	s_nop 0
	v_add_f32_e32 v152, 1.0, v152
	v_rcp_f32_e32 v152, v152
	v_mul_f32_e32 v153, 0xbfb8aa3b, v113
	v_exp_f32_e32 v153, v153
	s_nop 0
	v_add_f32_e32 v153, 1.0, v153
	v_rcp_f32_e32 v153, v153
	v_mul_f32_e32 v154, 0xbfb8aa3b, v109
	v_exp_f32_e32 v154, v154
	s_nop 0
	v_add_f32_e32 v154, 1.0, v154
	v_rcp_f32_e32 v154, v154
	v_or_b32_e32 v155, 19, v0
	v_cvt_pk_bf16_f32 v153, v153, v154
	v_mad_i64_i32 v[154:155], s[22:23], s14, v155, 0
	v_cvt_pk_bf16_f32 v152, v148, v152
	v_lshl_add_u64 v[154:155], v[154:155], 1, v[142:143]
	global_store_dwordx2 v[154:155], v[152:153], off
	v_mul_f32_e32 v148, 0xbfb8aa3b, v86
	v_exp_f32_e32 v148, v148
	s_nop 0
	v_add_f32_e32 v148, 1.0, v148
	v_rcp_f32_e32 v148, v148
	v_mul_f32_e32 v152, 0xbfb8aa3b, v82
	v_exp_f32_e32 v152, v152
	s_nop 0
	v_add_f32_e32 v152, 1.0, v152
	v_rcp_f32_e32 v152, v152
	v_mul_f32_e32 v153, 0xbfb8aa3b, v94
	v_exp_f32_e32 v153, v153
	s_nop 0
	v_add_f32_e32 v153, 1.0, v153
	v_rcp_f32_e32 v153, v153
	v_mul_f32_e32 v154, 0xbfb8aa3b, v90
	v_exp_f32_e32 v154, v154
	s_nop 0
	v_add_f32_e32 v154, 1.0, v154
	v_rcp_f32_e32 v154, v154
	v_or_b32_e32 v155, 32, v0
	v_cvt_pk_bf16_f32 v153, v153, v154
	v_mad_i64_i32 v[154:155], s[22:23], s14, v155, 0
	v_cvt_pk_bf16_f32 v152, v148, v152
	v_lshl_add_u64 v[154:155], v[154:155], 1, v[142:143]
	global_store_dwordx2 v[154:155], v[152:153], off
	v_mul_f32_e32 v148, 0xbfb8aa3b, v87
	v_exp_f32_e32 v148, v148
	s_nop 0
	v_add_f32_e32 v148, 1.0, v148
	v_rcp_f32_e32 v148, v148
	v_mul_f32_e32 v152, 0xbfb8aa3b, v83
	v_exp_f32_e32 v152, v152
	s_nop 0
	v_add_f32_e32 v152, 1.0, v152
	v_rcp_f32_e32 v152, v152
	v_mul_f32_e32 v153, 0xbfb8aa3b, v95
	v_exp_f32_e32 v153, v153
	s_nop 0
	v_add_f32_e32 v153, 1.0, v153
	v_rcp_f32_e32 v153, v153
	v_mul_f32_e32 v154, 0xbfb8aa3b, v91
	v_exp_f32_e32 v154, v154
	s_nop 0
	v_add_f32_e32 v154, 1.0, v154
	v_rcp_f32_e32 v154, v154
	v_or_b32_e32 v155, 33, v0
	v_cvt_pk_bf16_f32 v153, v153, v154
	v_mad_i64_i32 v[154:155], s[22:23], s14, v155, 0
	v_cvt_pk_bf16_f32 v152, v148, v152
	v_lshl_add_u64 v[154:155], v[154:155], 1, v[142:143]
	global_store_dwordx2 v[154:155], v[152:153], off
	v_mul_f32_e32 v148, 0xbfb8aa3b, v88
	v_exp_f32_e32 v148, v148
	s_nop 0
	v_add_f32_e32 v148, 1.0, v148
	v_rcp_f32_e32 v148, v148
	v_mul_f32_e32 v152, 0xbfb8aa3b, v84
	v_exp_f32_e32 v152, v152
	s_nop 0
	v_add_f32_e32 v152, 1.0, v152
	v_rcp_f32_e32 v152, v152
	v_mul_f32_e32 v153, 0xbfb8aa3b, v96
	v_exp_f32_e32 v153, v153
	s_nop 0
	v_add_f32_e32 v153, 1.0, v153
	v_rcp_f32_e32 v153, v153
	v_mul_f32_e32 v154, 0xbfb8aa3b, v92
	v_exp_f32_e32 v154, v154
	s_nop 0
	v_add_f32_e32 v154, 1.0, v154
	v_rcp_f32_e32 v154, v154
	v_or_b32_e32 v155, 34, v0
	v_cvt_pk_bf16_f32 v153, v153, v154
	v_mad_i64_i32 v[154:155], s[22:23], s14, v155, 0
	v_cvt_pk_bf16_f32 v152, v148, v152
	v_lshl_add_u64 v[154:155], v[154:155], 1, v[142:143]
	global_store_dwordx2 v[154:155], v[152:153], off
	v_mul_f32_e32 v148, 0xbfb8aa3b, v89
	v_exp_f32_e32 v148, v148
	s_nop 0
	v_add_f32_e32 v148, 1.0, v148
	v_rcp_f32_e32 v148, v148
	v_mul_f32_e32 v152, 0xbfb8aa3b, v85
	v_exp_f32_e32 v152, v152
	s_nop 0
	v_add_f32_e32 v152, 1.0, v152
	v_rcp_f32_e32 v152, v152
	v_mul_f32_e32 v153, 0xbfb8aa3b, v97
	v_exp_f32_e32 v153, v153
	s_nop 0
	v_add_f32_e32 v153, 1.0, v153
	v_rcp_f32_e32 v153, v153
	v_mul_f32_e32 v154, 0xbfb8aa3b, v93
	v_exp_f32_e32 v154, v154
	s_nop 0
	v_add_f32_e32 v154, 1.0, v154
; DEVINL float sigmoidf_(float x) { return __fdividef(1.f, 1.f + __expf(-x)); }
; DEVINL float siluf_(float x) { return __fdividef(x, 1.f + __expf(-x)); }
;   DEVINL void operator()(Acc& acc, int brow, int bcol) const {
;     ...
;       _Pragma("unroll") for (int ai = 0; ai < 2; ++ai) _Pragma("unroll") for (int m = 0; m < 4; ++m) _Pragma("unroll") for (int j = 0; j < 4; ++j) {
;         const int row = brow + ai * 128 + wr * 64 + m * 16 + fq * 4 + j;
;         float v[4] = {acc[ai][0][m][0][j], acc[ai][0][m][1][j], acc[ai][1][m][0][j], acc[ai][1][m][1][j]};
;         _Pragma("unroll") for (int k = 0; k < 4; ++k) v[k] = fn == 1 ? siluf_(v[k]) : (fn == 2 ? sigmoidf_(v[k]) : (fn == 3 ? v[k] * 0.125f : v[k]));
;         *(bf16x4*)(dst + (size_t)row * ld + c0) = pack4(v[0], v[1], v[2], v[3]);
;       }
	v_rcp_f32_e32 v154, v154
	v_or_b32_e32 v155, 35, v0
	v_cvt_pk_bf16_f32 v153, v153, v154
	v_mad_i64_i32 v[154:155], s[22:23], s14, v155, 0
	v_cvt_pk_bf16_f32 v152, v148, v152
	v_lshl_add_u64 v[154:155], v[154:155], 1, v[142:143]
	global_store_dwordx2 v[154:155], v[152:153], off
	v_mul_f32_e32 v148, 0xbfb8aa3b, v70
	v_exp_f32_e32 v148, v148
	s_nop 0
	v_add_f32_e32 v148, 1.0, v148
	v_rcp_f32_e32 v148, v148
	v_mul_f32_e32 v152, 0xbfb8aa3b, v66
	v_exp_f32_e32 v152, v152
	s_nop 0
	v_add_f32_e32 v152, 1.0, v152
	v_rcp_f32_e32 v152, v152
	v_mul_f32_e32 v153, 0xbfb8aa3b, v78
	v_exp_f32_e32 v153, v153
	s_nop 0
	v_add_f32_e32 v153, 1.0, v153
	v_rcp_f32_e32 v153, v153
	v_mul_f32_e32 v154, 0xbfb8aa3b, v74
	v_exp_f32_e32 v154, v154
	s_nop 0
	v_add_f32_e32 v154, 1.0, v154
	v_rcp_f32_e32 v154, v154
	v_or_b32_e32 v155, 48, v0
	v_cvt_pk_bf16_f32 v153, v153, v154
	v_mad_i64_i32 v[154:155], s[22:23], s14, v155, 0
	v_cvt_pk_bf16_f32 v152, v148, v152
	v_lshl_add_u64 v[154:155], v[154:155], 1, v[142:143]
	global_store_dwordx2 v[154:155], v[152:153], off
	v_mul_f32_e32 v148, 0xbfb8aa3b, v71
	v_exp_f32_e32 v148, v148
	s_nop 0
	v_add_f32_e32 v148, 1.0, v148
	v_rcp_f32_e32 v148, v148
	v_mul_f32_e32 v152, 0xbfb8aa3b, v67
	v_exp_f32_e32 v152, v152
	s_nop 0
	v_add_f32_e32 v152, 1.0, v152
	v_rcp_f32_e32 v152, v152
	v_mul_f32_e32 v153, 0xbfb8aa3b, v79
	v_exp_f32_e32 v153, v153
	s_nop 0
	v_add_f32_e32 v153, 1.0, v153
	v_rcp_f32_e32 v153, v153
	v_mul_f32_e32 v154, 0xbfb8aa3b, v75
	v_exp_f32_e32 v154, v154
	s_nop 0
	v_add_f32_e32 v154, 1.0, v154
	v_rcp_f32_e32 v154, v154
	v_or_b32_e32 v155, 49, v0
	v_cvt_pk_bf16_f32 v153, v153, v154
	v_mad_i64_i32 v[154:155], s[22:23], s14, v155, 0
	v_cvt_pk_bf16_f32 v152, v148, v152
	v_lshl_add_u64 v[154:155], v[154:155], 1, v[142:143]
	global_store_dwordx2 v[154:155], v[152:153], off
	v_mul_f32_e32 v148, 0xbfb8aa3b, v72
	v_exp_f32_e32 v148, v148
	s_nop 0
	v_add_f32_e32 v148, 1.0, v148
	v_rcp_f32_e32 v148, v148
	v_mul_f32_e32 v152, 0xbfb8aa3b, v68
	v_exp_f32_e32 v152, v152
	s_nop 0
	v_add_f32_e32 v152, 1.0, v152
	v_rcp_f32_e32 v152, v152
	v_mul_f32_e32 v153, 0xbfb8aa3b, v80
	v_exp_f32_e32 v153, v153
	s_nop 0
	v_add_f32_e32 v153, 1.0, v153
	v_rcp_f32_e32 v153, v153
	v_mul_f32_e32 v154, 0xbfb8aa3b, v76
	v_exp_f32_e32 v154, v154
	s_nop 0
	v_add_f32_e32 v154, 1.0, v154
	v_rcp_f32_e32 v154, v154
	v_or_b32_e32 v155, 50, v0
	v_cvt_pk_bf16_f32 v153, v153, v154
	v_mad_i64_i32 v[154:155], s[22:23], s14, v155, 0
	v_cvt_pk_bf16_f32 v152, v148, v152
	v_lshl_add_u64 v[154:155], v[154:155], 1, v[142:143]
	global_store_dwordx2 v[154:155], v[152:153], off
	v_mul_f32_e32 v148, 0xbfb8aa3b, v73
	v_exp_f32_e32 v148, v148
	s_nop 0
	v_add_f32_e32 v148, 1.0, v148
	v_rcp_f32_e32 v148, v148
	v_mul_f32_e32 v152, 0xbfb8aa3b, v69
	v_exp_f32_e32 v152, v152
	s_nop 0
	v_add_f32_e32 v152, 1.0, v152
	v_rcp_f32_e32 v152, v152
	v_mul_f32_e32 v153, 0xbfb8aa3b, v81
	v_exp_f32_e32 v153, v153
	s_nop 0
	v_add_f32_e32 v153, 1.0, v153
	v_rcp_f32_e32 v153, v153
	v_mul_f32_e32 v154, 0xbfb8aa3b, v77
	v_exp_f32_e32 v154, v154
	s_nop 0
	v_add_f32_e32 v154, 1.0, v154
	v_rcp_f32_e32 v154, v154
	v_or_b32_e32 v155, 51, v0
	v_cvt_pk_bf16_f32 v153, v153, v154
	v_mad_i64_i32 v[154:155], s[22:23], s14, v155, 0
	v_cvt_pk_bf16_f32 v152, v148, v152
	v_lshl_add_u64 v[154:155], v[154:155], 1, v[142:143]
	global_store_dwordx2 v[154:155], v[152:153], off
	v_mul_f32_e32 v148, 0xbfb8aa3b, v54
	v_exp_f32_e32 v148, v148
	s_nop 0
	v_add_f32_e32 v148, 1.0, v148
	v_rcp_f32_e32 v148, v148
	v_mul_f32_e32 v152, 0xbfb8aa3b, v50
	v_exp_f32_e32 v152, v152
	s_nop 0
	v_add_f32_e32 v152, 1.0, v152
	v_rcp_f32_e32 v152, v152
	v_mul_f32_e32 v153, 0xbfb8aa3b, v62
	v_exp_f32_e32 v153, v153
	s_nop 0
	v_add_f32_e32 v153, 1.0, v153
	v_rcp_f32_e32 v153, v153
	v_mul_f32_e32 v154, 0xbfb8aa3b, v58
	v_exp_f32_e32 v154, v154
	s_nop 0
	v_add_f32_e32 v154, 1.0, v154
	v_rcp_f32_e32 v154, v154
	v_add_u32_e32 v155, 0x80, v0
	v_cvt_pk_bf16_f32 v153, v153, v154
	v_mad_i64_i32 v[154:155], s[22:23], s14, v155, 0
	v_cvt_pk_bf16_f32 v152, v148, v152
	v_lshl_add_u64 v[154:155], v[154:155], 1, v[142:143]
	global_store_dwordx2 v[154:155], v[152:153], off
	v_mul_f32_e32 v148, 0xbfb8aa3b, v55
	v_exp_f32_e32 v148, v148
	s_nop 0
	v_add_f32_e32 v148, 1.0, v148
	v_rcp_f32_e32 v148, v148
	v_mul_f32_e32 v152, 0xbfb8aa3b, v51
	v_exp_f32_e32 v152, v152
	s_nop 0
	v_add_f32_e32 v152, 1.0, v152
	v_rcp_f32_e32 v152, v152
	v_mul_f32_e32 v153, 0xbfb8aa3b, v63
	v_exp_f32_e32 v153, v153
	s_nop 0
	v_add_f32_e32 v153, 1.0, v153
	v_rcp_f32_e32 v153, v153
	v_mul_f32_e32 v154, 0xbfb8aa3b, v59
	v_exp_f32_e32 v154, v154
	s_nop 0
	v_add_f32_e32 v154, 1.0, v154
	v_rcp_f32_e32 v154, v154
	v_add_u32_e32 v155, 0x81, v0
	v_cvt_pk_bf16_f32 v153, v153, v154
	v_mad_i64_i32 v[154:155], s[22:23], s14, v155, 0
	v_cvt_pk_bf16_f32 v152, v148, v152
	v_lshl_add_u64 v[154:155], v[154:155], 1, v[142:143]
	global_store_dwordx2 v[154:155], v[152:153], off
	v_mul_f32_e32 v148, 0xbfb8aa3b, v56
	v_exp_f32_e32 v148, v148
	s_nop 0
	v_add_f32_e32 v148, 1.0, v148
	v_rcp_f32_e32 v148, v148
	v_mul_f32_e32 v152, 0xbfb8aa3b, v52
	v_exp_f32_e32 v152, v152
	s_nop 0
	v_add_f32_e32 v152, 1.0, v152
	v_rcp_f32_e32 v152, v152
	v_mul_f32_e32 v153, 0xbfb8aa3b, v64
	v_exp_f32_e32 v153, v153
	s_nop 0
	v_add_f32_e32 v153, 1.0, v153
	v_rcp_f32_e32 v153, v153
	v_mul_f32_e32 v154, 0xbfb8aa3b, v60
	v_exp_f32_e32 v154, v154
	s_nop 0
	v_add_f32_e32 v154, 1.0, v154
	v_rcp_f32_e32 v154, v154
	v_add_u32_e32 v155, 0x82, v0
	v_cvt_pk_bf16_f32 v153, v153, v154
	v_mad_i64_i32 v[154:155], s[22:23], s14, v155, 0
	v_cvt_pk_bf16_f32 v152, v148, v152
	v_lshl_add_u64 v[154:155], v[154:155], 1, v[142:143]
; DEVINL float sigmoidf_(float x) { return __fdividef(1.f, 1.f + __expf(-x)); }
; DEVINL float siluf_(float x) { return __fdividef(x, 1.f + __expf(-x)); }
;   DEVINL void operator()(Acc& acc, int brow, int bcol) const {
;     ...
;       _Pragma("unroll") for (int ai = 0; ai < 2; ++ai) _Pragma("unroll") for (int m = 0; m < 4; ++m) _Pragma("unroll") for (int j = 0; j < 4; ++j) {
;         const int row = brow + ai * 128 + wr * 64 + m * 16 + fq * 4 + j;
;         float v[4] = {acc[ai][0][m][0][j], acc[ai][0][m][1][j], acc[ai][1][m][0][j], acc[ai][1][m][1][j]};
;         _Pragma("unroll") for (int k = 0; k < 4; ++k) v[k] = fn == 1 ? siluf_(v[k]) : (fn == 2 ? sigmoidf_(v[k]) : (fn == 3 ? v[k] * 0.125f : v[k]));
;         *(bf16x4*)(dst + (size_t)row * ld + c0) = pack4(v[0], v[1], v[2], v[3]);
;       }
	global_store_dwordx2 v[154:155], v[152:153], off
	v_mul_f32_e32 v148, 0xbfb8aa3b, v57
	v_exp_f32_e32 v148, v148
	s_nop 0
	v_add_f32_e32 v148, 1.0, v148
	v_rcp_f32_e32 v148, v148
	v_mul_f32_e32 v152, 0xbfb8aa3b, v53
	v_exp_f32_e32 v152, v152
	s_nop 0
	v_add_f32_e32 v152, 1.0, v152
	v_rcp_f32_e32 v152, v152
	v_mul_f32_e32 v153, 0xbfb8aa3b, v65
	v_exp_f32_e32 v153, v153
	s_nop 0
	v_add_f32_e32 v153, 1.0, v153
	v_rcp_f32_e32 v153, v153
	v_mul_f32_e32 v154, 0xbfb8aa3b, v61
	v_exp_f32_e32 v154, v154
	s_nop 0
	v_add_f32_e32 v154, 1.0, v154
	v_rcp_f32_e32 v154, v154
	v_add_u32_e32 v155, 0x83, v0
	v_cvt_pk_bf16_f32 v153, v153, v154
	v_mad_i64_i32 v[154:155], s[22:23], s14, v155, 0
	v_cvt_pk_bf16_f32 v152, v148, v152
	v_lshl_add_u64 v[154:155], v[154:155], 1, v[142:143]
	global_store_dwordx2 v[154:155], v[152:153], off
	v_mul_f32_e32 v148, 0xbfb8aa3b, v38
	v_exp_f32_e32 v148, v148
	s_nop 0
	v_add_f32_e32 v148, 1.0, v148
	v_rcp_f32_e32 v148, v148
	v_mul_f32_e32 v152, 0xbfb8aa3b, v34
	v_exp_f32_e32 v152, v152
	s_nop 0
	v_add_f32_e32 v152, 1.0, v152
	v_rcp_f32_e32 v152, v152
	v_mul_f32_e32 v153, 0xbfb8aa3b, v46
	v_exp_f32_e32 v153, v153
	s_nop 0
	v_add_f32_e32 v153, 1.0, v153
	v_rcp_f32_e32 v153, v153
	v_mul_f32_e32 v154, 0xbfb8aa3b, v42
	v_exp_f32_e32 v154, v154
	s_nop 0
	v_add_f32_e32 v154, 1.0, v154
	v_rcp_f32_e32 v154, v154
	v_add_u32_e32 v155, 0x90, v0
	v_cvt_pk_bf16_f32 v153, v153, v154
	v_mad_i64_i32 v[154:155], s[22:23], s14, v155, 0
	v_cvt_pk_bf16_f32 v152, v148, v152
	v_lshl_add_u64 v[154:155], v[154:155], 1, v[142:143]
	global_store_dwordx2 v[154:155], v[152:153], off
	v_mul_f32_e32 v148, 0xbfb8aa3b, v39
	v_exp_f32_e32 v148, v148
	s_nop 0
	v_add_f32_e32 v148, 1.0, v148
	v_rcp_f32_e32 v148, v148
	v_mul_f32_e32 v152, 0xbfb8aa3b, v35
	v_exp_f32_e32 v152, v152
	s_nop 0
	v_add_f32_e32 v152, 1.0, v152
	v_rcp_f32_e32 v152, v152
	v_mul_f32_e32 v153, 0xbfb8aa3b, v47
	v_exp_f32_e32 v153, v153
	s_nop 0
	v_add_f32_e32 v153, 1.0, v153
	v_rcp_f32_e32 v153, v153
	v_mul_f32_e32 v154, 0xbfb8aa3b, v43
	v_exp_f32_e32 v154, v154
	s_nop 0
	v_add_f32_e32 v154, 1.0, v154
	v_rcp_f32_e32 v154, v154
	v_add_u32_e32 v155, 0x91, v0
	v_cvt_pk_bf16_f32 v153, v153, v154
	v_mad_i64_i32 v[154:155], s[22:23], s14, v155, 0
	v_cvt_pk_bf16_f32 v152, v148, v152
	v_lshl_add_u64 v[154:155], v[154:155], 1, v[142:143]
	global_store_dwordx2 v[154:155], v[152:153], off
	v_mul_f32_e32 v148, 0xbfb8aa3b, v40
	v_exp_f32_e32 v148, v148
	s_nop 0
	v_add_f32_e32 v148, 1.0, v148
	v_rcp_f32_e32 v148, v148
	v_mul_f32_e32 v152, 0xbfb8aa3b, v36
	v_exp_f32_e32 v152, v152
	s_nop 0
	v_add_f32_e32 v152, 1.0, v152
	v_rcp_f32_e32 v152, v152
	v_mul_f32_e32 v153, 0xbfb8aa3b, v48
	v_exp_f32_e32 v153, v153
	s_nop 0
	v_add_f32_e32 v153, 1.0, v153
	v_rcp_f32_e32 v153, v153
	v_mul_f32_e32 v154, 0xbfb8aa3b, v44
	v_exp_f32_e32 v154, v154
	s_nop 0
	v_add_f32_e32 v154, 1.0, v154
	v_rcp_f32_e32 v154, v154
	v_add_u32_e32 v155, 0x92, v0
	v_cvt_pk_bf16_f32 v153, v153, v154
	v_mad_i64_i32 v[154:155], s[22:23], s14, v155, 0
	v_cvt_pk_bf16_f32 v152, v148, v152
	v_lshl_add_u64 v[154:155], v[154:155], 1, v[142:143]
	global_store_dwordx2 v[154:155], v[152:153], off
	v_mul_f32_e32 v148, 0xbfb8aa3b, v41
	v_exp_f32_e32 v148, v148
	s_nop 0
	v_add_f32_e32 v148, 1.0, v148
	v_rcp_f32_e32 v148, v148
	v_mul_f32_e32 v152, 0xbfb8aa3b, v37
	v_exp_f32_e32 v152, v152
	s_nop 0
	v_add_f32_e32 v152, 1.0, v152
	v_rcp_f32_e32 v152, v152
	v_mul_f32_e32 v153, 0xbfb8aa3b, v49
	v_exp_f32_e32 v153, v153
	s_nop 0
	v_add_f32_e32 v153, 1.0, v153
	v_rcp_f32_e32 v153, v153
	v_mul_f32_e32 v154, 0xbfb8aa3b, v45
	v_exp_f32_e32 v154, v154
	s_nop 0
	v_add_f32_e32 v154, 1.0, v154
	v_rcp_f32_e32 v154, v154
	v_add_u32_e32 v155, 0x93, v0
	v_cvt_pk_bf16_f32 v153, v153, v154
	v_mad_i64_i32 v[154:155], s[22:23], s14, v155, 0
	v_cvt_pk_bf16_f32 v152, v148, v152
	v_lshl_add_u64 v[154:155], v[154:155], 1, v[142:143]
	global_store_dwordx2 v[154:155], v[152:153], off
	v_mul_f32_e32 v148, 0xbfb8aa3b, v22
	v_exp_f32_e32 v148, v148
	s_nop 0
	v_add_f32_e32 v148, 1.0, v148
	v_rcp_f32_e32 v148, v148
	v_mul_f32_e32 v152, 0xbfb8aa3b, v18
	v_exp_f32_e32 v152, v152
	s_nop 0
	v_add_f32_e32 v152, 1.0, v152
	v_rcp_f32_e32 v152, v152
	v_mul_f32_e32 v153, 0xbfb8aa3b, v30
	v_exp_f32_e32 v153, v153
	s_nop 0
	v_add_f32_e32 v153, 1.0, v153
	v_rcp_f32_e32 v153, v153
	v_mul_f32_e32 v154, 0xbfb8aa3b, v26
	v_exp_f32_e32 v154, v154
	s_nop 0
	v_add_f32_e32 v154, 1.0, v154
	v_rcp_f32_e32 v154, v154
	v_add_u32_e32 v155, 0xa0, v0
	v_cvt_pk_bf16_f32 v153, v153, v154
	v_mad_i64_i32 v[154:155], s[22:23], s14, v155, 0
	v_cvt_pk_bf16_f32 v152, v148, v152
	v_lshl_add_u64 v[154:155], v[154:155], 1, v[142:143]
	global_store_dwordx2 v[154:155], v[152:153], off
	v_mul_f32_e32 v148, 0xbfb8aa3b, v23
	v_exp_f32_e32 v148, v148
	s_nop 0
	v_add_f32_e32 v148, 1.0, v148
	v_rcp_f32_e32 v148, v148
	v_mul_f32_e32 v152, 0xbfb8aa3b, v19
	v_exp_f32_e32 v152, v152
	s_nop 0
	v_add_f32_e32 v152, 1.0, v152
	v_rcp_f32_e32 v152, v152
	v_mul_f32_e32 v153, 0xbfb8aa3b, v31
	v_exp_f32_e32 v153, v153
	s_nop 0
	v_add_f32_e32 v153, 1.0, v153
; DEVINL float sigmoidf_(float x) { return __fdividef(1.f, 1.f + __expf(-x)); }
; DEVINL float siluf_(float x) { return __fdividef(x, 1.f + __expf(-x)); }
;   DEVINL void operator()(Acc& acc, int brow, int bcol) const {
;     ...
;       _Pragma("unroll") for (int ai = 0; ai < 2; ++ai) _Pragma("unroll") for (int m = 0; m < 4; ++m) _Pragma("unroll") for (int j = 0; j < 4; ++j) {
;         const int row = brow + ai * 128 + wr * 64 + m * 16 + fq * 4 + j;
;         float v[4] = {acc[ai][0][m][0][j], acc[ai][0][m][1][j], acc[ai][1][m][0][j], acc[ai][1][m][1][j]};
;         _Pragma("unroll") for (int k = 0; k < 4; ++k) v[k] = fn == 1 ? siluf_(v[k]) : (fn == 2 ? sigmoidf_(v[k]) : (fn == 3 ? v[k] * 0.125f : v[k]));
;         *(bf16x4*)(dst + (size_t)row * ld + c0) = pack4(v[0], v[1], v[2], v[3]);
;       }
	v_rcp_f32_e32 v153, v153
	v_mul_f32_e32 v154, 0xbfb8aa3b, v27
	v_exp_f32_e32 v154, v154
	s_nop 0
	v_add_f32_e32 v154, 1.0, v154
	v_rcp_f32_e32 v154, v154
	v_add_u32_e32 v155, 0xa1, v0
	v_cvt_pk_bf16_f32 v153, v153, v154
	v_mad_i64_i32 v[154:155], s[22:23], s14, v155, 0
	v_cvt_pk_bf16_f32 v152, v148, v152
	v_lshl_add_u64 v[154:155], v[154:155], 1, v[142:143]
	global_store_dwordx2 v[154:155], v[152:153], off
	v_mul_f32_e32 v148, 0xbfb8aa3b, v24
	v_exp_f32_e32 v148, v148
	s_nop 0
	v_add_f32_e32 v148, 1.0, v148
	v_rcp_f32_e32 v148, v148
	v_mul_f32_e32 v152, 0xbfb8aa3b, v20
	v_exp_f32_e32 v152, v152
	s_nop 0
	v_add_f32_e32 v152, 1.0, v152
	v_rcp_f32_e32 v152, v152
	v_mul_f32_e32 v153, 0xbfb8aa3b, v32
	v_exp_f32_e32 v153, v153
	s_nop 0
	v_add_f32_e32 v153, 1.0, v153
	v_rcp_f32_e32 v153, v153
	v_mul_f32_e32 v154, 0xbfb8aa3b, v28
	v_exp_f32_e32 v154, v154
	s_nop 0
	v_add_f32_e32 v154, 1.0, v154
	v_rcp_f32_e32 v154, v154
	v_add_u32_e32 v155, 0xa2, v0
	v_cvt_pk_bf16_f32 v153, v153, v154
	v_mad_i64_i32 v[154:155], s[22:23], s14, v155, 0
	v_cvt_pk_bf16_f32 v152, v148, v152
	v_lshl_add_u64 v[154:155], v[154:155], 1, v[142:143]
	global_store_dwordx2 v[154:155], v[152:153], off
	v_mul_f32_e32 v148, 0xbfb8aa3b, v25
	v_exp_f32_e32 v148, v148
	s_nop 0
	v_add_f32_e32 v148, 1.0, v148
	v_rcp_f32_e32 v148, v148
	v_mul_f32_e32 v152, 0xbfb8aa3b, v21
	v_exp_f32_e32 v152, v152
	s_nop 0
	v_add_f32_e32 v152, 1.0, v152
	v_rcp_f32_e32 v152, v152
	v_mul_f32_e32 v153, 0xbfb8aa3b, v33
	v_exp_f32_e32 v153, v153
	s_nop 0
	v_add_f32_e32 v153, 1.0, v153
	v_rcp_f32_e32 v153, v153
	v_mul_f32_e32 v154, 0xbfb8aa3b, v29
	v_exp_f32_e32 v154, v154
	s_nop 0
	v_add_f32_e32 v154, 1.0, v154
	v_rcp_f32_e32 v154, v154
	v_add_u32_e32 v155, 0xa3, v0
	v_cvt_pk_bf16_f32 v153, v153, v154
	v_mad_i64_i32 v[154:155], s[22:23], s14, v155, 0
	v_cvt_pk_bf16_f32 v152, v148, v152
	v_lshl_add_u64 v[154:155], v[154:155], 1, v[142:143]
	global_store_dwordx2 v[154:155], v[152:153], off
	v_mul_f32_e32 v148, 0xbfb8aa3b, v6
	v_exp_f32_e32 v148, v148
	s_nop 0
	v_add_f32_e32 v148, 1.0, v148
	v_rcp_f32_e32 v148, v148
	v_mul_f32_e32 v152, 0xbfb8aa3b, v2
	v_exp_f32_e32 v152, v152
	s_nop 0
	v_add_f32_e32 v152, 1.0, v152
	v_rcp_f32_e32 v152, v152
	v_mul_f32_e32 v153, 0xbfb8aa3b, v14
	v_exp_f32_e32 v153, v153
	s_nop 0
	v_add_f32_e32 v153, 1.0, v153
	v_rcp_f32_e32 v153, v153
	v_mul_f32_e32 v154, 0xbfb8aa3b, v10
	v_exp_f32_e32 v154, v154
	s_nop 0
	v_add_f32_e32 v154, 1.0, v154
	v_rcp_f32_e32 v154, v154
	v_add_u32_e32 v155, 0xb0, v0
	v_cvt_pk_bf16_f32 v153, v153, v154
	v_mad_i64_i32 v[154:155], s[22:23], s14, v155, 0
	v_cvt_pk_bf16_f32 v152, v148, v152
	v_lshl_add_u64 v[154:155], v[154:155], 1, v[142:143]
	global_store_dwordx2 v[154:155], v[152:153], off
	v_mul_f32_e32 v148, 0xbfb8aa3b, v7
	v_exp_f32_e32 v148, v148
	s_nop 0
	v_add_f32_e32 v148, 1.0, v148
	v_rcp_f32_e32 v148, v148
	v_mul_f32_e32 v152, 0xbfb8aa3b, v3
	v_exp_f32_e32 v152, v152
	s_nop 0
	v_add_f32_e32 v152, 1.0, v152
	v_rcp_f32_e32 v152, v152
	v_mul_f32_e32 v153, 0xbfb8aa3b, v15
	v_exp_f32_e32 v153, v153
	s_nop 0
	v_add_f32_e32 v153, 1.0, v153
	v_rcp_f32_e32 v153, v153
	v_mul_f32_e32 v154, 0xbfb8aa3b, v11
	v_exp_f32_e32 v154, v154
	s_nop 0
	v_add_f32_e32 v154, 1.0, v154
	v_rcp_f32_e32 v154, v154
	v_add_u32_e32 v155, 0xb1, v0
	v_cvt_pk_bf16_f32 v153, v153, v154
	v_mad_i64_i32 v[154:155], s[22:23], s14, v155, 0
	v_cvt_pk_bf16_f32 v152, v148, v152
	v_lshl_add_u64 v[154:155], v[154:155], 1, v[142:143]
	global_store_dwordx2 v[154:155], v[152:153], off
	v_mul_f32_e32 v148, 0xbfb8aa3b, v8
	v_exp_f32_e32 v148, v148
	s_nop 0
	v_add_f32_e32 v148, 1.0, v148
	v_rcp_f32_e32 v148, v148
	v_mul_f32_e32 v152, 0xbfb8aa3b, v4
	v_exp_f32_e32 v152, v152
	s_nop 0
	v_add_f32_e32 v152, 1.0, v152
	v_rcp_f32_e32 v152, v152
	v_mul_f32_e32 v153, 0xbfb8aa3b, v16
	v_exp_f32_e32 v153, v153
	s_nop 0
	v_add_f32_e32 v153, 1.0, v153
	v_rcp_f32_e32 v153, v153
	v_mul_f32_e32 v154, 0xbfb8aa3b, v12
	v_exp_f32_e32 v154, v154
	s_nop 0
	v_add_f32_e32 v154, 1.0, v154
	v_rcp_f32_e32 v154, v154
	v_add_u32_e32 v155, 0xb2, v0
	v_cvt_pk_bf16_f32 v153, v153, v154
	v_mad_i64_i32 v[154:155], s[22:23], s14, v155, 0
	v_cvt_pk_bf16_f32 v152, v148, v152
	v_lshl_add_u64 v[154:155], v[154:155], 1, v[142:143]
	global_store_dwordx2 v[154:155], v[152:153], off
	v_mul_f32_e32 v148, 0xbfb8aa3b, v9
	v_exp_f32_e32 v148, v148
	s_nop 0
	v_add_f32_e32 v148, 1.0, v148
	v_rcp_f32_e32 v148, v148
	v_mul_f32_e32 v152, 0xbfb8aa3b, v5
	v_exp_f32_e32 v152, v152
	s_nop 0
	v_add_f32_e32 v152, 1.0, v152
	v_rcp_f32_e32 v152, v152
	v_mul_f32_e32 v153, 0xbfb8aa3b, v17
	v_exp_f32_e32 v153, v153
	s_nop 0
	v_add_f32_e32 v153, 1.0, v153
	v_rcp_f32_e32 v153, v153
	v_mul_f32_e32 v154, 0xbfb8aa3b, v13
	v_exp_f32_e32 v154, v154
	s_nop 0
	v_add_f32_e32 v154, 1.0, v154
	v_rcp_f32_e32 v154, v154
	v_add_u32_e32 v0, 0xb3, v0
	v_cvt_pk_bf16_f32 v153, v153, v154
	v_mad_i64_i32 v[154:155], s[8:9], s14, v0, 0
	v_cvt_pk_bf16_f32 v152, v148, v152
	v_lshl_add_u64 v[142:143], v[154:155], 1, v[142:143]
	global_store_dwordx2 v[142:143], v[152:153], off
	s_branch .LBB0_445

; DEVINL unsigned pack2(float a, float b) { hf2 v = {a, b}; hbf2 r = __builtin_convertvector(v, hbf2); return __builtin_bit_cast(unsigned, r); }
; DEVINL float sigmoidf_(float x) { return __fdividef(1.f, 1.f + __expf(-x)); }
; DEVINL float siluf_(float x) { return __fdividef(x, 1.f + __expf(-x)); }
;   DEVINL void operator()(Acc& acc, int brow, int bcol) const {
;     ...
;         if (isq) {
;           _Pragma("unroll") for (int j = 0; j < 4; ++j) {
;             const int row = row0 + j, nl = row & 127;
;             const size_t o = (size_t)row * 512 + head * 128 + i0;
;             *(unsigned*)(P.q + o) = pack2(o1[0][j], o1[1][j]); *(unsigned*)(P.q + o + 64) = pack2(o2[0][j], o2[1][j]);
;           }
;     ...
;       _Pragma("unroll") for (int ai = 0; ai < 2; ++ai) _Pragma("unroll") for (int m = 0; m < 4; ++m) _Pragma("unroll") for (int j = 0; j < 4; ++j) {
;         const int row = brow + ai * 128 + wr * 64 + m * 16 + fq * 4 + j;
;         float v[4] = {acc[ai][0][m][0][j], acc[ai][0][m][1][j], acc[ai][1][m][0][j], acc[ai][1][m][1][j]};
;         _Pragma("unroll") for (int k = 0; k < 4; ++k) v[k] = fn == 1 ? siluf_(v[k]) : (fn == 2 ? sigmoidf_(v[k]) : (fn == 3 ? v[k] * 0.125f : v[k]));
;         *(bf16x4*)(dst + (size_t)row * ld + c0) = pack4(v[0], v[1], v[2], v[3]);
;       }
.LBB0_794:
	s_andn2_b64 vcc, exec, s[10:11]
	s_cbranch_vccnz .LBB0_445
	s_load_dwordx2 s[8:9], s[88:89], 0x178
	v_mov_b32_e32 v115, v1
	v_lshlrev_b64 v[12:13], 10, v[18:19]
	v_cvt_pk_bf16_f32 v22, v22, v23
	v_cvt_pk_bf16_f32 v18, v20, v21
	s_waitcnt lgkmcnt(0)
	v_lshl_add_u64 v[16:17], s[8:9], 0, v[0:1]
	v_lshl_add_u64 v[16:17], v[16:17], 0, v[114:115]
	v_cvt_pk_bf16_f32 v0, v6, v7
	v_lshlrev_b64 v[6:7], 10, v[24:25]
	v_lshl_add_u64 v[12:13], v[16:17], 0, v[12:13]
	v_lshl_add_u64 v[6:7], v[16:17], 0, v[6:7]
	global_store_dword v[12:13], v22, off
	global_store_dword v[12:13], v18, off offset:128
	global_store_dword v[6:7], v0, off
	v_cvt_pk_bf16_f32 v0, v2, v3
	v_lshlrev_b64 v[2:3], 10, v[10:11]
	global_store_dword v[6:7], v0, off offset:128
	v_cvt_pk_bf16_f32 v0, v26, v27
	v_lshl_add_u64 v[2:3], v[16:17], 0, v[2:3]
	global_store_dword v[2:3], v0, off
	v_cvt_pk_bf16_f32 v0, v14, v15
	global_store_dword v[2:3], v0, off offset:128
	v_lshlrev_b64 v[2:3], 10, v[28:29]
	v_cvt_pk_bf16_f32 v0, v8, v9
	v_lshl_add_u64 v[2:3], v[16:17], 0, v[2:3]
	global_store_dword v[2:3], v0, off
	v_cvt_pk_bf16_f32 v0, v4, v5
	global_store_dword v[2:3], v0, off offset:128
	s_branch .LBB0_445
.LBB0_1526:
	s_mov_b64 s[12:13], -1
